# all 10 GEMM K loops: in the two 16-ds_read loader segments the segment's two LDS-DMA pieces are issued ahead of the ds_read burst instead of behind it (B1 address temp renamed into its last destinatio
# baseline (speedup 1.0000x reference)
.LBB0_311:
	s_add_u32 s4, s62, 0xfffc0080
	s_addc_u32 s5, s63, -1
	s_add_i32 s84, 0, 0x10000
	s_cmp_eq_u32 s82, 12
	s_cselect_b32 s65, s33, s5
	s_cselect_b32 s64, s36, s4
	s_cselect_b32 s35, s53, s79
	s_cselect_b32 s34, s55, s75
	s_add_i32 s4, 0, 0x14000
	v_lshl_add_u64 v[180:181], s[62:63], 0, v[134:135]
	s_add_i32 m0, s68, 0xc000
	s_nop 0
	global_load_lds_dwordx4 v[180:181], off
	v_lshl_add_u64 v[180:181], s[62:63], 0, v[136:137]
	s_add_i32 m0, s68, 0xe000
	s_nop 0
	global_load_lds_dwordx4 v[180:181], off
	v_add_u32_e32 v164, s84, v143
	v_add_u32_e32 v204, s4, v143
	ds_read_b128 v[138:141], v164
	ds_read_b128 v[156:159], v164 offset:1024
	ds_read_b128 v[160:163], v164 offset:2048
	ds_read_b128 v[164:167], v164 offset:3072
	ds_read_b128 v[168:171], v204
	ds_read_b128 v[172:175], v204 offset:1024
	ds_read_b128 v[176:179], v204 offset:2048
	ds_read_b128 v[204:207], v204 offset:3072
	ds_read_b128 v[208:211], v155
	ds_read_b128 v[212:215], v155 offset:1024
	ds_read_b128 v[216:219], v155 offset:2048
	ds_read_b128 v[220:223], v155 offset:3072
	ds_read_b128 v[224:227], v155 offset:4096
	ds_read_b128 v[228:231], v155 offset:5120
	ds_read_b128 v[232:235], v155 offset:6144
	ds_read_b128 v[236:239], v155 offset:7168
	s_waitcnt vmcnt(8)
	s_waitcnt lgkmcnt(0)
	s_barrier
	s_setprio 1
	s_waitcnt lgkmcnt(0)
	v_mfma_f32_16x16x32_bf16 v[124:127], v[138:141], v[208:211], v[124:127]
	v_mfma_f32_16x16x32_bf16 v[120:123], v[160:163], v[208:211], v[120:123]
	v_mfma_f32_16x16x32_bf16 v[108:111], v[138:141], v[216:219], v[108:111]
	v_mfma_f32_16x16x32_bf16 v[104:107], v[160:163], v[216:219], v[104:107]
	v_mfma_f32_16x16x32_bf16 v[92:95], v[138:141], v[224:227], v[92:95]
	v_mfma_f32_16x16x32_bf16 v[88:91], v[160:163], v[224:227], v[88:91]
	v_mfma_f32_16x16x32_bf16 v[76:79], v[138:141], v[232:235], v[76:79]
	v_mfma_f32_16x16x32_bf16 v[72:75], v[160:163], v[232:235], v[72:75]
	v_mfma_f32_16x16x32_bf16 v[124:127], v[156:159], v[212:215], v[124:127]
	v_mfma_f32_16x16x32_bf16 v[120:123], v[164:167], v[212:215], v[120:123]
	v_mfma_f32_16x16x32_bf16 v[108:111], v[156:159], v[220:223], v[108:111]
	v_mfma_f32_16x16x32_bf16 v[104:107], v[164:167], v[220:223], v[104:107]
	v_mfma_f32_16x16x32_bf16 v[92:95], v[156:159], v[228:231], v[92:95]
	v_mfma_f32_16x16x32_bf16 v[88:91], v[164:167], v[228:231], v[88:91]
	v_mfma_f32_16x16x32_bf16 v[76:79], v[156:159], v[236:239], v[76:79]
	v_mfma_f32_16x16x32_bf16 v[72:75], v[164:167], v[236:239], v[72:75]
	s_setprio 0
	s_setprio 1
	v_mfma_f32_16x16x32_bf16 v[116:119], v[168:171], v[208:211], v[116:119]
	v_mfma_f32_16x16x32_bf16 v[112:115], v[176:179], v[208:211], v[112:115]
	v_mfma_f32_16x16x32_bf16 v[100:103], v[168:171], v[216:219], v[100:103]
	v_mfma_f32_16x16x32_bf16 v[96:99], v[176:179], v[216:219], v[96:99]
	v_mfma_f32_16x16x32_bf16 v[84:87], v[168:171], v[224:227], v[84:87]
	v_mfma_f32_16x16x32_bf16 v[80:83], v[176:179], v[224:227], v[80:83]
	v_mfma_f32_16x16x32_bf16 v[68:71], v[168:171], v[232:235], v[68:71]
	v_mfma_f32_16x16x32_bf16 v[64:67], v[176:179], v[232:235], v[64:67]
	v_mfma_f32_16x16x32_bf16 v[116:119], v[172:175], v[212:215], v[116:119]
	v_mfma_f32_16x16x32_bf16 v[112:115], v[204:207], v[212:215], v[112:115]
	v_mfma_f32_16x16x32_bf16 v[100:103], v[172:175], v[220:223], v[100:103]
	v_mfma_f32_16x16x32_bf16 v[96:99], v[204:207], v[220:223], v[96:99]
	v_mfma_f32_16x16x32_bf16 v[84:87], v[172:175], v[228:231], v[84:87]
	v_mfma_f32_16x16x32_bf16 v[80:83], v[204:207], v[228:231], v[80:83]
	v_mfma_f32_16x16x32_bf16 v[68:71], v[172:175], v[236:239], v[68:71]
	v_mfma_f32_16x16x32_bf16 v[64:67], v[204:207], v[236:239], v[64:67]
	s_setprio 0
	s_barrier
	s_add_i32 s5, s84, s28
	v_lshl_add_u64 v[180:181], s[34:35], 0, v[144:145]
	s_mov_b32 m0, s5
	ds_read_b128 v[208:211], v155 offset:16384
	ds_read_b128 v[212:215], v155 offset:17408
	ds_read_b128 v[216:219], v155 offset:18432
	ds_read_b128 v[220:223], v155 offset:19456
	ds_read_b128 v[224:227], v155 offset:20480
	ds_read_b128 v[228:231], v155 offset:21504
	ds_read_b128 v[232:235], v155 offset:22528
	ds_read_b128 v[236:239], v155 offset:23552
	global_load_lds_dwordx4 v[180:181], off
	s_add_i32 m0, s5, 0x2000
	s_add_u32 s88, s34, 0x40000
	v_lshl_add_u64 v[240:241], s[34:35], 0, v[128:129]
	s_addc_u32 s89, s35, 0
	s_add_i32 s4, s4, s28
	global_load_lds_dwordx4 v[240:241], off
	v_lshl_add_u64 v[242:243], s[88:89], 0, v[144:145]
	s_mov_b32 m0, s4
	v_lshl_add_u64 v[244:245], s[64:65], 0, v[130:131]
	global_load_lds_dwordx4 v[242:243], off
	v_lshl_add_u64 v[242:243], s[88:89], 0, v[128:129]
	s_add_i32 m0, s4, 0x2000
	s_nop 0
	global_load_lds_dwordx4 v[242:243], off
	v_lshl_add_u64 v[242:243], s[64:65], 0, v[132:133]
	s_mov_b32 m0, s68
	s_nop 0
	global_load_lds_dwordx4 v[242:243], off
	s_mov_b32 m0, s69
	s_nop 0
	global_load_lds_dwordx4 v[244:245], off
	s_waitcnt vmcnt(8)
	s_waitcnt lgkmcnt(0)
	s_barrier
	s_setprio 1
	s_waitcnt lgkmcnt(0)
	v_mfma_f32_16x16x32_bf16 v[60:63], v[138:141], v[208:211], v[60:63]
	v_mfma_f32_16x16x32_bf16 v[56:59], v[160:163], v[208:211], v[56:59]
	v_mfma_f32_16x16x32_bf16 v[44:47], v[138:141], v[216:219], v[44:47]
	v_mfma_f32_16x16x32_bf16 v[40:43], v[160:163], v[216:219], v[40:43]
	v_mfma_f32_16x16x32_bf16 v[28:31], v[138:141], v[224:227], v[28:31]
	v_mfma_f32_16x16x32_bf16 v[24:27], v[160:163], v[224:227], v[24:27]
	v_mfma_f32_16x16x32_bf16 v[12:15], v[138:141], v[232:235], v[12:15]
	v_mfma_f32_16x16x32_bf16 v[8:11], v[160:163], v[232:235], v[8:11]
	v_mfma_f32_16x16x32_bf16 v[60:63], v[156:159], v[212:215], v[60:63]
	v_mfma_f32_16x16x32_bf16 v[56:59], v[164:167], v[212:215], v[56:59]
	v_mfma_f32_16x16x32_bf16 v[44:47], v[156:159], v[220:223], v[44:47]
	v_mfma_f32_16x16x32_bf16 v[40:43], v[164:167], v[220:223], v[40:43]
	v_mfma_f32_16x16x32_bf16 v[28:31], v[156:159], v[228:231], v[28:31]
	v_mfma_f32_16x16x32_bf16 v[24:27], v[164:167], v[228:231], v[24:27]
	v_mfma_f32_16x16x32_bf16 v[12:15], v[156:159], v[236:239], v[12:15]
	v_mfma_f32_16x16x32_bf16 v[8:11], v[164:167], v[236:239], v[8:11]
	s_setprio 0
	s_setprio 1
	v_mfma_f32_16x16x32_bf16 v[52:55], v[168:171], v[208:211], v[52:55]
	v_mfma_f32_16x16x32_bf16 v[48:51], v[176:179], v[208:211], v[48:51]
	v_mfma_f32_16x16x32_bf16 v[36:39], v[168:171], v[216:219], v[36:39]
	v_mfma_f32_16x16x32_bf16 v[32:35], v[176:179], v[216:219], v[32:35]
	v_mfma_f32_16x16x32_bf16 v[20:23], v[168:171], v[224:227], v[20:23]
	v_mfma_f32_16x16x32_bf16 v[16:19], v[176:179], v[224:227], v[16:19]
	v_mfma_f32_16x16x32_bf16 v[4:7], v[168:171], v[232:235], v[4:7]
	v_mfma_f32_16x16x32_bf16 v[0:3], v[176:179], v[232:235], v[0:3]
	v_mfma_f32_16x16x32_bf16 v[52:55], v[172:175], v[212:215], v[52:55]
	v_mfma_f32_16x16x32_bf16 v[48:51], v[204:207], v[212:215], v[48:51]
	v_mfma_f32_16x16x32_bf16 v[36:39], v[172:175], v[220:223], v[36:39]
	v_mfma_f32_16x16x32_bf16 v[32:35], v[204:207], v[220:223], v[32:35]
	v_mfma_f32_16x16x32_bf16 v[20:23], v[172:175], v[228:231], v[20:23]
	v_mfma_f32_16x16x32_bf16 v[16:19], v[204:207], v[228:231], v[16:19]
	v_mfma_f32_16x16x32_bf16 v[4:7], v[172:175], v[236:239], v[4:7]
	v_mfma_f32_16x16x32_bf16 v[0:3], v[204:207], v[236:239], v[0:3]
	s_setprio 0
	s_barrier
	s_add_i32 s4, 0, 0x18000
	s_add_i32 s5, 0, 0x1c000
	s_add_u32 s64, s64, 0x40000
	s_addc_u32 s65, s65, 0
	s_mov_b32 m0, s70
	v_lshl_add_u64 v[246:247], s[64:65], 0, v[132:133]
	global_load_lds_dwordx4 v[246:247], off
	v_lshl_add_u64 v[246:247], s[64:65], 0, v[130:131]
	s_mov_b32 m0, s71
	s_nop 0
	global_load_lds_dwordx4 v[246:247], off
	v_add_u32_e32 v164, s4, v143
	v_add_u32_e32 v204, s5, v143
	ds_read_b128 v[138:141], v164
	ds_read_b128 v[156:159], v164 offset:1024
	ds_read_b128 v[160:163], v164 offset:2048
	ds_read_b128 v[164:167], v164 offset:3072
	ds_read_b128 v[168:171], v204
	ds_read_b128 v[172:175], v204 offset:1024
	ds_read_b128 v[176:179], v204 offset:2048
	ds_read_b128 v[204:207], v204 offset:3072
	ds_read_b128 v[208:211], v155 offset:32768
	ds_read_b128 v[212:215], v155 offset:33792
	ds_read_b128 v[216:219], v155 offset:34816
	ds_read_b128 v[220:223], v155 offset:35840
	ds_read_b128 v[224:227], v155 offset:36864
	ds_read_b128 v[228:231], v155 offset:37888
	ds_read_b128 v[232:235], v155 offset:38912
	ds_read_b128 v[236:239], v155 offset:39936
	s_waitcnt vmcnt(8)
	s_waitcnt lgkmcnt(0)
	s_barrier
	s_setprio 1
	s_waitcnt lgkmcnt(0)
	v_mfma_f32_16x16x32_bf16 v[124:127], v[138:141], v[208:211], v[124:127]
	v_mfma_f32_16x16x32_bf16 v[120:123], v[160:163], v[208:211], v[120:123]
	v_mfma_f32_16x16x32_bf16 v[108:111], v[138:141], v[216:219], v[108:111]
	v_mfma_f32_16x16x32_bf16 v[104:107], v[160:163], v[216:219], v[104:107]
	v_mfma_f32_16x16x32_bf16 v[92:95], v[138:141], v[224:227], v[92:95]
	v_mfma_f32_16x16x32_bf16 v[88:91], v[160:163], v[224:227], v[88:91]
	v_mfma_f32_16x16x32_bf16 v[76:79], v[138:141], v[232:235], v[76:79]
	v_mfma_f32_16x16x32_bf16 v[72:75], v[160:163], v[232:235], v[72:75]
	v_mfma_f32_16x16x32_bf16 v[124:127], v[156:159], v[212:215], v[124:127]
	v_mfma_f32_16x16x32_bf16 v[120:123], v[164:167], v[212:215], v[120:123]
	v_mfma_f32_16x16x32_bf16 v[108:111], v[156:159], v[220:223], v[108:111]
	v_mfma_f32_16x16x32_bf16 v[104:107], v[164:167], v[220:223], v[104:107]
	v_mfma_f32_16x16x32_bf16 v[92:95], v[156:159], v[228:231], v[92:95]
	v_mfma_f32_16x16x32_bf16 v[88:91], v[164:167], v[228:231], v[88:91]
	v_mfma_f32_16x16x32_bf16 v[76:79], v[156:159], v[236:239], v[76:79]
	v_mfma_f32_16x16x32_bf16 v[72:75], v[164:167], v[236:239], v[72:75]
	s_setprio 0
	s_setprio 1
	v_mfma_f32_16x16x32_bf16 v[116:119], v[168:171], v[208:211], v[116:119]
	v_mfma_f32_16x16x32_bf16 v[112:115], v[176:179], v[208:211], v[112:115]
	v_mfma_f32_16x16x32_bf16 v[100:103], v[168:171], v[216:219], v[100:103]
	v_mfma_f32_16x16x32_bf16 v[96:99], v[176:179], v[216:219], v[96:99]
	v_mfma_f32_16x16x32_bf16 v[84:87], v[168:171], v[224:227], v[84:87]
	v_mfma_f32_16x16x32_bf16 v[80:83], v[176:179], v[224:227], v[80:83]
	v_mfma_f32_16x16x32_bf16 v[68:71], v[168:171], v[232:235], v[68:71]
	v_mfma_f32_16x16x32_bf16 v[64:67], v[176:179], v[232:235], v[64:67]
	v_mfma_f32_16x16x32_bf16 v[116:119], v[172:175], v[212:215], v[116:119]
	v_mfma_f32_16x16x32_bf16 v[112:115], v[204:207], v[212:215], v[112:115]
	v_mfma_f32_16x16x32_bf16 v[100:103], v[172:175], v[220:223], v[100:103]
	v_mfma_f32_16x16x32_bf16 v[96:99], v[204:207], v[220:223], v[96:99]
	v_mfma_f32_16x16x32_bf16 v[84:87], v[172:175], v[228:231], v[84:87]
	v_mfma_f32_16x16x32_bf16 v[80:83], v[204:207], v[228:231], v[80:83]
	v_mfma_f32_16x16x32_bf16 v[68:71], v[172:175], v[236:239], v[68:71]
	v_mfma_f32_16x16x32_bf16 v[64:67], v[204:207], v[236:239], v[64:67]
	s_setprio 0
	s_barrier
	s_add_i32 s4, s4, s28
	v_lshl_add_u64 v[180:181], v[180:181], 0, s[26:27]
	s_mov_b32 m0, s4
	ds_read_b128 v[208:211], v155 offset:49152
	ds_read_b128 v[212:215], v155 offset:50176
	ds_read_b128 v[216:219], v155 offset:51200
	ds_read_b128 v[220:223], v155 offset:52224
	ds_read_b128 v[224:227], v155 offset:53248
	ds_read_b128 v[228:231], v155 offset:54272
	ds_read_b128 v[232:235], v155 offset:55296
	ds_read_b128 v[236:239], v155 offset:56320
	global_load_lds_dwordx4 v[180:181], off
	s_add_i32 m0, s4, 0x2000
	s_add_u32 s34, s34, 0x40080
	v_lshl_add_u64 v[180:181], v[240:241], 0, s[26:27]
	s_addc_u32 s35, s35, 0
	s_add_i32 s4, s5, s28
	global_load_lds_dwordx4 v[180:181], off
	v_lshl_add_u64 v[180:181], s[34:35], 0, v[144:145]
	s_mov_b32 m0, s4
	s_nop 0
	global_load_lds_dwordx4 v[180:181], off
	v_lshl_add_u64 v[180:181], s[34:35], 0, v[128:129]
	s_add_i32 m0, s4, 0x2000
	s_nop 0
	global_load_lds_dwordx4 v[180:181], off
	v_lshl_add_u64 v[180:181], v[242:243], 0, s[26:27]
	s_mov_b32 m0, s72
	s_nop 0
	global_load_lds_dwordx4 v[180:181], off
	v_lshl_add_u64 v[180:181], v[244:245], 0, s[26:27]
	s_mov_b32 m0, s73
	s_nop 0
	global_load_lds_dwordx4 v[180:181], off
	s_waitcnt vmcnt(8)
	s_waitcnt lgkmcnt(0)
	s_barrier
	s_setprio 1
	s_waitcnt lgkmcnt(0)
	v_mfma_f32_16x16x32_bf16 v[60:63], v[138:141], v[208:211], v[60:63]
	v_mfma_f32_16x16x32_bf16 v[56:59], v[160:163], v[208:211], v[56:59]
	v_mfma_f32_16x16x32_bf16 v[44:47], v[138:141], v[216:219], v[44:47]
	v_mfma_f32_16x16x32_bf16 v[40:43], v[160:163], v[216:219], v[40:43]
	v_mfma_f32_16x16x32_bf16 v[28:31], v[138:141], v[224:227], v[28:31]
	v_mfma_f32_16x16x32_bf16 v[24:27], v[160:163], v[224:227], v[24:27]
	v_mfma_f32_16x16x32_bf16 v[12:15], v[138:141], v[232:235], v[12:15]
	v_mfma_f32_16x16x32_bf16 v[8:11], v[160:163], v[232:235], v[8:11]
	v_mfma_f32_16x16x32_bf16 v[60:63], v[156:159], v[212:215], v[60:63]
	v_mfma_f32_16x16x32_bf16 v[56:59], v[164:167], v[212:215], v[56:59]
	v_mfma_f32_16x16x32_bf16 v[44:47], v[156:159], v[220:223], v[44:47]
	v_mfma_f32_16x16x32_bf16 v[40:43], v[164:167], v[220:223], v[40:43]
	v_mfma_f32_16x16x32_bf16 v[28:31], v[156:159], v[228:231], v[28:31]
	v_mfma_f32_16x16x32_bf16 v[24:27], v[164:167], v[228:231], v[24:27]
	v_mfma_f32_16x16x32_bf16 v[12:15], v[156:159], v[236:239], v[12:15]
	v_mfma_f32_16x16x32_bf16 v[8:11], v[164:167], v[236:239], v[8:11]
	s_setprio 0
	s_setprio 1
	v_mfma_f32_16x16x32_bf16 v[52:55], v[168:171], v[208:211], v[52:55]
	v_mfma_f32_16x16x32_bf16 v[48:51], v[176:179], v[208:211], v[48:51]
	v_mfma_f32_16x16x32_bf16 v[36:39], v[168:171], v[216:219], v[36:39]
	v_mfma_f32_16x16x32_bf16 v[32:35], v[176:179], v[216:219], v[32:35]
	v_mfma_f32_16x16x32_bf16 v[20:23], v[168:171], v[224:227], v[20:23]
	v_mfma_f32_16x16x32_bf16 v[16:19], v[176:179], v[224:227], v[16:19]
	v_mfma_f32_16x16x32_bf16 v[4:7], v[168:171], v[232:235], v[4:7]
	v_mfma_f32_16x16x32_bf16 v[0:3], v[176:179], v[232:235], v[0:3]
	v_mfma_f32_16x16x32_bf16 v[52:55], v[172:175], v[212:215], v[52:55]
	v_mfma_f32_16x16x32_bf16 v[48:51], v[204:207], v[212:215], v[48:51]
	v_mfma_f32_16x16x32_bf16 v[36:39], v[172:175], v[220:223], v[36:39]
	v_mfma_f32_16x16x32_bf16 v[32:35], v[204:207], v[220:223], v[32:35]
	v_mfma_f32_16x16x32_bf16 v[20:23], v[172:175], v[228:231], v[20:23]
	v_mfma_f32_16x16x32_bf16 v[16:19], v[204:207], v[228:231], v[16:19]
	v_mfma_f32_16x16x32_bf16 v[4:7], v[172:175], v[236:239], v[4:7]
	v_mfma_f32_16x16x32_bf16 v[0:3], v[204:207], v[236:239], v[0:3]
	s_setprio 0
	s_barrier
	s_add_i32 s82, s82, 2
	s_add_u32 s62, s62, 0x100
	s_addc_u32 s63, s63, 0
	s_add_u32 s75, s75, 0x100
	s_addc_u32 s79, s79, 0
	s_cmp_gt_u32 s82, 13
	s_cbranch_scc0 .LBB0_311
	s_and_b64 vcc, s[38:39], exec
	s_cselect_b32 s4, s54, s2
	v_lshl_add_u32 v178, s4, 8, v142
	v_ashrrev_i32_e32 v179, 31, v178
	v_lshl_add_u64 v[178:179], v[178:179], 4, s[48:49]
	global_load_dwordx4 v[208:211], v[178:179], off
	global_load_dwordx4 v[212:215], v[178:179], off offset:256
	global_load_dwordx4 v[216:219], v[178:179], off offset:512
	global_load_dwordx4 v[220:223], v[178:179], off offset:768
	global_load_dwordx4 v[224:227], v[178:179], off offset:2048
	global_load_dwordx4 v[228:231], v[178:179], off offset:2304
	global_load_dwordx4 v[232:235], v[178:179], off offset:2560
	global_load_dwordx4 v[236:239], v[178:179], off offset:2816
	s_and_b64 vcc, exec, s[50:51]
	s_cbranch_vccz .LBB0_314
	s_barrier

.LBB0_406:
	s_add_u32 s62, s60, 0x100
	s_addc_u32 s63, s61, 0
	s_add_i32 s4, 0, 0x10000
	s_cmp_eq_u32 s29, 40
	s_cselect_b32 s65, s45, s63
	s_cselect_b32 s64, s44, s62
	s_cselect_b32 s35, s59, s28
	s_cselect_b32 s34, s58, s3
	s_add_i32 s5, 0, 0x14000
	v_lshl_add_u64 v[142:143], s[60:61], 0, v[134:135]
	s_add_i32 m0, s36, 0xc000
	s_nop 0
	global_load_lds_dwordx4 v[142:143], off
	v_lshl_add_u64 v[142:143], s[60:61], 0, v[136:137]
	s_add_i32 m0, s36, 0xe000
	s_nop 0
	global_load_lds_dwordx4 v[142:143], off
	v_add_u32_e32 v176, s4, v160
	ds_read_b128 v[138:141], v176
	ds_read_b128 v[154:157], v176 offset:1024
	ds_read_b128 v[172:175], v176 offset:2048
	ds_read_b128 v[176:179], v176 offset:3072
	v_add_u32_e32 v216, s5, v160
	ds_read_b128 v[204:207], v216
	ds_read_b128 v[208:211], v216 offset:1024
	ds_read_b128 v[212:215], v216 offset:2048
	ds_read_b128 v[216:219], v216 offset:3072
	ds_read_b128 v[220:223], v170
	ds_read_b128 v[224:227], v170 offset:1024
	ds_read_b128 v[228:231], v170 offset:2048
	ds_read_b128 v[232:235], v170 offset:3072
	ds_read_b128 v[236:239], v170 offset:4096
	ds_read_b128 v[240:243], v170 offset:5120
	ds_read_b128 v[244:247], v170 offset:6144
	ds_read_b128 v[248:251], v170 offset:7168
	s_waitcnt vmcnt(8)
	s_waitcnt lgkmcnt(0)
	s_barrier
	s_setprio 1
	s_waitcnt lgkmcnt(0)
	v_mfma_f32_16x16x32_bf16 v[124:127], v[138:141], v[220:223], v[124:127]
	v_mfma_f32_16x16x32_bf16 v[120:123], v[172:175], v[220:223], v[120:123]
	v_mfma_f32_16x16x32_bf16 v[108:111], v[138:141], v[228:231], v[108:111]
	v_mfma_f32_16x16x32_bf16 v[104:107], v[172:175], v[228:231], v[104:107]
	v_mfma_f32_16x16x32_bf16 v[92:95], v[138:141], v[236:239], v[92:95]
	v_mfma_f32_16x16x32_bf16 v[88:91], v[172:175], v[236:239], v[88:91]
	v_mfma_f32_16x16x32_bf16 v[76:79], v[138:141], v[244:247], v[76:79]
	v_mfma_f32_16x16x32_bf16 v[72:75], v[172:175], v[244:247], v[72:75]
	v_mfma_f32_16x16x32_bf16 v[124:127], v[154:157], v[224:227], v[124:127]
	v_mfma_f32_16x16x32_bf16 v[120:123], v[176:179], v[224:227], v[120:123]
	v_mfma_f32_16x16x32_bf16 v[108:111], v[154:157], v[232:235], v[108:111]
	v_mfma_f32_16x16x32_bf16 v[104:107], v[176:179], v[232:235], v[104:107]
	v_mfma_f32_16x16x32_bf16 v[92:95], v[154:157], v[240:243], v[92:95]
	v_mfma_f32_16x16x32_bf16 v[88:91], v[176:179], v[240:243], v[88:91]
	v_mfma_f32_16x16x32_bf16 v[76:79], v[154:157], v[248:251], v[76:79]
	v_mfma_f32_16x16x32_bf16 v[72:75], v[176:179], v[248:251], v[72:75]
	s_setprio 0
	s_setprio 1
	v_mfma_f32_16x16x32_bf16 v[116:119], v[204:207], v[220:223], v[116:119]
	v_mfma_f32_16x16x32_bf16 v[112:115], v[212:215], v[220:223], v[112:115]
	v_mfma_f32_16x16x32_bf16 v[100:103], v[204:207], v[228:231], v[100:103]
	v_mfma_f32_16x16x32_bf16 v[96:99], v[212:215], v[228:231], v[96:99]
	v_mfma_f32_16x16x32_bf16 v[84:87], v[204:207], v[236:239], v[84:87]
	v_mfma_f32_16x16x32_bf16 v[80:83], v[212:215], v[236:239], v[80:83]
	v_mfma_f32_16x16x32_bf16 v[68:71], v[204:207], v[244:247], v[68:71]
	v_mfma_f32_16x16x32_bf16 v[64:67], v[212:215], v[244:247], v[64:67]
	v_mfma_f32_16x16x32_bf16 v[116:119], v[208:211], v[224:227], v[116:119]
	v_mfma_f32_16x16x32_bf16 v[112:115], v[216:219], v[224:227], v[112:115]
	v_mfma_f32_16x16x32_bf16 v[100:103], v[208:211], v[232:235], v[100:103]
	v_mfma_f32_16x16x32_bf16 v[96:99], v[216:219], v[232:235], v[96:99]
	v_mfma_f32_16x16x32_bf16 v[84:87], v[208:211], v[240:243], v[84:87]
	v_mfma_f32_16x16x32_bf16 v[80:83], v[216:219], v[240:243], v[80:83]
	v_mfma_f32_16x16x32_bf16 v[68:71], v[208:211], v[248:251], v[68:71]
	v_mfma_f32_16x16x32_bf16 v[64:67], v[216:219], v[248:251], v[64:67]
	s_setprio 0
	s_barrier
	s_add_i32 s4, s4, s33
	v_lshl_add_u64 v[142:143], s[34:35], 0, v[128:129]
	s_mov_b32 m0, s4
	ds_read_b128 v[220:223], v170 offset:16384
	ds_read_b128 v[224:227], v170 offset:17408
	ds_read_b128 v[228:231], v170 offset:18432
	ds_read_b128 v[232:235], v170 offset:19456
	ds_read_b128 v[236:239], v170 offset:20480
	ds_read_b128 v[240:243], v170 offset:21504
	ds_read_b128 v[244:247], v170 offset:22528
	ds_read_b128 v[248:251], v170 offset:23552
	global_load_lds_dwordx4 v[142:143], off
	s_add_i32 m0, s4, 0x2000
	s_add_u32 s60, s34, 0xb0000
	v_lshl_add_u64 v[158:159], s[34:35], 0, v[130:131]
	s_addc_u32 s61, s35, 0
	s_add_i32 s4, s5, s33
	global_load_lds_dwordx4 v[158:159], off
	v_lshl_add_u64 v[180:181], s[60:61], 0, v[128:129]
	s_mov_b32 m0, s4
	v_lshl_add_u64 v[202:203], s[64:65], 0, v[130:131]
	global_load_lds_dwordx4 v[180:181], off
	v_lshl_add_u64 v[180:181], s[60:61], 0, v[130:131]
	s_add_i32 m0, s4, 0x2000
	s_nop 0
	global_load_lds_dwordx4 v[180:181], off
	v_lshl_add_u64 v[180:181], s[64:65], 0, v[128:129]
	s_mov_b32 m0, s36
	s_nop 0
	global_load_lds_dwordx4 v[180:181], off
	s_mov_b32 m0, s70
	s_nop 0
	global_load_lds_dwordx4 v[202:203], off
	s_waitcnt vmcnt(8)
	s_waitcnt lgkmcnt(0)
	s_barrier
	s_setprio 1
	s_waitcnt lgkmcnt(0)
	v_mfma_f32_16x16x32_bf16 v[60:63], v[138:141], v[220:223], v[60:63]
	v_mfma_f32_16x16x32_bf16 v[56:59], v[172:175], v[220:223], v[56:59]
	v_mfma_f32_16x16x32_bf16 v[44:47], v[138:141], v[228:231], v[44:47]
	v_mfma_f32_16x16x32_bf16 v[40:43], v[172:175], v[228:231], v[40:43]
	v_mfma_f32_16x16x32_bf16 v[28:31], v[138:141], v[236:239], v[28:31]
	v_mfma_f32_16x16x32_bf16 v[24:27], v[172:175], v[236:239], v[24:27]
	v_mfma_f32_16x16x32_bf16 v[12:15], v[138:141], v[244:247], v[12:15]
	v_mfma_f32_16x16x32_bf16 v[8:11], v[172:175], v[244:247], v[8:11]
	v_mfma_f32_16x16x32_bf16 v[60:63], v[154:157], v[224:227], v[60:63]
	v_mfma_f32_16x16x32_bf16 v[56:59], v[176:179], v[224:227], v[56:59]
	v_mfma_f32_16x16x32_bf16 v[44:47], v[154:157], v[232:235], v[44:47]
	v_mfma_f32_16x16x32_bf16 v[40:43], v[176:179], v[232:235], v[40:43]
	v_mfma_f32_16x16x32_bf16 v[28:31], v[154:157], v[240:243], v[28:31]
	v_mfma_f32_16x16x32_bf16 v[24:27], v[176:179], v[240:243], v[24:27]
	v_mfma_f32_16x16x32_bf16 v[12:15], v[154:157], v[248:251], v[12:15]
	v_mfma_f32_16x16x32_bf16 v[8:11], v[176:179], v[248:251], v[8:11]
	s_setprio 0
	s_setprio 1
	v_mfma_f32_16x16x32_bf16 v[52:55], v[204:207], v[220:223], v[52:55]
	v_mfma_f32_16x16x32_bf16 v[48:51], v[212:215], v[220:223], v[48:51]
	v_mfma_f32_16x16x32_bf16 v[36:39], v[204:207], v[228:231], v[36:39]
	v_mfma_f32_16x16x32_bf16 v[32:35], v[212:215], v[228:231], v[32:35]
	v_mfma_f32_16x16x32_bf16 v[20:23], v[204:207], v[236:239], v[20:23]
	v_mfma_f32_16x16x32_bf16 v[16:19], v[212:215], v[236:239], v[16:19]
	v_mfma_f32_16x16x32_bf16 v[4:7], v[204:207], v[244:247], v[4:7]
	v_mfma_f32_16x16x32_bf16 v[0:3], v[212:215], v[244:247], v[0:3]
	v_mfma_f32_16x16x32_bf16 v[52:55], v[208:211], v[224:227], v[52:55]
	v_mfma_f32_16x16x32_bf16 v[48:51], v[216:219], v[224:227], v[48:51]
	v_mfma_f32_16x16x32_bf16 v[36:39], v[208:211], v[232:235], v[36:39]
	v_mfma_f32_16x16x32_bf16 v[32:35], v[216:219], v[232:235], v[32:35]
	v_mfma_f32_16x16x32_bf16 v[20:23], v[208:211], v[240:243], v[20:23]
	v_mfma_f32_16x16x32_bf16 v[16:19], v[216:219], v[240:243], v[16:19]
	v_mfma_f32_16x16x32_bf16 v[4:7], v[208:211], v[248:251], v[4:7]
	v_mfma_f32_16x16x32_bf16 v[0:3], v[216:219], v[248:251], v[0:3]
	s_setprio 0
	s_barrier
	s_add_i32 s4, 0, 0x18000
	s_add_i32 s5, 0, 0x1c000
	s_add_u32 s60, s64, 0xb0000
	s_addc_u32 s61, s65, 0
	s_mov_b32 m0, s71
	v_lshl_add_u64 v[252:253], s[60:61], 0, v[128:129]
	global_load_lds_dwordx4 v[252:253], off
	v_lshl_add_u64 v[252:253], s[60:61], 0, v[130:131]
	s_mov_b32 m0, s72
	s_nop 0
	global_load_lds_dwordx4 v[252:253], off
	v_add_u32_e32 v176, s4, v160
	ds_read_b128 v[138:141], v176
	ds_read_b128 v[154:157], v176 offset:1024
	ds_read_b128 v[172:175], v176 offset:2048
	ds_read_b128 v[176:179], v176 offset:3072
	v_add_u32_e32 v216, s5, v160
	ds_read_b128 v[204:207], v216
	ds_read_b128 v[208:211], v216 offset:1024
	ds_read_b128 v[212:215], v216 offset:2048
	ds_read_b128 v[216:219], v216 offset:3072
	ds_read_b128 v[220:223], v170 offset:32768
	ds_read_b128 v[224:227], v170 offset:33792
	ds_read_b128 v[228:231], v170 offset:34816
	ds_read_b128 v[232:235], v170 offset:35840
	ds_read_b128 v[236:239], v170 offset:36864
	ds_read_b128 v[240:243], v170 offset:37888
	ds_read_b128 v[244:247], v170 offset:38912
	ds_read_b128 v[248:251], v170 offset:39936
	s_waitcnt vmcnt(8)
	s_waitcnt lgkmcnt(0)
	s_barrier
	s_setprio 1
	s_waitcnt lgkmcnt(0)
	v_mfma_f32_16x16x32_bf16 v[124:127], v[138:141], v[220:223], v[124:127]
	v_mfma_f32_16x16x32_bf16 v[120:123], v[172:175], v[220:223], v[120:123]
	v_mfma_f32_16x16x32_bf16 v[108:111], v[138:141], v[228:231], v[108:111]
	v_mfma_f32_16x16x32_bf16 v[104:107], v[172:175], v[228:231], v[104:107]
	v_mfma_f32_16x16x32_bf16 v[92:95], v[138:141], v[236:239], v[92:95]
	v_mfma_f32_16x16x32_bf16 v[88:91], v[172:175], v[236:239], v[88:91]
	v_mfma_f32_16x16x32_bf16 v[76:79], v[138:141], v[244:247], v[76:79]
	v_mfma_f32_16x16x32_bf16 v[72:75], v[172:175], v[244:247], v[72:75]
	v_mfma_f32_16x16x32_bf16 v[124:127], v[154:157], v[224:227], v[124:127]
	v_mfma_f32_16x16x32_bf16 v[120:123], v[176:179], v[224:227], v[120:123]
	v_mfma_f32_16x16x32_bf16 v[108:111], v[154:157], v[232:235], v[108:111]
	v_mfma_f32_16x16x32_bf16 v[104:107], v[176:179], v[232:235], v[104:107]
	v_mfma_f32_16x16x32_bf16 v[92:95], v[154:157], v[240:243], v[92:95]
	v_mfma_f32_16x16x32_bf16 v[88:91], v[176:179], v[240:243], v[88:91]
	v_mfma_f32_16x16x32_bf16 v[76:79], v[154:157], v[248:251], v[76:79]
	v_mfma_f32_16x16x32_bf16 v[72:75], v[176:179], v[248:251], v[72:75]
	s_setprio 0
	s_setprio 1
	v_mfma_f32_16x16x32_bf16 v[116:119], v[204:207], v[220:223], v[116:119]
	v_mfma_f32_16x16x32_bf16 v[112:115], v[212:215], v[220:223], v[112:115]
	v_mfma_f32_16x16x32_bf16 v[100:103], v[204:207], v[228:231], v[100:103]
	v_mfma_f32_16x16x32_bf16 v[96:99], v[212:215], v[228:231], v[96:99]
	v_mfma_f32_16x16x32_bf16 v[84:87], v[204:207], v[236:239], v[84:87]
	v_mfma_f32_16x16x32_bf16 v[80:83], v[212:215], v[236:239], v[80:83]
	v_mfma_f32_16x16x32_bf16 v[68:71], v[204:207], v[244:247], v[68:71]
	v_mfma_f32_16x16x32_bf16 v[64:67], v[212:215], v[244:247], v[64:67]
	v_mfma_f32_16x16x32_bf16 v[116:119], v[208:211], v[224:227], v[116:119]
	v_mfma_f32_16x16x32_bf16 v[112:115], v[216:219], v[224:227], v[112:115]
	v_mfma_f32_16x16x32_bf16 v[100:103], v[208:211], v[232:235], v[100:103]
	v_mfma_f32_16x16x32_bf16 v[96:99], v[216:219], v[232:235], v[96:99]
	v_mfma_f32_16x16x32_bf16 v[84:87], v[208:211], v[240:243], v[84:87]
	v_mfma_f32_16x16x32_bf16 v[80:83], v[216:219], v[240:243], v[80:83]
	v_mfma_f32_16x16x32_bf16 v[68:71], v[208:211], v[248:251], v[68:71]
	v_mfma_f32_16x16x32_bf16 v[64:67], v[216:219], v[248:251], v[64:67]
	s_setprio 0
	s_barrier
	s_add_i32 s4, s4, s33
	v_lshl_add_u64 v[142:143], v[142:143], 0, s[26:27]
	s_mov_b32 m0, s4
	ds_read_b128 v[220:223], v170 offset:49152
	ds_read_b128 v[224:227], v170 offset:50176
	ds_read_b128 v[228:231], v170 offset:51200
	ds_read_b128 v[232:235], v170 offset:52224
	ds_read_b128 v[236:239], v170 offset:53248
	ds_read_b128 v[240:243], v170 offset:54272
	ds_read_b128 v[244:247], v170 offset:55296
	ds_read_b128 v[248:251], v170 offset:56320
	global_load_lds_dwordx4 v[142:143], off
	s_add_i32 m0, s4, 0x2000
	s_add_u32 s34, s34, 0xb0080
	v_lshl_add_u64 v[142:143], v[158:159], 0, s[26:27]
	s_addc_u32 s35, s35, 0
	s_add_i32 s4, s5, s33
	global_load_lds_dwordx4 v[142:143], off
	v_lshl_add_u64 v[142:143], s[34:35], 0, v[128:129]
	s_mov_b32 m0, s4
	s_nop 0
	global_load_lds_dwordx4 v[142:143], off
	v_lshl_add_u64 v[142:143], s[34:35], 0, v[130:131]
	s_add_i32 m0, s4, 0x2000
	s_nop 0
	global_load_lds_dwordx4 v[142:143], off
	v_lshl_add_u64 v[142:143], v[180:181], 0, s[26:27]
	s_mov_b32 m0, s73
	s_nop 0
	global_load_lds_dwordx4 v[142:143], off
	v_lshl_add_u64 v[142:143], v[202:203], 0, s[26:27]
	s_mov_b32 m0, s74
	s_nop 0
	global_load_lds_dwordx4 v[142:143], off
	s_waitcnt vmcnt(8)
	s_waitcnt lgkmcnt(0)
	s_barrier
	s_setprio 1
	s_waitcnt lgkmcnt(0)
	v_mfma_f32_16x16x32_bf16 v[60:63], v[138:141], v[220:223], v[60:63]
	v_mfma_f32_16x16x32_bf16 v[56:59], v[172:175], v[220:223], v[56:59]
	v_mfma_f32_16x16x32_bf16 v[44:47], v[138:141], v[228:231], v[44:47]
	v_mfma_f32_16x16x32_bf16 v[40:43], v[172:175], v[228:231], v[40:43]
	v_mfma_f32_16x16x32_bf16 v[28:31], v[138:141], v[236:239], v[28:31]
	v_mfma_f32_16x16x32_bf16 v[24:27], v[172:175], v[236:239], v[24:27]
	v_mfma_f32_16x16x32_bf16 v[12:15], v[138:141], v[244:247], v[12:15]
	v_mfma_f32_16x16x32_bf16 v[8:11], v[172:175], v[244:247], v[8:11]
	v_mfma_f32_16x16x32_bf16 v[60:63], v[154:157], v[224:227], v[60:63]
	v_mfma_f32_16x16x32_bf16 v[56:59], v[176:179], v[224:227], v[56:59]
	v_mfma_f32_16x16x32_bf16 v[44:47], v[154:157], v[232:235], v[44:47]
	v_mfma_f32_16x16x32_bf16 v[40:43], v[176:179], v[232:235], v[40:43]
	v_mfma_f32_16x16x32_bf16 v[28:31], v[154:157], v[240:243], v[28:31]
	v_mfma_f32_16x16x32_bf16 v[24:27], v[176:179], v[240:243], v[24:27]
	v_mfma_f32_16x16x32_bf16 v[12:15], v[154:157], v[248:251], v[12:15]
	v_mfma_f32_16x16x32_bf16 v[8:11], v[176:179], v[248:251], v[8:11]
	s_setprio 0
	s_setprio 1
	v_mfma_f32_16x16x32_bf16 v[52:55], v[204:207], v[220:223], v[52:55]
	v_mfma_f32_16x16x32_bf16 v[48:51], v[212:215], v[220:223], v[48:51]
	v_mfma_f32_16x16x32_bf16 v[36:39], v[204:207], v[228:231], v[36:39]
	v_mfma_f32_16x16x32_bf16 v[32:35], v[212:215], v[228:231], v[32:35]
	v_mfma_f32_16x16x32_bf16 v[20:23], v[204:207], v[236:239], v[20:23]
	v_mfma_f32_16x16x32_bf16 v[16:19], v[212:215], v[236:239], v[16:19]
	v_mfma_f32_16x16x32_bf16 v[4:7], v[204:207], v[244:247], v[4:7]
	v_mfma_f32_16x16x32_bf16 v[0:3], v[212:215], v[244:247], v[0:3]
	v_mfma_f32_16x16x32_bf16 v[52:55], v[208:211], v[224:227], v[52:55]
	v_mfma_f32_16x16x32_bf16 v[48:51], v[216:219], v[224:227], v[48:51]
	v_mfma_f32_16x16x32_bf16 v[36:39], v[208:211], v[232:235], v[36:39]
	v_mfma_f32_16x16x32_bf16 v[32:35], v[216:219], v[232:235], v[32:35]
	v_mfma_f32_16x16x32_bf16 v[20:23], v[208:211], v[240:243], v[20:23]
	v_mfma_f32_16x16x32_bf16 v[16:19], v[216:219], v[240:243], v[16:19]
	v_mfma_f32_16x16x32_bf16 v[4:7], v[208:211], v[248:251], v[4:7]
	v_mfma_f32_16x16x32_bf16 v[0:3], v[216:219], v[248:251], v[0:3]
	s_setprio 0
	s_barrier
	s_add_i32 s29, s29, 2
	s_add_u32 s3, s3, 0x100
	s_addc_u32 s28, s28, 0
	s_cmp_gt_u32 s29, 41
	s_mov_b64 s[60:61], s[62:63]
	s_cbranch_scc0 .LBB0_406
	s_and_b64 vcc, exec, s[54:55]
	s_cbranch_vccz .LBB0_409
	s_barrier

.LBB0_456:
	s_add_u32 s60, s58, 0x100
	s_addc_u32 s61, s59, 0
	s_add_i32 s4, 0, 0x10000
	s_cmp_eq_u32 s51, 40
	s_cselect_b32 s63, s45, s61
	s_cselect_b32 s62, s44, s60
	s_cselect_b32 s35, s47, s29
	s_cselect_b32 s34, s46, s28
	s_add_i32 s5, 0, 0x14000
	v_lshl_add_u64 v[164:165], s[58:59], 0, v[160:161]
	s_add_i32 m0, s36, 0xc000
	s_nop 0
	global_load_lds_dwordx4 v[164:165], off
	v_lshl_add_u64 v[164:165], s[58:59], 0, v[162:163]
	s_add_i32 m0, s36, 0xe000
	s_nop 0
	global_load_lds_dwordx4 v[164:165], off
	v_add_u32_e32 v140, s4, v166
	v_add_u32_e32 v212, s5, v166
	ds_read_b128 v[128:131], v140
	ds_read_b128 v[132:135], v140 offset:1024
	ds_read_b128 v[136:139], v140 offset:2048
	ds_read_b128 v[140:143], v140 offset:3072
	ds_read_b128 v[178:181], v212
	ds_read_b128 v[204:207], v212 offset:1024
	ds_read_b128 v[208:211], v212 offset:2048
	ds_read_b128 v[212:215], v212 offset:3072
	ds_read_b128 v[216:219], v176
	ds_read_b128 v[220:223], v176 offset:1024
	ds_read_b128 v[224:227], v176 offset:2048
	ds_read_b128 v[228:231], v176 offset:3072
	ds_read_b128 v[232:235], v176 offset:4096
	ds_read_b128 v[236:239], v176 offset:5120
	ds_read_b128 v[240:243], v176 offset:6144
	ds_read_b128 v[244:247], v176 offset:7168
	s_waitcnt vmcnt(8)
	s_waitcnt lgkmcnt(0)
	s_barrier
	s_setprio 1
	s_waitcnt lgkmcnt(0)
	v_mfma_f32_16x16x32_bf16 v[124:127], v[128:131], v[216:219], v[124:127]
	v_mfma_f32_16x16x32_bf16 v[120:123], v[136:139], v[216:219], v[120:123]
	v_mfma_f32_16x16x32_bf16 v[108:111], v[128:131], v[224:227], v[108:111]
	v_mfma_f32_16x16x32_bf16 v[104:107], v[136:139], v[224:227], v[104:107]
	v_mfma_f32_16x16x32_bf16 v[92:95], v[128:131], v[232:235], v[92:95]
	v_mfma_f32_16x16x32_bf16 v[88:91], v[136:139], v[232:235], v[88:91]
	v_mfma_f32_16x16x32_bf16 v[76:79], v[128:131], v[240:243], v[76:79]
	v_mfma_f32_16x16x32_bf16 v[72:75], v[136:139], v[240:243], v[72:75]
	v_mfma_f32_16x16x32_bf16 v[124:127], v[132:135], v[220:223], v[124:127]
	v_mfma_f32_16x16x32_bf16 v[120:123], v[140:143], v[220:223], v[120:123]
	v_mfma_f32_16x16x32_bf16 v[108:111], v[132:135], v[228:231], v[108:111]
	v_mfma_f32_16x16x32_bf16 v[104:107], v[140:143], v[228:231], v[104:107]
	v_mfma_f32_16x16x32_bf16 v[92:95], v[132:135], v[236:239], v[92:95]
	v_mfma_f32_16x16x32_bf16 v[88:91], v[140:143], v[236:239], v[88:91]
	v_mfma_f32_16x16x32_bf16 v[76:79], v[132:135], v[244:247], v[76:79]
	v_mfma_f32_16x16x32_bf16 v[72:75], v[140:143], v[244:247], v[72:75]
	s_setprio 0
	s_setprio 1
	v_mfma_f32_16x16x32_bf16 v[116:119], v[178:181], v[216:219], v[116:119]
	v_mfma_f32_16x16x32_bf16 v[112:115], v[208:211], v[216:219], v[112:115]
	v_mfma_f32_16x16x32_bf16 v[100:103], v[178:181], v[224:227], v[100:103]
	v_mfma_f32_16x16x32_bf16 v[96:99], v[208:211], v[224:227], v[96:99]
	v_mfma_f32_16x16x32_bf16 v[84:87], v[178:181], v[232:235], v[84:87]
	v_mfma_f32_16x16x32_bf16 v[80:83], v[208:211], v[232:235], v[80:83]
	v_mfma_f32_16x16x32_bf16 v[68:71], v[178:181], v[240:243], v[68:71]
	v_mfma_f32_16x16x32_bf16 v[64:67], v[208:211], v[240:243], v[64:67]
	v_mfma_f32_16x16x32_bf16 v[116:119], v[204:207], v[220:223], v[116:119]
	v_mfma_f32_16x16x32_bf16 v[112:115], v[212:215], v[220:223], v[112:115]
	v_mfma_f32_16x16x32_bf16 v[100:103], v[204:207], v[228:231], v[100:103]
	v_mfma_f32_16x16x32_bf16 v[96:99], v[212:215], v[228:231], v[96:99]
	v_mfma_f32_16x16x32_bf16 v[84:87], v[204:207], v[236:239], v[84:87]
	v_mfma_f32_16x16x32_bf16 v[80:83], v[212:215], v[236:239], v[80:83]
	v_mfma_f32_16x16x32_bf16 v[68:71], v[204:207], v[244:247], v[68:71]
	v_mfma_f32_16x16x32_bf16 v[64:67], v[212:215], v[244:247], v[64:67]
	s_setprio 0
	s_barrier
	s_add_i32 s4, s4, s33
	v_lshl_add_u64 v[164:165], s[34:35], 0, v[154:155]
	s_mov_b32 m0, s4
	ds_read_b128 v[216:219], v176 offset:16384
	ds_read_b128 v[220:223], v176 offset:17408
	ds_read_b128 v[224:227], v176 offset:18432
	ds_read_b128 v[228:231], v176 offset:19456
	ds_read_b128 v[232:235], v176 offset:20480
	ds_read_b128 v[236:239], v176 offset:21504
	ds_read_b128 v[240:243], v176 offset:22528
	ds_read_b128 v[244:247], v176 offset:23552
	global_load_lds_dwordx4 v[164:165], off
	s_add_i32 m0, s4, 0x2000
	s_add_u32 s58, s34, 0xb0000
	v_lshl_add_u64 v[248:249], s[34:35], 0, v[156:157]
	s_addc_u32 s59, s35, 0
	s_add_i32 s4, s5, s33
	global_load_lds_dwordx4 v[248:249], off
	v_lshl_add_u64 v[250:251], s[58:59], 0, v[154:155]
	s_mov_b32 m0, s4
	v_lshl_add_u64 v[252:253], s[62:63], 0, v[156:157]
	global_load_lds_dwordx4 v[250:251], off
	v_lshl_add_u64 v[250:251], s[58:59], 0, v[156:157]
	s_add_i32 m0, s4, 0x2000
	s_nop 0
	global_load_lds_dwordx4 v[250:251], off
	v_lshl_add_u64 v[250:251], s[62:63], 0, v[154:155]
	s_mov_b32 m0, s36
	s_nop 0
	global_load_lds_dwordx4 v[250:251], off
	s_mov_b32 m0, s64
	s_nop 0
	global_load_lds_dwordx4 v[252:253], off
	s_waitcnt vmcnt(8)
	s_waitcnt lgkmcnt(0)
	s_barrier
	s_setprio 1
	s_waitcnt lgkmcnt(0)
	v_mfma_f32_16x16x32_bf16 v[60:63], v[128:131], v[216:219], v[60:63]
	v_mfma_f32_16x16x32_bf16 v[56:59], v[136:139], v[216:219], v[56:59]
	v_mfma_f32_16x16x32_bf16 v[44:47], v[128:131], v[224:227], v[44:47]
	v_mfma_f32_16x16x32_bf16 v[40:43], v[136:139], v[224:227], v[40:43]
	v_mfma_f32_16x16x32_bf16 v[28:31], v[128:131], v[232:235], v[28:31]
	v_mfma_f32_16x16x32_bf16 v[24:27], v[136:139], v[232:235], v[24:27]
	v_mfma_f32_16x16x32_bf16 v[12:15], v[128:131], v[240:243], v[12:15]
	v_mfma_f32_16x16x32_bf16 v[8:11], v[136:139], v[240:243], v[8:11]
	v_mfma_f32_16x16x32_bf16 v[60:63], v[132:135], v[220:223], v[60:63]
	v_mfma_f32_16x16x32_bf16 v[56:59], v[140:143], v[220:223], v[56:59]
	v_mfma_f32_16x16x32_bf16 v[44:47], v[132:135], v[228:231], v[44:47]
	v_mfma_f32_16x16x32_bf16 v[40:43], v[140:143], v[228:231], v[40:43]
	v_mfma_f32_16x16x32_bf16 v[28:31], v[132:135], v[236:239], v[28:31]
	v_mfma_f32_16x16x32_bf16 v[24:27], v[140:143], v[236:239], v[24:27]
	v_mfma_f32_16x16x32_bf16 v[12:15], v[132:135], v[244:247], v[12:15]
	v_mfma_f32_16x16x32_bf16 v[8:11], v[140:143], v[244:247], v[8:11]
	s_setprio 0
	s_setprio 1
	v_mfma_f32_16x16x32_bf16 v[52:55], v[178:181], v[216:219], v[52:55]
	v_mfma_f32_16x16x32_bf16 v[48:51], v[208:211], v[216:219], v[48:51]
	v_mfma_f32_16x16x32_bf16 v[36:39], v[178:181], v[224:227], v[36:39]
	v_mfma_f32_16x16x32_bf16 v[32:35], v[208:211], v[224:227], v[32:35]
	v_mfma_f32_16x16x32_bf16 v[20:23], v[178:181], v[232:235], v[20:23]
	v_mfma_f32_16x16x32_bf16 v[16:19], v[208:211], v[232:235], v[16:19]
	v_mfma_f32_16x16x32_bf16 v[4:7], v[178:181], v[240:243], v[4:7]
	v_mfma_f32_16x16x32_bf16 v[0:3], v[208:211], v[240:243], v[0:3]
	v_mfma_f32_16x16x32_bf16 v[52:55], v[204:207], v[220:223], v[52:55]
	v_mfma_f32_16x16x32_bf16 v[48:51], v[212:215], v[220:223], v[48:51]
	v_mfma_f32_16x16x32_bf16 v[36:39], v[204:207], v[228:231], v[36:39]
	v_mfma_f32_16x16x32_bf16 v[32:35], v[212:215], v[228:231], v[32:35]
	v_mfma_f32_16x16x32_bf16 v[20:23], v[204:207], v[236:239], v[20:23]
	v_mfma_f32_16x16x32_bf16 v[16:19], v[212:215], v[236:239], v[16:19]
	v_mfma_f32_16x16x32_bf16 v[4:7], v[204:207], v[244:247], v[4:7]
	v_mfma_f32_16x16x32_bf16 v[0:3], v[212:215], v[244:247], v[0:3]
	s_setprio 0
	s_barrier
	s_add_i32 s4, 0, 0x18000
	s_add_i32 s5, 0, 0x1c000
	s_add_u32 s58, s62, 0xb0000
	s_addc_u32 s59, s63, 0
	s_mov_b32 m0, s65
	v_lshl_add_u64 v[202:203], s[58:59], 0, v[154:155]
	global_load_lds_dwordx4 v[202:203], off
	v_lshl_add_u64 v[202:203], s[58:59], 0, v[156:157]
	s_mov_b32 m0, s70
	s_nop 0
	global_load_lds_dwordx4 v[202:203], off
	v_add_u32_e32 v140, s4, v166
	v_add_u32_e32 v212, s5, v166
	ds_read_b128 v[128:131], v140
	ds_read_b128 v[132:135], v140 offset:1024
	ds_read_b128 v[136:139], v140 offset:2048
	ds_read_b128 v[140:143], v140 offset:3072
	ds_read_b128 v[178:181], v212
	ds_read_b128 v[204:207], v212 offset:1024
	ds_read_b128 v[208:211], v212 offset:2048
	ds_read_b128 v[212:215], v212 offset:3072
	ds_read_b128 v[216:219], v176 offset:32768
	ds_read_b128 v[220:223], v176 offset:33792
	ds_read_b128 v[224:227], v176 offset:34816
	ds_read_b128 v[228:231], v176 offset:35840
	ds_read_b128 v[232:235], v176 offset:36864
	ds_read_b128 v[236:239], v176 offset:37888
	ds_read_b128 v[240:243], v176 offset:38912
	ds_read_b128 v[244:247], v176 offset:39936
	s_waitcnt vmcnt(8)
	s_waitcnt lgkmcnt(0)
	s_barrier
	s_setprio 1
	s_waitcnt lgkmcnt(0)
	v_mfma_f32_16x16x32_bf16 v[124:127], v[128:131], v[216:219], v[124:127]
	v_mfma_f32_16x16x32_bf16 v[120:123], v[136:139], v[216:219], v[120:123]
	v_mfma_f32_16x16x32_bf16 v[108:111], v[128:131], v[224:227], v[108:111]
	v_mfma_f32_16x16x32_bf16 v[104:107], v[136:139], v[224:227], v[104:107]
	v_mfma_f32_16x16x32_bf16 v[92:95], v[128:131], v[232:235], v[92:95]
	v_mfma_f32_16x16x32_bf16 v[88:91], v[136:139], v[232:235], v[88:91]
	v_mfma_f32_16x16x32_bf16 v[76:79], v[128:131], v[240:243], v[76:79]
	v_mfma_f32_16x16x32_bf16 v[72:75], v[136:139], v[240:243], v[72:75]
	v_mfma_f32_16x16x32_bf16 v[124:127], v[132:135], v[220:223], v[124:127]
	v_mfma_f32_16x16x32_bf16 v[120:123], v[140:143], v[220:223], v[120:123]
	v_mfma_f32_16x16x32_bf16 v[108:111], v[132:135], v[228:231], v[108:111]
	v_mfma_f32_16x16x32_bf16 v[104:107], v[140:143], v[228:231], v[104:107]
	v_mfma_f32_16x16x32_bf16 v[92:95], v[132:135], v[236:239], v[92:95]
	v_mfma_f32_16x16x32_bf16 v[88:91], v[140:143], v[236:239], v[88:91]
	v_mfma_f32_16x16x32_bf16 v[76:79], v[132:135], v[244:247], v[76:79]
	v_mfma_f32_16x16x32_bf16 v[72:75], v[140:143], v[244:247], v[72:75]
	s_setprio 0
	s_setprio 1
	v_mfma_f32_16x16x32_bf16 v[116:119], v[178:181], v[216:219], v[116:119]
	v_mfma_f32_16x16x32_bf16 v[112:115], v[208:211], v[216:219], v[112:115]
	v_mfma_f32_16x16x32_bf16 v[100:103], v[178:181], v[224:227], v[100:103]
	v_mfma_f32_16x16x32_bf16 v[96:99], v[208:211], v[224:227], v[96:99]
	v_mfma_f32_16x16x32_bf16 v[84:87], v[178:181], v[232:235], v[84:87]
	v_mfma_f32_16x16x32_bf16 v[80:83], v[208:211], v[232:235], v[80:83]
	v_mfma_f32_16x16x32_bf16 v[68:71], v[178:181], v[240:243], v[68:71]
	v_mfma_f32_16x16x32_bf16 v[64:67], v[208:211], v[240:243], v[64:67]
	v_mfma_f32_16x16x32_bf16 v[116:119], v[204:207], v[220:223], v[116:119]
	v_mfma_f32_16x16x32_bf16 v[112:115], v[212:215], v[220:223], v[112:115]
	v_mfma_f32_16x16x32_bf16 v[100:103], v[204:207], v[228:231], v[100:103]
	v_mfma_f32_16x16x32_bf16 v[96:99], v[212:215], v[228:231], v[96:99]
	v_mfma_f32_16x16x32_bf16 v[84:87], v[204:207], v[236:239], v[84:87]
	v_mfma_f32_16x16x32_bf16 v[80:83], v[212:215], v[236:239], v[80:83]
	v_mfma_f32_16x16x32_bf16 v[68:71], v[204:207], v[244:247], v[68:71]
	v_mfma_f32_16x16x32_bf16 v[64:67], v[212:215], v[244:247], v[64:67]
	s_setprio 0
	s_barrier
	s_add_i32 s4, s4, s33
	v_lshl_add_u64 v[164:165], v[164:165], 0, s[26:27]
	s_mov_b32 m0, s4
	ds_read_b128 v[216:219], v176 offset:49152
	ds_read_b128 v[220:223], v176 offset:50176
	ds_read_b128 v[224:227], v176 offset:51200
	ds_read_b128 v[228:231], v176 offset:52224
	ds_read_b128 v[232:235], v176 offset:53248
	ds_read_b128 v[236:239], v176 offset:54272
	ds_read_b128 v[240:243], v176 offset:55296
	ds_read_b128 v[244:247], v176 offset:56320
	global_load_lds_dwordx4 v[164:165], off
	s_add_i32 m0, s4, 0x2000
	s_add_u32 s34, s34, 0xb0080
	v_lshl_add_u64 v[164:165], v[248:249], 0, s[26:27]
	s_addc_u32 s35, s35, 0
	s_add_i32 s4, s5, s33
	global_load_lds_dwordx4 v[164:165], off
	v_lshl_add_u64 v[164:165], s[34:35], 0, v[154:155]
	s_mov_b32 m0, s4
	s_nop 0
	global_load_lds_dwordx4 v[164:165], off
	v_lshl_add_u64 v[164:165], s[34:35], 0, v[156:157]
	s_add_i32 m0, s4, 0x2000
	s_nop 0
	global_load_lds_dwordx4 v[164:165], off
	v_lshl_add_u64 v[164:165], v[250:251], 0, s[26:27]
	s_mov_b32 m0, s71
	s_nop 0
	global_load_lds_dwordx4 v[164:165], off
	v_lshl_add_u64 v[164:165], v[252:253], 0, s[26:27]
	s_mov_b32 m0, s72
	s_nop 0
	global_load_lds_dwordx4 v[164:165], off
	s_waitcnt vmcnt(8)
	s_waitcnt lgkmcnt(0)
	s_barrier
	s_setprio 1
	s_waitcnt lgkmcnt(0)
	v_mfma_f32_16x16x32_bf16 v[60:63], v[128:131], v[216:219], v[60:63]
	v_mfma_f32_16x16x32_bf16 v[56:59], v[136:139], v[216:219], v[56:59]
	v_mfma_f32_16x16x32_bf16 v[44:47], v[128:131], v[224:227], v[44:47]
	v_mfma_f32_16x16x32_bf16 v[40:43], v[136:139], v[224:227], v[40:43]
	v_mfma_f32_16x16x32_bf16 v[28:31], v[128:131], v[232:235], v[28:31]
	v_mfma_f32_16x16x32_bf16 v[24:27], v[136:139], v[232:235], v[24:27]
	v_mfma_f32_16x16x32_bf16 v[12:15], v[128:131], v[240:243], v[12:15]
	v_mfma_f32_16x16x32_bf16 v[8:11], v[136:139], v[240:243], v[8:11]
	v_mfma_f32_16x16x32_bf16 v[60:63], v[132:135], v[220:223], v[60:63]
	v_mfma_f32_16x16x32_bf16 v[56:59], v[140:143], v[220:223], v[56:59]
	v_mfma_f32_16x16x32_bf16 v[44:47], v[132:135], v[228:231], v[44:47]
	v_mfma_f32_16x16x32_bf16 v[40:43], v[140:143], v[228:231], v[40:43]
	v_mfma_f32_16x16x32_bf16 v[28:31], v[132:135], v[236:239], v[28:31]
	v_mfma_f32_16x16x32_bf16 v[24:27], v[140:143], v[236:239], v[24:27]
	v_mfma_f32_16x16x32_bf16 v[12:15], v[132:135], v[244:247], v[12:15]
	v_mfma_f32_16x16x32_bf16 v[8:11], v[140:143], v[244:247], v[8:11]
	s_setprio 0
	s_setprio 1
	v_mfma_f32_16x16x32_bf16 v[52:55], v[178:181], v[216:219], v[52:55]
	v_mfma_f32_16x16x32_bf16 v[48:51], v[208:211], v[216:219], v[48:51]
	v_mfma_f32_16x16x32_bf16 v[36:39], v[178:181], v[224:227], v[36:39]
	v_mfma_f32_16x16x32_bf16 v[32:35], v[208:211], v[224:227], v[32:35]
	v_mfma_f32_16x16x32_bf16 v[20:23], v[178:181], v[232:235], v[20:23]
	v_mfma_f32_16x16x32_bf16 v[16:19], v[208:211], v[232:235], v[16:19]
	v_mfma_f32_16x16x32_bf16 v[4:7], v[178:181], v[240:243], v[4:7]
	v_mfma_f32_16x16x32_bf16 v[0:3], v[208:211], v[240:243], v[0:3]
	v_mfma_f32_16x16x32_bf16 v[52:55], v[204:207], v[220:223], v[52:55]
	v_mfma_f32_16x16x32_bf16 v[48:51], v[212:215], v[220:223], v[48:51]
	v_mfma_f32_16x16x32_bf16 v[36:39], v[204:207], v[228:231], v[36:39]
	v_mfma_f32_16x16x32_bf16 v[32:35], v[212:215], v[228:231], v[32:35]
	v_mfma_f32_16x16x32_bf16 v[20:23], v[204:207], v[236:239], v[20:23]
	v_mfma_f32_16x16x32_bf16 v[16:19], v[212:215], v[236:239], v[16:19]
	v_mfma_f32_16x16x32_bf16 v[4:7], v[204:207], v[244:247], v[4:7]
	v_mfma_f32_16x16x32_bf16 v[0:3], v[212:215], v[244:247], v[0:3]
	s_setprio 0
	s_barrier
	s_add_i32 s51, s51, 2
	s_add_u32 s28, s28, 0x100
	s_addc_u32 s29, s29, 0
	s_cmp_gt_u32 s51, 41
	s_mov_b64 s[58:59], s[60:61]
	s_cbranch_scc0 .LBB0_456
	s_and_b64 vcc, exec, s[54:55]
	s_cbranch_vccz .LBB0_459
	s_barrier

.LBB0_605:
	s_add_u32 s4, s0, 0xfffc0080
	s_addc_u32 s5, s1, -1
	s_add_i32 s89, 0, 0x10000
	s_cmp_eq_u32 s88, 12
	s_cselect_b32 s43, s3, s5
	s_cselect_b32 s42, s36, s4
	s_cselect_b32 s35, s39, s84
	s_cselect_b32 s34, s71, s79
	s_add_i32 s4, 0, 0x14000
	v_lshl_add_u64 v[180:181], s[0:1], 0, v[164:165]
	s_add_i32 m0, s69, 0xc000
	s_nop 0
	global_load_lds_dwordx4 v[180:181], off
	v_lshl_add_u64 v[180:181], s[0:1], 0, v[166:167]
	s_add_i32 m0, s69, 0xe000
	s_nop 0
	global_load_lds_dwordx4 v[180:181], off
	v_add_u32_e32 v140, s89, v203
	v_add_u32_e32 v206, s4, v203
	ds_read_b128 v[128:131], v140
	ds_read_b128 v[132:135], v140 offset:1024
	ds_read_b128 v[136:139], v140 offset:2048
	ds_read_b128 v[140:143], v140 offset:3072
	ds_read_b128 v[168:171], v206
	ds_read_b128 v[172:175], v206 offset:1024
	ds_read_b128 v[176:179], v206 offset:2048
	ds_read_b128 v[206:209], v206 offset:3072
	ds_read_b128 v[210:213], v205
	ds_read_b128 v[214:217], v205 offset:1024
	ds_read_b128 v[218:221], v205 offset:2048
	ds_read_b128 v[222:225], v205 offset:3072
	ds_read_b128 v[226:229], v205 offset:4096
	ds_read_b128 v[230:233], v205 offset:5120
	ds_read_b128 v[234:237], v205 offset:6144
	ds_read_b128 v[238:241], v205 offset:7168
	s_waitcnt vmcnt(8)
	s_waitcnt lgkmcnt(0)
	s_barrier
	s_setprio 1
	s_waitcnt lgkmcnt(0)
	v_mfma_f32_16x16x32_bf16 v[124:127], v[128:131], v[210:213], v[124:127]
	v_mfma_f32_16x16x32_bf16 v[120:123], v[136:139], v[210:213], v[120:123]
	v_mfma_f32_16x16x32_bf16 v[112:115], v[128:131], v[218:221], v[112:115]
	v_mfma_f32_16x16x32_bf16 v[108:111], v[136:139], v[218:221], v[108:111]
	v_mfma_f32_16x16x32_bf16 v[100:103], v[128:131], v[226:229], v[100:103]
	v_mfma_f32_16x16x32_bf16 v[92:95], v[136:139], v[226:229], v[92:95]
	v_mfma_f32_16x16x32_bf16 v[84:87], v[128:131], v[234:237], v[84:87]
	v_mfma_f32_16x16x32_bf16 v[76:79], v[136:139], v[234:237], v[76:79]
	v_mfma_f32_16x16x32_bf16 v[124:127], v[132:135], v[214:217], v[124:127]
	v_mfma_f32_16x16x32_bf16 v[120:123], v[140:143], v[214:217], v[120:123]
	v_mfma_f32_16x16x32_bf16 v[112:115], v[132:135], v[222:225], v[112:115]
	v_mfma_f32_16x16x32_bf16 v[108:111], v[140:143], v[222:225], v[108:111]
	v_mfma_f32_16x16x32_bf16 v[100:103], v[132:135], v[230:233], v[100:103]
	v_mfma_f32_16x16x32_bf16 v[92:95], v[140:143], v[230:233], v[92:95]
	v_mfma_f32_16x16x32_bf16 v[84:87], v[132:135], v[238:241], v[84:87]
	v_mfma_f32_16x16x32_bf16 v[76:79], v[140:143], v[238:241], v[76:79]
	s_setprio 0
	s_setprio 1
	v_mfma_f32_16x16x32_bf16 v[116:119], v[168:171], v[210:213], v[116:119]
	v_mfma_f32_16x16x32_bf16 v[104:107], v[176:179], v[210:213], v[104:107]
	v_mfma_f32_16x16x32_bf16 v[96:99], v[168:171], v[218:221], v[96:99]
	v_mfma_f32_16x16x32_bf16 v[88:91], v[176:179], v[218:221], v[88:91]
	v_mfma_f32_16x16x32_bf16 v[80:83], v[168:171], v[226:229], v[80:83]
	v_mfma_f32_16x16x32_bf16 v[72:75], v[176:179], v[226:229], v[72:75]
	v_mfma_f32_16x16x32_bf16 v[68:71], v[168:171], v[234:237], v[68:71]
	v_mfma_f32_16x16x32_bf16 v[64:67], v[176:179], v[234:237], v[64:67]
	v_mfma_f32_16x16x32_bf16 v[116:119], v[172:175], v[214:217], v[116:119]
	v_mfma_f32_16x16x32_bf16 v[104:107], v[206:209], v[214:217], v[104:107]
	v_mfma_f32_16x16x32_bf16 v[96:99], v[172:175], v[222:225], v[96:99]
	v_mfma_f32_16x16x32_bf16 v[88:91], v[206:209], v[222:225], v[88:91]
	v_mfma_f32_16x16x32_bf16 v[80:83], v[172:175], v[230:233], v[80:83]
	v_mfma_f32_16x16x32_bf16 v[72:75], v[206:209], v[230:233], v[72:75]
	v_mfma_f32_16x16x32_bf16 v[68:71], v[172:175], v[238:241], v[68:71]
	v_mfma_f32_16x16x32_bf16 v[64:67], v[206:209], v[238:241], v[64:67]
	s_setprio 0
	s_barrier
	s_add_i32 s5, s89, s28
	v_lshl_add_u64 v[180:181], s[34:35], 0, v[156:157]
	s_mov_b32 m0, s5
	ds_read_b128 v[210:213], v205 offset:16384
	ds_read_b128 v[214:217], v205 offset:17408
	ds_read_b128 v[218:221], v205 offset:18432
	ds_read_b128 v[222:225], v205 offset:19456
	ds_read_b128 v[226:229], v205 offset:20480
	ds_read_b128 v[230:233], v205 offset:21504
	ds_read_b128 v[234:237], v205 offset:22528
	ds_read_b128 v[238:241], v205 offset:23552
	global_load_lds_dwordx4 v[180:181], off
	s_add_i32 m0, s5, 0x2000
	s_add_u32 s90, s34, 0x40000
	v_lshl_add_u64 v[242:243], s[34:35], 0, v[160:161]
	s_addc_u32 s91, s35, 0
	s_add_i32 s4, s4, s28
	global_load_lds_dwordx4 v[242:243], off
	v_lshl_add_u64 v[244:245], s[90:91], 0, v[156:157]
	s_mov_b32 m0, s4
	v_lshl_add_u64 v[246:247], s[42:43], 0, v[158:159]
	global_load_lds_dwordx4 v[244:245], off
	v_lshl_add_u64 v[244:245], s[90:91], 0, v[160:161]
	s_add_i32 m0, s4, 0x2000
	s_nop 0
	global_load_lds_dwordx4 v[244:245], off
	v_lshl_add_u64 v[244:245], s[42:43], 0, v[154:155]
	s_mov_b32 m0, s69
	s_nop 0
	global_load_lds_dwordx4 v[244:245], off
	s_mov_b32 m0, s62
	s_nop 0
	global_load_lds_dwordx4 v[246:247], off
	s_waitcnt vmcnt(8)
	s_waitcnt lgkmcnt(0)
	s_barrier
	s_setprio 1
	s_waitcnt lgkmcnt(0)
	v_mfma_f32_16x16x32_bf16 v[60:63], v[128:131], v[210:213], v[60:63]
	v_mfma_f32_16x16x32_bf16 v[56:59], v[136:139], v[210:213], v[56:59]
	v_mfma_f32_16x16x32_bf16 v[52:55], v[128:131], v[218:221], v[52:55]
	v_mfma_f32_16x16x32_bf16 v[44:47], v[136:139], v[218:221], v[44:47]
	v_mfma_f32_16x16x32_bf16 v[36:39], v[128:131], v[226:229], v[36:39]
	v_mfma_f32_16x16x32_bf16 v[28:31], v[136:139], v[226:229], v[28:31]
	v_mfma_f32_16x16x32_bf16 v[20:23], v[128:131], v[234:237], v[20:23]
	v_mfma_f32_16x16x32_bf16 v[12:15], v[136:139], v[234:237], v[12:15]
	v_mfma_f32_16x16x32_bf16 v[60:63], v[132:135], v[214:217], v[60:63]
	v_mfma_f32_16x16x32_bf16 v[56:59], v[140:143], v[214:217], v[56:59]
	v_mfma_f32_16x16x32_bf16 v[52:55], v[132:135], v[222:225], v[52:55]
	v_mfma_f32_16x16x32_bf16 v[44:47], v[140:143], v[222:225], v[44:47]
	v_mfma_f32_16x16x32_bf16 v[36:39], v[132:135], v[230:233], v[36:39]
	v_mfma_f32_16x16x32_bf16 v[28:31], v[140:143], v[230:233], v[28:31]
	v_mfma_f32_16x16x32_bf16 v[20:23], v[132:135], v[238:241], v[20:23]
	v_mfma_f32_16x16x32_bf16 v[12:15], v[140:143], v[238:241], v[12:15]
	s_setprio 0
	s_setprio 1
	v_mfma_f32_16x16x32_bf16 v[48:51], v[168:171], v[210:213], v[48:51]
	v_mfma_f32_16x16x32_bf16 v[40:43], v[176:179], v[210:213], v[40:43]
	v_mfma_f32_16x16x32_bf16 v[32:35], v[168:171], v[218:221], v[32:35]
	v_mfma_f32_16x16x32_bf16 v[24:27], v[176:179], v[218:221], v[24:27]
	v_mfma_f32_16x16x32_bf16 v[16:19], v[168:171], v[226:229], v[16:19]
	v_mfma_f32_16x16x32_bf16 v[8:11], v[176:179], v[226:229], v[8:11]
	v_mfma_f32_16x16x32_bf16 v[4:7], v[168:171], v[234:237], v[4:7]
	v_mfma_f32_16x16x32_bf16 v[0:3], v[176:179], v[234:237], v[0:3]
	v_mfma_f32_16x16x32_bf16 v[48:51], v[172:175], v[214:217], v[48:51]
	v_mfma_f32_16x16x32_bf16 v[40:43], v[206:209], v[214:217], v[40:43]
	v_mfma_f32_16x16x32_bf16 v[32:35], v[172:175], v[222:225], v[32:35]
	v_mfma_f32_16x16x32_bf16 v[24:27], v[206:209], v[222:225], v[24:27]
	v_mfma_f32_16x16x32_bf16 v[16:19], v[172:175], v[230:233], v[16:19]
	v_mfma_f32_16x16x32_bf16 v[8:11], v[206:209], v[230:233], v[8:11]
	v_mfma_f32_16x16x32_bf16 v[4:7], v[172:175], v[238:241], v[4:7]
	v_mfma_f32_16x16x32_bf16 v[0:3], v[206:209], v[238:241], v[0:3]
	s_setprio 0
	s_barrier
	s_add_i32 s4, 0, 0x18000
	s_add_i32 s5, 0, 0x1c000
	s_add_u32 s42, s42, 0x40000
	s_addc_u32 s43, s43, 0
	s_mov_b32 m0, s63
	v_lshl_add_u64 v[248:249], s[42:43], 0, v[154:155]
	global_load_lds_dwordx4 v[248:249], off
	v_lshl_add_u64 v[248:249], s[42:43], 0, v[158:159]
	s_mov_b32 m0, s50
	s_nop 0
	global_load_lds_dwordx4 v[248:249], off
	v_add_u32_e32 v140, s4, v203
	v_add_u32_e32 v206, s5, v203
	ds_read_b128 v[128:131], v140
	ds_read_b128 v[132:135], v140 offset:1024
	ds_read_b128 v[136:139], v140 offset:2048
	ds_read_b128 v[140:143], v140 offset:3072
	ds_read_b128 v[168:171], v206
	ds_read_b128 v[172:175], v206 offset:1024
	ds_read_b128 v[176:179], v206 offset:2048
	ds_read_b128 v[206:209], v206 offset:3072
	ds_read_b128 v[210:213], v205 offset:32768
	ds_read_b128 v[214:217], v205 offset:33792
	ds_read_b128 v[218:221], v205 offset:34816
	ds_read_b128 v[222:225], v205 offset:35840
	ds_read_b128 v[226:229], v205 offset:36864
	ds_read_b128 v[230:233], v205 offset:37888
	ds_read_b128 v[234:237], v205 offset:38912
	ds_read_b128 v[238:241], v205 offset:39936
	s_waitcnt vmcnt(8)
	s_waitcnt lgkmcnt(0)
	s_barrier
	s_setprio 1
	s_waitcnt lgkmcnt(0)
	v_mfma_f32_16x16x32_bf16 v[124:127], v[128:131], v[210:213], v[124:127]
	v_mfma_f32_16x16x32_bf16 v[120:123], v[136:139], v[210:213], v[120:123]
	v_mfma_f32_16x16x32_bf16 v[112:115], v[128:131], v[218:221], v[112:115]
	v_mfma_f32_16x16x32_bf16 v[108:111], v[136:139], v[218:221], v[108:111]
	v_mfma_f32_16x16x32_bf16 v[100:103], v[128:131], v[226:229], v[100:103]
	v_mfma_f32_16x16x32_bf16 v[92:95], v[136:139], v[226:229], v[92:95]
	v_mfma_f32_16x16x32_bf16 v[84:87], v[128:131], v[234:237], v[84:87]
	v_mfma_f32_16x16x32_bf16 v[76:79], v[136:139], v[234:237], v[76:79]
	v_mfma_f32_16x16x32_bf16 v[124:127], v[132:135], v[214:217], v[124:127]
	v_mfma_f32_16x16x32_bf16 v[120:123], v[140:143], v[214:217], v[120:123]
	v_mfma_f32_16x16x32_bf16 v[112:115], v[132:135], v[222:225], v[112:115]
	v_mfma_f32_16x16x32_bf16 v[108:111], v[140:143], v[222:225], v[108:111]
	v_mfma_f32_16x16x32_bf16 v[100:103], v[132:135], v[230:233], v[100:103]
	v_mfma_f32_16x16x32_bf16 v[92:95], v[140:143], v[230:233], v[92:95]
	v_mfma_f32_16x16x32_bf16 v[84:87], v[132:135], v[238:241], v[84:87]
	v_mfma_f32_16x16x32_bf16 v[76:79], v[140:143], v[238:241], v[76:79]
	s_setprio 0
	s_setprio 1
	v_mfma_f32_16x16x32_bf16 v[116:119], v[168:171], v[210:213], v[116:119]
	v_mfma_f32_16x16x32_bf16 v[104:107], v[176:179], v[210:213], v[104:107]
	v_mfma_f32_16x16x32_bf16 v[96:99], v[168:171], v[218:221], v[96:99]
	v_mfma_f32_16x16x32_bf16 v[88:91], v[176:179], v[218:221], v[88:91]
	v_mfma_f32_16x16x32_bf16 v[80:83], v[168:171], v[226:229], v[80:83]
	v_mfma_f32_16x16x32_bf16 v[72:75], v[176:179], v[226:229], v[72:75]
	v_mfma_f32_16x16x32_bf16 v[68:71], v[168:171], v[234:237], v[68:71]
	v_mfma_f32_16x16x32_bf16 v[64:67], v[176:179], v[234:237], v[64:67]
	v_mfma_f32_16x16x32_bf16 v[116:119], v[172:175], v[214:217], v[116:119]
	v_mfma_f32_16x16x32_bf16 v[104:107], v[206:209], v[214:217], v[104:107]
	v_mfma_f32_16x16x32_bf16 v[96:99], v[172:175], v[222:225], v[96:99]
	v_mfma_f32_16x16x32_bf16 v[88:91], v[206:209], v[222:225], v[88:91]
	v_mfma_f32_16x16x32_bf16 v[80:83], v[172:175], v[230:233], v[80:83]
	v_mfma_f32_16x16x32_bf16 v[72:75], v[206:209], v[230:233], v[72:75]
	v_mfma_f32_16x16x32_bf16 v[68:71], v[172:175], v[238:241], v[68:71]
	v_mfma_f32_16x16x32_bf16 v[64:67], v[206:209], v[238:241], v[64:67]
	s_setprio 0
	s_barrier
	s_add_i32 s4, s4, s28
	v_lshl_add_u64 v[180:181], v[180:181], 0, s[26:27]
	s_mov_b32 m0, s4
	ds_read_b128 v[210:213], v205 offset:49152
	ds_read_b128 v[214:217], v205 offset:50176
	ds_read_b128 v[218:221], v205 offset:51200
	ds_read_b128 v[222:225], v205 offset:52224
	ds_read_b128 v[226:229], v205 offset:53248
	ds_read_b128 v[230:233], v205 offset:54272
	ds_read_b128 v[234:237], v205 offset:55296
	ds_read_b128 v[238:241], v205 offset:56320
	global_load_lds_dwordx4 v[180:181], off
	s_add_i32 m0, s4, 0x2000
	s_add_u32 s34, s34, 0x40080
	v_lshl_add_u64 v[180:181], v[242:243], 0, s[26:27]
	s_addc_u32 s35, s35, 0
	s_add_i32 s4, s5, s28
	global_load_lds_dwordx4 v[180:181], off
	v_lshl_add_u64 v[180:181], s[34:35], 0, v[156:157]
	s_mov_b32 m0, s4
	s_nop 0
	global_load_lds_dwordx4 v[180:181], off
	v_lshl_add_u64 v[180:181], s[34:35], 0, v[160:161]
	s_add_i32 m0, s4, 0x2000
	s_nop 0
	global_load_lds_dwordx4 v[180:181], off
	v_lshl_add_u64 v[180:181], v[244:245], 0, s[26:27]
	s_mov_b32 m0, s51
	s_nop 0
	global_load_lds_dwordx4 v[180:181], off
	v_lshl_add_u64 v[180:181], v[246:247], 0, s[26:27]
	s_mov_b32 m0, s64
	s_nop 0
	global_load_lds_dwordx4 v[180:181], off
	s_waitcnt vmcnt(8)
	s_waitcnt lgkmcnt(0)
	s_barrier
	s_setprio 1
	s_waitcnt lgkmcnt(0)
	v_mfma_f32_16x16x32_bf16 v[60:63], v[128:131], v[210:213], v[60:63]
	v_mfma_f32_16x16x32_bf16 v[56:59], v[136:139], v[210:213], v[56:59]
	v_mfma_f32_16x16x32_bf16 v[52:55], v[128:131], v[218:221], v[52:55]
	v_mfma_f32_16x16x32_bf16 v[44:47], v[136:139], v[218:221], v[44:47]
	v_mfma_f32_16x16x32_bf16 v[36:39], v[128:131], v[226:229], v[36:39]
	v_mfma_f32_16x16x32_bf16 v[28:31], v[136:139], v[226:229], v[28:31]
	v_mfma_f32_16x16x32_bf16 v[20:23], v[128:131], v[234:237], v[20:23]
	v_mfma_f32_16x16x32_bf16 v[12:15], v[136:139], v[234:237], v[12:15]
	v_mfma_f32_16x16x32_bf16 v[60:63], v[132:135], v[214:217], v[60:63]
	v_mfma_f32_16x16x32_bf16 v[56:59], v[140:143], v[214:217], v[56:59]
	v_mfma_f32_16x16x32_bf16 v[52:55], v[132:135], v[222:225], v[52:55]
	v_mfma_f32_16x16x32_bf16 v[44:47], v[140:143], v[222:225], v[44:47]
	v_mfma_f32_16x16x32_bf16 v[36:39], v[132:135], v[230:233], v[36:39]
	v_mfma_f32_16x16x32_bf16 v[28:31], v[140:143], v[230:233], v[28:31]
	v_mfma_f32_16x16x32_bf16 v[20:23], v[132:135], v[238:241], v[20:23]
	v_mfma_f32_16x16x32_bf16 v[12:15], v[140:143], v[238:241], v[12:15]
	s_setprio 0
	s_setprio 1
	v_mfma_f32_16x16x32_bf16 v[48:51], v[168:171], v[210:213], v[48:51]
	v_mfma_f32_16x16x32_bf16 v[40:43], v[176:179], v[210:213], v[40:43]
	v_mfma_f32_16x16x32_bf16 v[32:35], v[168:171], v[218:221], v[32:35]
	v_mfma_f32_16x16x32_bf16 v[24:27], v[176:179], v[218:221], v[24:27]
	v_mfma_f32_16x16x32_bf16 v[16:19], v[168:171], v[226:229], v[16:19]
	v_mfma_f32_16x16x32_bf16 v[8:11], v[176:179], v[226:229], v[8:11]
	v_mfma_f32_16x16x32_bf16 v[4:7], v[168:171], v[234:237], v[4:7]
	v_mfma_f32_16x16x32_bf16 v[0:3], v[176:179], v[234:237], v[0:3]
	v_mfma_f32_16x16x32_bf16 v[48:51], v[172:175], v[214:217], v[48:51]
	v_mfma_f32_16x16x32_bf16 v[40:43], v[206:209], v[214:217], v[40:43]
	v_mfma_f32_16x16x32_bf16 v[32:35], v[172:175], v[222:225], v[32:35]
	v_mfma_f32_16x16x32_bf16 v[24:27], v[206:209], v[222:225], v[24:27]
	v_mfma_f32_16x16x32_bf16 v[16:19], v[172:175], v[230:233], v[16:19]
	v_mfma_f32_16x16x32_bf16 v[8:11], v[206:209], v[230:233], v[8:11]
	v_mfma_f32_16x16x32_bf16 v[4:7], v[172:175], v[238:241], v[4:7]
	v_mfma_f32_16x16x32_bf16 v[0:3], v[206:209], v[238:241], v[0:3]
	s_setprio 0
	s_barrier
	s_add_i32 s88, s88, 2
	s_add_u32 s0, s0, 0x100
	s_addc_u32 s1, s1, 0
	s_add_u32 s79, s79, 0x100
	s_addc_u32 s84, s84, 0
	s_cmp_gt_u32 s88, 13
	s_cbranch_scc0 .LBB0_605
	s_and_b64 vcc, exec, s[66:67]
	s_cbranch_vccz .LBB0_608
	s_barrier

.LBB0_1005:
	s_add_u32 s4, s54, 0xfffe0080
	s_addc_u32 s5, s55, -1
	s_add_i32 s72, 0, 0x10000
	s_cmp_eq_u32 s71, 4
	s_cselect_b32 s59, s29, s5
	s_cselect_b32 s58, s47, s4
	s_cselect_b32 s35, s45, s70
	s_cselect_b32 s34, s68, s69
	s_add_i32 s73, 0, 0x14000
	v_lshl_add_u64 v[138:139], s[54:55], 0, v[134:135]
	s_add_i32 m0, s53, 0xc000
	s_nop 0
	global_load_lds_dwordx4 v[138:139], off
	v_lshl_add_u64 v[138:139], s[54:55], 0, v[136:137]
	s_add_i32 m0, s53, 0xe000
	s_nop 0
	global_load_lds_dwordx4 v[138:139], off
	v_add_u32_e32 v166, s72, v141
	ds_read_b128 v[154:157], v166
	ds_read_b128 v[158:161], v166 offset:1024
	ds_read_b128 v[162:165], v166 offset:2048
	ds_read_b128 v[166:169], v166 offset:3072
	v_add_u32_e32 v204, s73, v141
	ds_read_b128 v[170:173], v204
	ds_read_b128 v[174:177], v204 offset:1024
	ds_read_b128 v[178:181], v204 offset:2048
	ds_read_b128 v[204:207], v204 offset:3072
	ds_read_b128 v[208:211], v143
	ds_read_b128 v[212:215], v143 offset:1024
	ds_read_b128 v[216:219], v143 offset:2048
	ds_read_b128 v[220:223], v143 offset:3072
	ds_read_b128 v[224:227], v143 offset:4096
	ds_read_b128 v[228:231], v143 offset:5120
	ds_read_b128 v[232:235], v143 offset:6144
	ds_read_b128 v[236:239], v143 offset:7168
	s_waitcnt vmcnt(8)
	s_waitcnt lgkmcnt(0)
	s_barrier
	s_setprio 1
	s_waitcnt lgkmcnt(0)
	v_mfma_f32_16x16x32_bf16 v[120:123], v[154:157], v[208:211], v[120:123]
	v_mfma_f32_16x16x32_bf16 v[124:127], v[162:165], v[208:211], v[124:127]
	v_mfma_f32_16x16x32_bf16 v[104:107], v[154:157], v[216:219], v[104:107]
	v_mfma_f32_16x16x32_bf16 v[108:111], v[162:165], v[216:219], v[108:111]
	v_mfma_f32_16x16x32_bf16 v[88:91], v[154:157], v[224:227], v[88:91]
	v_mfma_f32_16x16x32_bf16 v[92:95], v[162:165], v[224:227], v[92:95]
	v_mfma_f32_16x16x32_bf16 v[72:75], v[154:157], v[232:235], v[72:75]
	v_mfma_f32_16x16x32_bf16 v[76:79], v[162:165], v[232:235], v[76:79]
	v_mfma_f32_16x16x32_bf16 v[120:123], v[158:161], v[212:215], v[120:123]
	v_mfma_f32_16x16x32_bf16 v[124:127], v[166:169], v[212:215], v[124:127]
	v_mfma_f32_16x16x32_bf16 v[104:107], v[158:161], v[220:223], v[104:107]
	v_mfma_f32_16x16x32_bf16 v[108:111], v[166:169], v[220:223], v[108:111]
	v_mfma_f32_16x16x32_bf16 v[88:91], v[158:161], v[228:231], v[88:91]
	v_mfma_f32_16x16x32_bf16 v[92:95], v[166:169], v[228:231], v[92:95]
	v_mfma_f32_16x16x32_bf16 v[72:75], v[158:161], v[236:239], v[72:75]
	v_mfma_f32_16x16x32_bf16 v[76:79], v[166:169], v[236:239], v[76:79]
	s_setprio 0
	s_setprio 1
	v_mfma_f32_16x16x32_bf16 v[112:115], v[170:173], v[208:211], v[112:115]
	v_mfma_f32_16x16x32_bf16 v[116:119], v[178:181], v[208:211], v[116:119]
	v_mfma_f32_16x16x32_bf16 v[96:99], v[170:173], v[216:219], v[96:99]
	v_mfma_f32_16x16x32_bf16 v[100:103], v[178:181], v[216:219], v[100:103]
	v_mfma_f32_16x16x32_bf16 v[80:83], v[170:173], v[224:227], v[80:83]
	v_mfma_f32_16x16x32_bf16 v[84:87], v[178:181], v[224:227], v[84:87]
	v_mfma_f32_16x16x32_bf16 v[64:67], v[170:173], v[232:235], v[64:67]
	v_mfma_f32_16x16x32_bf16 v[68:71], v[178:181], v[232:235], v[68:71]
	v_mfma_f32_16x16x32_bf16 v[112:115], v[174:177], v[212:215], v[112:115]
	v_mfma_f32_16x16x32_bf16 v[116:119], v[204:207], v[212:215], v[116:119]
	v_mfma_f32_16x16x32_bf16 v[96:99], v[174:177], v[220:223], v[96:99]
	v_mfma_f32_16x16x32_bf16 v[100:103], v[204:207], v[220:223], v[100:103]
	v_mfma_f32_16x16x32_bf16 v[80:83], v[174:177], v[228:231], v[80:83]
	v_mfma_f32_16x16x32_bf16 v[84:87], v[204:207], v[228:231], v[84:87]
	v_mfma_f32_16x16x32_bf16 v[64:67], v[174:177], v[236:239], v[64:67]
	v_mfma_f32_16x16x32_bf16 v[68:71], v[204:207], v[236:239], v[68:71]
	s_setprio 0
	s_barrier
	s_add_i32 s4, s72, s30
	v_lshl_add_u64 v[138:139], s[34:35], 0, v[144:145]
	s_mov_b32 m0, s4
	ds_read_b128 v[208:211], v143 offset:16384
	ds_read_b128 v[212:215], v143 offset:17408
	ds_read_b128 v[216:219], v143 offset:18432
	ds_read_b128 v[220:223], v143 offset:19456
	ds_read_b128 v[224:227], v143 offset:20480
	ds_read_b128 v[228:231], v143 offset:21504
	ds_read_b128 v[232:235], v143 offset:22528
	ds_read_b128 v[236:239], v143 offset:23552
	global_load_lds_dwordx4 v[138:139], off
	s_add_i32 m0, s4, 0x2000
	s_add_u32 s4, s34, 0x20000
	v_lshl_add_u64 v[202:203], s[34:35], 0, v[132:133]
	s_addc_u32 s5, s35, 0
	s_add_i32 s72, s73, s30
	global_load_lds_dwordx4 v[202:203], off
	v_lshl_add_u64 v[240:241], s[4:5], 0, v[144:145]
	s_mov_b32 m0, s72
	v_lshl_add_u64 v[242:243], s[58:59], 0, v[130:131]
	global_load_lds_dwordx4 v[240:241], off
	v_lshl_add_u64 v[240:241], s[4:5], 0, v[132:133]
	s_add_i32 m0, s72, 0x2000
	s_nop 0
	global_load_lds_dwordx4 v[240:241], off
	v_lshl_add_u64 v[240:241], s[58:59], 0, v[128:129]
	s_mov_b32 m0, s53
	s_nop 0
	global_load_lds_dwordx4 v[240:241], off
	s_mov_b32 m0, s62
	s_nop 0
	global_load_lds_dwordx4 v[242:243], off
	s_waitcnt vmcnt(8)
	s_waitcnt lgkmcnt(0)
	s_barrier
	s_setprio 1
	s_waitcnt lgkmcnt(0)
	v_mfma_f32_16x16x32_bf16 v[56:59], v[154:157], v[208:211], v[56:59]
	v_mfma_f32_16x16x32_bf16 v[60:63], v[162:165], v[208:211], v[60:63]
	v_mfma_f32_16x16x32_bf16 v[40:43], v[154:157], v[216:219], v[40:43]
	v_mfma_f32_16x16x32_bf16 v[44:47], v[162:165], v[216:219], v[44:47]
	v_mfma_f32_16x16x32_bf16 v[24:27], v[154:157], v[224:227], v[24:27]
	v_mfma_f32_16x16x32_bf16 v[28:31], v[162:165], v[224:227], v[28:31]
	v_mfma_f32_16x16x32_bf16 v[8:11], v[154:157], v[232:235], v[8:11]
	v_mfma_f32_16x16x32_bf16 v[12:15], v[162:165], v[232:235], v[12:15]
	v_mfma_f32_16x16x32_bf16 v[56:59], v[158:161], v[212:215], v[56:59]
	v_mfma_f32_16x16x32_bf16 v[60:63], v[166:169], v[212:215], v[60:63]
	v_mfma_f32_16x16x32_bf16 v[40:43], v[158:161], v[220:223], v[40:43]
	v_mfma_f32_16x16x32_bf16 v[44:47], v[166:169], v[220:223], v[44:47]
	v_mfma_f32_16x16x32_bf16 v[24:27], v[158:161], v[228:231], v[24:27]
	v_mfma_f32_16x16x32_bf16 v[28:31], v[166:169], v[228:231], v[28:31]
	v_mfma_f32_16x16x32_bf16 v[8:11], v[158:161], v[236:239], v[8:11]
	v_mfma_f32_16x16x32_bf16 v[12:15], v[166:169], v[236:239], v[12:15]
	s_setprio 0
	s_setprio 1
	v_mfma_f32_16x16x32_bf16 v[48:51], v[170:173], v[208:211], v[48:51]
	v_mfma_f32_16x16x32_bf16 v[52:55], v[178:181], v[208:211], v[52:55]
	v_mfma_f32_16x16x32_bf16 v[32:35], v[170:173], v[216:219], v[32:35]
	v_mfma_f32_16x16x32_bf16 v[36:39], v[178:181], v[216:219], v[36:39]
	v_mfma_f32_16x16x32_bf16 v[16:19], v[170:173], v[224:227], v[16:19]
	v_mfma_f32_16x16x32_bf16 v[20:23], v[178:181], v[224:227], v[20:23]
	v_mfma_f32_16x16x32_bf16 v[0:3], v[170:173], v[232:235], v[0:3]
	v_mfma_f32_16x16x32_bf16 v[4:7], v[178:181], v[232:235], v[4:7]
	v_mfma_f32_16x16x32_bf16 v[48:51], v[174:177], v[212:215], v[48:51]
	v_mfma_f32_16x16x32_bf16 v[52:55], v[204:207], v[212:215], v[52:55]
	v_mfma_f32_16x16x32_bf16 v[32:35], v[174:177], v[220:223], v[32:35]
	v_mfma_f32_16x16x32_bf16 v[36:39], v[204:207], v[220:223], v[36:39]
	v_mfma_f32_16x16x32_bf16 v[16:19], v[174:177], v[228:231], v[16:19]
	v_mfma_f32_16x16x32_bf16 v[20:23], v[204:207], v[228:231], v[20:23]
	v_mfma_f32_16x16x32_bf16 v[0:3], v[174:177], v[236:239], v[0:3]
	v_mfma_f32_16x16x32_bf16 v[4:7], v[204:207], v[236:239], v[4:7]
	s_setprio 0
	s_barrier
	s_add_i32 s72, 0, 0x18000
	s_add_i32 s73, 0, 0x1c000
	s_add_u32 s4, s58, 0x20000
	s_addc_u32 s5, s59, 0
	s_mov_b32 m0, s63
	v_lshl_add_u64 v[244:245], s[4:5], 0, v[128:129]
	global_load_lds_dwordx4 v[244:245], off
	v_lshl_add_u64 v[244:245], s[4:5], 0, v[130:131]
	s_mov_b32 m0, s64
	s_nop 0
	global_load_lds_dwordx4 v[244:245], off
	v_add_u32_e32 v166, s72, v141
	v_add_u32_e32 v204, s73, v141
	ds_read_b128 v[154:157], v166
	ds_read_b128 v[158:161], v166 offset:1024
	ds_read_b128 v[162:165], v166 offset:2048
	ds_read_b128 v[166:169], v166 offset:3072
	ds_read_b128 v[170:173], v204
	ds_read_b128 v[174:177], v204 offset:1024
	ds_read_b128 v[178:181], v204 offset:2048
	ds_read_b128 v[204:207], v204 offset:3072
	ds_read_b128 v[208:211], v143 offset:32768
	ds_read_b128 v[212:215], v143 offset:33792
	ds_read_b128 v[216:219], v143 offset:34816
	ds_read_b128 v[220:223], v143 offset:35840
	ds_read_b128 v[224:227], v143 offset:36864
	ds_read_b128 v[228:231], v143 offset:37888
	ds_read_b128 v[232:235], v143 offset:38912
	ds_read_b128 v[236:239], v143 offset:39936
	s_waitcnt vmcnt(8)
	s_waitcnt lgkmcnt(0)
	s_barrier
	s_setprio 1
	s_waitcnt lgkmcnt(0)
	v_mfma_f32_16x16x32_bf16 v[120:123], v[154:157], v[208:211], v[120:123]
	v_mfma_f32_16x16x32_bf16 v[124:127], v[162:165], v[208:211], v[124:127]
	v_mfma_f32_16x16x32_bf16 v[104:107], v[154:157], v[216:219], v[104:107]
	v_mfma_f32_16x16x32_bf16 v[108:111], v[162:165], v[216:219], v[108:111]
	v_mfma_f32_16x16x32_bf16 v[88:91], v[154:157], v[224:227], v[88:91]
	v_mfma_f32_16x16x32_bf16 v[92:95], v[162:165], v[224:227], v[92:95]
	v_mfma_f32_16x16x32_bf16 v[72:75], v[154:157], v[232:235], v[72:75]
	v_mfma_f32_16x16x32_bf16 v[76:79], v[162:165], v[232:235], v[76:79]
	v_mfma_f32_16x16x32_bf16 v[120:123], v[158:161], v[212:215], v[120:123]
	v_mfma_f32_16x16x32_bf16 v[124:127], v[166:169], v[212:215], v[124:127]
	v_mfma_f32_16x16x32_bf16 v[104:107], v[158:161], v[220:223], v[104:107]
	v_mfma_f32_16x16x32_bf16 v[108:111], v[166:169], v[220:223], v[108:111]
	v_mfma_f32_16x16x32_bf16 v[88:91], v[158:161], v[228:231], v[88:91]
	v_mfma_f32_16x16x32_bf16 v[92:95], v[166:169], v[228:231], v[92:95]
	v_mfma_f32_16x16x32_bf16 v[72:75], v[158:161], v[236:239], v[72:75]
	v_mfma_f32_16x16x32_bf16 v[76:79], v[166:169], v[236:239], v[76:79]
	s_setprio 0
	s_setprio 1
	v_mfma_f32_16x16x32_bf16 v[112:115], v[170:173], v[208:211], v[112:115]
	v_mfma_f32_16x16x32_bf16 v[116:119], v[178:181], v[208:211], v[116:119]
	v_mfma_f32_16x16x32_bf16 v[96:99], v[170:173], v[216:219], v[96:99]
	v_mfma_f32_16x16x32_bf16 v[100:103], v[178:181], v[216:219], v[100:103]
	v_mfma_f32_16x16x32_bf16 v[80:83], v[170:173], v[224:227], v[80:83]
	v_mfma_f32_16x16x32_bf16 v[84:87], v[178:181], v[224:227], v[84:87]
	v_mfma_f32_16x16x32_bf16 v[64:67], v[170:173], v[232:235], v[64:67]
	v_mfma_f32_16x16x32_bf16 v[68:71], v[178:181], v[232:235], v[68:71]
	v_mfma_f32_16x16x32_bf16 v[112:115], v[174:177], v[212:215], v[112:115]
	v_mfma_f32_16x16x32_bf16 v[116:119], v[204:207], v[212:215], v[116:119]
	v_mfma_f32_16x16x32_bf16 v[96:99], v[174:177], v[220:223], v[96:99]
	v_mfma_f32_16x16x32_bf16 v[100:103], v[204:207], v[220:223], v[100:103]
	v_mfma_f32_16x16x32_bf16 v[80:83], v[174:177], v[228:231], v[80:83]
	v_mfma_f32_16x16x32_bf16 v[84:87], v[204:207], v[228:231], v[84:87]
	v_mfma_f32_16x16x32_bf16 v[64:67], v[174:177], v[236:239], v[64:67]
	v_mfma_f32_16x16x32_bf16 v[68:71], v[204:207], v[236:239], v[68:71]
	s_setprio 0
	s_barrier
	s_add_i32 s4, s72, s30
	v_lshl_add_u64 v[138:139], v[138:139], 0, s[26:27]
	s_mov_b32 m0, s4
	ds_read_b128 v[208:211], v143 offset:49152
	ds_read_b128 v[212:215], v143 offset:50176
	ds_read_b128 v[216:219], v143 offset:51200
	ds_read_b128 v[220:223], v143 offset:52224
	ds_read_b128 v[224:227], v143 offset:53248
	ds_read_b128 v[228:231], v143 offset:54272
	ds_read_b128 v[232:235], v143 offset:55296
	ds_read_b128 v[236:239], v143 offset:56320
	global_load_lds_dwordx4 v[138:139], off
	s_add_i32 m0, s4, 0x2000
	s_add_u32 s4, s34, 0x20080
	v_lshl_add_u64 v[138:139], v[202:203], 0, s[26:27]
	s_addc_u32 s5, s35, 0
	s_add_i32 s34, s73, s30
	global_load_lds_dwordx4 v[138:139], off
	v_lshl_add_u64 v[138:139], s[4:5], 0, v[144:145]
	s_mov_b32 m0, s34
	s_nop 0
	global_load_lds_dwordx4 v[138:139], off
	v_lshl_add_u64 v[138:139], s[4:5], 0, v[132:133]
	s_add_i32 m0, s34, 0x2000
	s_nop 0
	global_load_lds_dwordx4 v[138:139], off
	v_lshl_add_u64 v[138:139], v[240:241], 0, s[26:27]
	s_mov_b32 m0, s65
	s_nop 0
	global_load_lds_dwordx4 v[138:139], off
	v_lshl_add_u64 v[138:139], v[242:243], 0, s[26:27]
	s_mov_b32 m0, s66
	s_nop 0
	global_load_lds_dwordx4 v[138:139], off
	s_waitcnt vmcnt(8)
	s_waitcnt lgkmcnt(0)
	s_barrier
	s_setprio 1
	s_waitcnt lgkmcnt(0)
	v_mfma_f32_16x16x32_bf16 v[56:59], v[154:157], v[208:211], v[56:59]
	v_mfma_f32_16x16x32_bf16 v[60:63], v[162:165], v[208:211], v[60:63]
	v_mfma_f32_16x16x32_bf16 v[40:43], v[154:157], v[216:219], v[40:43]
	v_mfma_f32_16x16x32_bf16 v[44:47], v[162:165], v[216:219], v[44:47]
	v_mfma_f32_16x16x32_bf16 v[24:27], v[154:157], v[224:227], v[24:27]
	v_mfma_f32_16x16x32_bf16 v[28:31], v[162:165], v[224:227], v[28:31]
	v_mfma_f32_16x16x32_bf16 v[8:11], v[154:157], v[232:235], v[8:11]
	v_mfma_f32_16x16x32_bf16 v[12:15], v[162:165], v[232:235], v[12:15]
	v_mfma_f32_16x16x32_bf16 v[56:59], v[158:161], v[212:215], v[56:59]
	v_mfma_f32_16x16x32_bf16 v[60:63], v[166:169], v[212:215], v[60:63]
	v_mfma_f32_16x16x32_bf16 v[40:43], v[158:161], v[220:223], v[40:43]
	v_mfma_f32_16x16x32_bf16 v[44:47], v[166:169], v[220:223], v[44:47]
	v_mfma_f32_16x16x32_bf16 v[24:27], v[158:161], v[228:231], v[24:27]
	v_mfma_f32_16x16x32_bf16 v[28:31], v[166:169], v[228:231], v[28:31]
	v_mfma_f32_16x16x32_bf16 v[8:11], v[158:161], v[236:239], v[8:11]
	v_mfma_f32_16x16x32_bf16 v[12:15], v[166:169], v[236:239], v[12:15]
	s_setprio 0
	s_setprio 1
	v_mfma_f32_16x16x32_bf16 v[48:51], v[170:173], v[208:211], v[48:51]
	v_mfma_f32_16x16x32_bf16 v[52:55], v[178:181], v[208:211], v[52:55]
	v_mfma_f32_16x16x32_bf16 v[32:35], v[170:173], v[216:219], v[32:35]
	v_mfma_f32_16x16x32_bf16 v[36:39], v[178:181], v[216:219], v[36:39]
	v_mfma_f32_16x16x32_bf16 v[16:19], v[170:173], v[224:227], v[16:19]
	v_mfma_f32_16x16x32_bf16 v[20:23], v[178:181], v[224:227], v[20:23]
	v_mfma_f32_16x16x32_bf16 v[0:3], v[170:173], v[232:235], v[0:3]
	v_mfma_f32_16x16x32_bf16 v[4:7], v[178:181], v[232:235], v[4:7]
	v_mfma_f32_16x16x32_bf16 v[48:51], v[174:177], v[212:215], v[48:51]
	v_mfma_f32_16x16x32_bf16 v[52:55], v[204:207], v[212:215], v[52:55]
	v_mfma_f32_16x16x32_bf16 v[32:35], v[174:177], v[220:223], v[32:35]
	v_mfma_f32_16x16x32_bf16 v[36:39], v[204:207], v[220:223], v[36:39]
	v_mfma_f32_16x16x32_bf16 v[16:19], v[174:177], v[228:231], v[16:19]
	v_mfma_f32_16x16x32_bf16 v[20:23], v[204:207], v[228:231], v[20:23]
	v_mfma_f32_16x16x32_bf16 v[0:3], v[174:177], v[236:239], v[0:3]
	v_mfma_f32_16x16x32_bf16 v[4:7], v[204:207], v[236:239], v[4:7]
	s_setprio 0
	s_barrier
	s_add_i32 s71, s71, 2
	s_add_u32 s54, s54, 0x100
	s_addc_u32 s55, s55, 0
	s_add_u32 s69, s69, 0x100
	s_addc_u32 s70, s70, 0
	s_cmp_gt_u32 s71, 5
	s_cbranch_scc0 .LBB0_1005
	v_readlane_b32 s68, v255, 7
	s_and_b64 vcc, exec, s[42:43]
	v_readlane_b32 s69, v255, 8
	s_cbranch_vccz .LBB0_1008
	s_barrier

.LBB0_1093:
	s_add_u32 s4, s58, 0xfffe0080
	s_addc_u32 s5, s59, -1
	s_add_i32 s74, 0, 0x10000
	s_cmp_eq_u32 s73, 4
	s_cselect_b32 s61, s33, s5
	s_cselect_b32 s60, s36, s4
	s_cselect_b32 s35, s49, s72
	s_cselect_b32 s34, s51, s71
	s_add_i32 s75, 0, 0x14000
	v_lshl_add_u64 v[180:181], s[58:59], 0, v[134:135]
	s_add_i32 m0, s64, 0xc000
	s_nop 0
	global_load_lds_dwordx4 v[180:181], off
	v_lshl_add_u64 v[180:181], s[58:59], 0, v[136:137]
	s_add_i32 m0, s64, 0xe000
	s_nop 0
	global_load_lds_dwordx4 v[180:181], off
	v_add_u32_e32 v164, s74, v143
	v_add_u32_e32 v204, s75, v143
	ds_read_b128 v[138:141], v164
	ds_read_b128 v[156:159], v164 offset:1024
	ds_read_b128 v[160:163], v164 offset:2048
	ds_read_b128 v[164:167], v164 offset:3072
	ds_read_b128 v[168:171], v204
	ds_read_b128 v[172:175], v204 offset:1024
	ds_read_b128 v[176:179], v204 offset:2048
	ds_read_b128 v[204:207], v204 offset:3072
	ds_read_b128 v[208:211], v155
	ds_read_b128 v[212:215], v155 offset:1024
	ds_read_b128 v[216:219], v155 offset:2048
	ds_read_b128 v[220:223], v155 offset:3072
	ds_read_b128 v[224:227], v155 offset:4096
	ds_read_b128 v[228:231], v155 offset:5120
	ds_read_b128 v[232:235], v155 offset:6144
	ds_read_b128 v[236:239], v155 offset:7168
	s_waitcnt vmcnt(8)
	s_waitcnt lgkmcnt(0)
	s_barrier
	s_setprio 1
	s_waitcnt lgkmcnt(0)
	v_mfma_f32_16x16x32_bf16 v[124:127], v[138:141], v[208:211], v[124:127]
	v_mfma_f32_16x16x32_bf16 v[120:123], v[160:163], v[208:211], v[120:123]
	v_mfma_f32_16x16x32_bf16 v[108:111], v[138:141], v[216:219], v[108:111]
	v_mfma_f32_16x16x32_bf16 v[104:107], v[160:163], v[216:219], v[104:107]
	v_mfma_f32_16x16x32_bf16 v[92:95], v[138:141], v[224:227], v[92:95]
	v_mfma_f32_16x16x32_bf16 v[88:91], v[160:163], v[224:227], v[88:91]
	v_mfma_f32_16x16x32_bf16 v[76:79], v[138:141], v[232:235], v[76:79]
	v_mfma_f32_16x16x32_bf16 v[72:75], v[160:163], v[232:235], v[72:75]
	v_mfma_f32_16x16x32_bf16 v[124:127], v[156:159], v[212:215], v[124:127]
	v_mfma_f32_16x16x32_bf16 v[120:123], v[164:167], v[212:215], v[120:123]
	v_mfma_f32_16x16x32_bf16 v[108:111], v[156:159], v[220:223], v[108:111]
	v_mfma_f32_16x16x32_bf16 v[104:107], v[164:167], v[220:223], v[104:107]
	v_mfma_f32_16x16x32_bf16 v[92:95], v[156:159], v[228:231], v[92:95]
	v_mfma_f32_16x16x32_bf16 v[88:91], v[164:167], v[228:231], v[88:91]
	v_mfma_f32_16x16x32_bf16 v[76:79], v[156:159], v[236:239], v[76:79]
	v_mfma_f32_16x16x32_bf16 v[72:75], v[164:167], v[236:239], v[72:75]
	s_setprio 0
	s_setprio 1
	v_mfma_f32_16x16x32_bf16 v[116:119], v[168:171], v[208:211], v[116:119]
	v_mfma_f32_16x16x32_bf16 v[112:115], v[176:179], v[208:211], v[112:115]
	v_mfma_f32_16x16x32_bf16 v[100:103], v[168:171], v[216:219], v[100:103]
	v_mfma_f32_16x16x32_bf16 v[96:99], v[176:179], v[216:219], v[96:99]
	v_mfma_f32_16x16x32_bf16 v[84:87], v[168:171], v[224:227], v[84:87]
	v_mfma_f32_16x16x32_bf16 v[80:83], v[176:179], v[224:227], v[80:83]
	v_mfma_f32_16x16x32_bf16 v[68:71], v[168:171], v[232:235], v[68:71]
	v_mfma_f32_16x16x32_bf16 v[64:67], v[176:179], v[232:235], v[64:67]
	v_mfma_f32_16x16x32_bf16 v[116:119], v[172:175], v[212:215], v[116:119]
	v_mfma_f32_16x16x32_bf16 v[112:115], v[204:207], v[212:215], v[112:115]
	v_mfma_f32_16x16x32_bf16 v[100:103], v[172:175], v[220:223], v[100:103]
	v_mfma_f32_16x16x32_bf16 v[96:99], v[204:207], v[220:223], v[96:99]
	v_mfma_f32_16x16x32_bf16 v[84:87], v[172:175], v[228:231], v[84:87]
	v_mfma_f32_16x16x32_bf16 v[80:83], v[204:207], v[228:231], v[80:83]
	v_mfma_f32_16x16x32_bf16 v[68:71], v[172:175], v[236:239], v[68:71]
	v_mfma_f32_16x16x32_bf16 v[64:67], v[204:207], v[236:239], v[64:67]
	s_setprio 0
	s_barrier
	s_add_i32 s4, s74, s28
	v_lshl_add_u64 v[180:181], s[34:35], 0, v[144:145]
	s_mov_b32 m0, s4
	ds_read_b128 v[208:211], v155 offset:16384
	ds_read_b128 v[212:215], v155 offset:17408
	ds_read_b128 v[216:219], v155 offset:18432
	ds_read_b128 v[220:223], v155 offset:19456
	ds_read_b128 v[224:227], v155 offset:20480
	ds_read_b128 v[228:231], v155 offset:21504
	ds_read_b128 v[232:235], v155 offset:22528
	ds_read_b128 v[236:239], v155 offset:23552
	global_load_lds_dwordx4 v[180:181], off
	s_add_i32 m0, s4, 0x2000
	s_add_u32 s4, s34, 0x20000
	v_lshl_add_u64 v[202:203], s[34:35], 0, v[132:133]
	s_addc_u32 s5, s35, 0
	s_add_i32 s74, s75, s28
	global_load_lds_dwordx4 v[202:203], off
	v_lshl_add_u64 v[240:241], s[4:5], 0, v[144:145]
	s_mov_b32 m0, s74
	v_lshl_add_u64 v[242:243], s[60:61], 0, v[130:131]
	global_load_lds_dwordx4 v[240:241], off
	v_lshl_add_u64 v[240:241], s[4:5], 0, v[132:133]
	s_add_i32 m0, s74, 0x2000
	s_nop 0
	global_load_lds_dwordx4 v[240:241], off
	v_lshl_add_u64 v[240:241], s[60:61], 0, v[128:129]
	s_mov_b32 m0, s64
	s_nop 0
	global_load_lds_dwordx4 v[240:241], off
	s_mov_b32 m0, s65
	s_nop 0
	global_load_lds_dwordx4 v[242:243], off
	s_waitcnt vmcnt(8)
	s_waitcnt lgkmcnt(0)
	s_barrier
	s_setprio 1
	s_waitcnt lgkmcnt(0)
	v_mfma_f32_16x16x32_bf16 v[60:63], v[138:141], v[208:211], v[60:63]
	v_mfma_f32_16x16x32_bf16 v[56:59], v[160:163], v[208:211], v[56:59]
	v_mfma_f32_16x16x32_bf16 v[44:47], v[138:141], v[216:219], v[44:47]
	v_mfma_f32_16x16x32_bf16 v[40:43], v[160:163], v[216:219], v[40:43]
	v_mfma_f32_16x16x32_bf16 v[28:31], v[138:141], v[224:227], v[28:31]
	v_mfma_f32_16x16x32_bf16 v[24:27], v[160:163], v[224:227], v[24:27]
	v_mfma_f32_16x16x32_bf16 v[12:15], v[138:141], v[232:235], v[12:15]
	v_mfma_f32_16x16x32_bf16 v[8:11], v[160:163], v[232:235], v[8:11]
	v_mfma_f32_16x16x32_bf16 v[60:63], v[156:159], v[212:215], v[60:63]
	v_mfma_f32_16x16x32_bf16 v[56:59], v[164:167], v[212:215], v[56:59]
	v_mfma_f32_16x16x32_bf16 v[44:47], v[156:159], v[220:223], v[44:47]
	v_mfma_f32_16x16x32_bf16 v[40:43], v[164:167], v[220:223], v[40:43]
	v_mfma_f32_16x16x32_bf16 v[28:31], v[156:159], v[228:231], v[28:31]
	v_mfma_f32_16x16x32_bf16 v[24:27], v[164:167], v[228:231], v[24:27]
	v_mfma_f32_16x16x32_bf16 v[12:15], v[156:159], v[236:239], v[12:15]
	v_mfma_f32_16x16x32_bf16 v[8:11], v[164:167], v[236:239], v[8:11]
	s_setprio 0
	s_setprio 1
	v_mfma_f32_16x16x32_bf16 v[52:55], v[168:171], v[208:211], v[52:55]
	v_mfma_f32_16x16x32_bf16 v[48:51], v[176:179], v[208:211], v[48:51]
	v_mfma_f32_16x16x32_bf16 v[36:39], v[168:171], v[216:219], v[36:39]
	v_mfma_f32_16x16x32_bf16 v[32:35], v[176:179], v[216:219], v[32:35]
	v_mfma_f32_16x16x32_bf16 v[20:23], v[168:171], v[224:227], v[20:23]
	v_mfma_f32_16x16x32_bf16 v[16:19], v[176:179], v[224:227], v[16:19]
	v_mfma_f32_16x16x32_bf16 v[4:7], v[168:171], v[232:235], v[4:7]
	v_mfma_f32_16x16x32_bf16 v[0:3], v[176:179], v[232:235], v[0:3]
	v_mfma_f32_16x16x32_bf16 v[52:55], v[172:175], v[212:215], v[52:55]
	v_mfma_f32_16x16x32_bf16 v[48:51], v[204:207], v[212:215], v[48:51]
	v_mfma_f32_16x16x32_bf16 v[36:39], v[172:175], v[220:223], v[36:39]
	v_mfma_f32_16x16x32_bf16 v[32:35], v[204:207], v[220:223], v[32:35]
	v_mfma_f32_16x16x32_bf16 v[20:23], v[172:175], v[228:231], v[20:23]
	v_mfma_f32_16x16x32_bf16 v[16:19], v[204:207], v[228:231], v[16:19]
	v_mfma_f32_16x16x32_bf16 v[4:7], v[172:175], v[236:239], v[4:7]
	v_mfma_f32_16x16x32_bf16 v[0:3], v[204:207], v[236:239], v[0:3]
	s_setprio 0
	s_barrier
	s_add_i32 s74, 0, 0x18000
	s_add_i32 s75, 0, 0x1c000
	s_add_u32 s4, s60, 0x20000
	s_addc_u32 s5, s61, 0
	s_mov_b32 m0, s66
	v_lshl_add_u64 v[244:245], s[4:5], 0, v[128:129]
	global_load_lds_dwordx4 v[244:245], off
	v_lshl_add_u64 v[244:245], s[4:5], 0, v[130:131]
	s_mov_b32 m0, s67
	s_nop 0
	global_load_lds_dwordx4 v[244:245], off
	v_add_u32_e32 v164, s74, v143
	v_add_u32_e32 v204, s75, v143
	ds_read_b128 v[138:141], v164
	ds_read_b128 v[156:159], v164 offset:1024
	ds_read_b128 v[160:163], v164 offset:2048
	ds_read_b128 v[164:167], v164 offset:3072
	ds_read_b128 v[168:171], v204
	ds_read_b128 v[172:175], v204 offset:1024
	ds_read_b128 v[176:179], v204 offset:2048
	ds_read_b128 v[204:207], v204 offset:3072
	ds_read_b128 v[208:211], v155 offset:32768
	ds_read_b128 v[212:215], v155 offset:33792
	ds_read_b128 v[216:219], v155 offset:34816
	ds_read_b128 v[220:223], v155 offset:35840
	ds_read_b128 v[224:227], v155 offset:36864
	ds_read_b128 v[228:231], v155 offset:37888
	ds_read_b128 v[232:235], v155 offset:38912
	ds_read_b128 v[236:239], v155 offset:39936
	s_waitcnt vmcnt(8)
	s_waitcnt lgkmcnt(0)
	s_barrier
	s_setprio 1
	s_waitcnt lgkmcnt(0)
	v_mfma_f32_16x16x32_bf16 v[124:127], v[138:141], v[208:211], v[124:127]
	v_mfma_f32_16x16x32_bf16 v[120:123], v[160:163], v[208:211], v[120:123]
	v_mfma_f32_16x16x32_bf16 v[108:111], v[138:141], v[216:219], v[108:111]
	v_mfma_f32_16x16x32_bf16 v[104:107], v[160:163], v[216:219], v[104:107]
	v_mfma_f32_16x16x32_bf16 v[92:95], v[138:141], v[224:227], v[92:95]
	v_mfma_f32_16x16x32_bf16 v[88:91], v[160:163], v[224:227], v[88:91]
	v_mfma_f32_16x16x32_bf16 v[76:79], v[138:141], v[232:235], v[76:79]
	v_mfma_f32_16x16x32_bf16 v[72:75], v[160:163], v[232:235], v[72:75]
	v_mfma_f32_16x16x32_bf16 v[124:127], v[156:159], v[212:215], v[124:127]
	v_mfma_f32_16x16x32_bf16 v[120:123], v[164:167], v[212:215], v[120:123]
	v_mfma_f32_16x16x32_bf16 v[108:111], v[156:159], v[220:223], v[108:111]
	v_mfma_f32_16x16x32_bf16 v[104:107], v[164:167], v[220:223], v[104:107]
	v_mfma_f32_16x16x32_bf16 v[92:95], v[156:159], v[228:231], v[92:95]
	v_mfma_f32_16x16x32_bf16 v[88:91], v[164:167], v[228:231], v[88:91]
	v_mfma_f32_16x16x32_bf16 v[76:79], v[156:159], v[236:239], v[76:79]
	v_mfma_f32_16x16x32_bf16 v[72:75], v[164:167], v[236:239], v[72:75]
	s_setprio 0
	s_setprio 1
	v_mfma_f32_16x16x32_bf16 v[116:119], v[168:171], v[208:211], v[116:119]
	v_mfma_f32_16x16x32_bf16 v[112:115], v[176:179], v[208:211], v[112:115]
	v_mfma_f32_16x16x32_bf16 v[100:103], v[168:171], v[216:219], v[100:103]
	v_mfma_f32_16x16x32_bf16 v[96:99], v[176:179], v[216:219], v[96:99]
	v_mfma_f32_16x16x32_bf16 v[84:87], v[168:171], v[224:227], v[84:87]
	v_mfma_f32_16x16x32_bf16 v[80:83], v[176:179], v[224:227], v[80:83]
	v_mfma_f32_16x16x32_bf16 v[68:71], v[168:171], v[232:235], v[68:71]
	v_mfma_f32_16x16x32_bf16 v[64:67], v[176:179], v[232:235], v[64:67]
	v_mfma_f32_16x16x32_bf16 v[116:119], v[172:175], v[212:215], v[116:119]
	v_mfma_f32_16x16x32_bf16 v[112:115], v[204:207], v[212:215], v[112:115]
	v_mfma_f32_16x16x32_bf16 v[100:103], v[172:175], v[220:223], v[100:103]
	v_mfma_f32_16x16x32_bf16 v[96:99], v[204:207], v[220:223], v[96:99]
	v_mfma_f32_16x16x32_bf16 v[84:87], v[172:175], v[228:231], v[84:87]
	v_mfma_f32_16x16x32_bf16 v[80:83], v[204:207], v[228:231], v[80:83]
	v_mfma_f32_16x16x32_bf16 v[68:71], v[172:175], v[236:239], v[68:71]
	v_mfma_f32_16x16x32_bf16 v[64:67], v[204:207], v[236:239], v[64:67]
	s_setprio 0
	s_barrier
	s_add_i32 s4, s74, s28
	v_lshl_add_u64 v[180:181], v[180:181], 0, s[26:27]
	s_mov_b32 m0, s4
	ds_read_b128 v[208:211], v155 offset:49152
	ds_read_b128 v[212:215], v155 offset:50176
	ds_read_b128 v[216:219], v155 offset:51200
	ds_read_b128 v[220:223], v155 offset:52224
	ds_read_b128 v[224:227], v155 offset:53248
	ds_read_b128 v[228:231], v155 offset:54272
	ds_read_b128 v[232:235], v155 offset:55296
	ds_read_b128 v[236:239], v155 offset:56320
	global_load_lds_dwordx4 v[180:181], off
	s_add_i32 m0, s4, 0x2000
	s_add_u32 s4, s34, 0x20080
	v_lshl_add_u64 v[180:181], v[202:203], 0, s[26:27]
	s_addc_u32 s5, s35, 0
	s_add_i32 s34, s75, s28
	global_load_lds_dwordx4 v[180:181], off
	v_lshl_add_u64 v[180:181], s[4:5], 0, v[144:145]
	s_mov_b32 m0, s34
	s_nop 0
	global_load_lds_dwordx4 v[180:181], off
	v_lshl_add_u64 v[180:181], s[4:5], 0, v[132:133]
	s_add_i32 m0, s34, 0x2000
	s_nop 0
	global_load_lds_dwordx4 v[180:181], off
	v_lshl_add_u64 v[180:181], v[240:241], 0, s[26:27]
	s_mov_b32 m0, s68
	s_nop 0
	global_load_lds_dwordx4 v[180:181], off
	v_lshl_add_u64 v[180:181], v[242:243], 0, s[26:27]
	s_mov_b32 m0, s69
	s_nop 0
	global_load_lds_dwordx4 v[180:181], off
	s_waitcnt vmcnt(8)
	s_waitcnt lgkmcnt(0)
	s_barrier
	s_setprio 1
	s_waitcnt lgkmcnt(0)
	v_mfma_f32_16x16x32_bf16 v[60:63], v[138:141], v[208:211], v[60:63]
	v_mfma_f32_16x16x32_bf16 v[56:59], v[160:163], v[208:211], v[56:59]
	v_mfma_f32_16x16x32_bf16 v[44:47], v[138:141], v[216:219], v[44:47]
	v_mfma_f32_16x16x32_bf16 v[40:43], v[160:163], v[216:219], v[40:43]
	v_mfma_f32_16x16x32_bf16 v[28:31], v[138:141], v[224:227], v[28:31]
	v_mfma_f32_16x16x32_bf16 v[24:27], v[160:163], v[224:227], v[24:27]
	v_mfma_f32_16x16x32_bf16 v[12:15], v[138:141], v[232:235], v[12:15]
	v_mfma_f32_16x16x32_bf16 v[8:11], v[160:163], v[232:235], v[8:11]
	v_mfma_f32_16x16x32_bf16 v[60:63], v[156:159], v[212:215], v[60:63]
	v_mfma_f32_16x16x32_bf16 v[56:59], v[164:167], v[212:215], v[56:59]
	v_mfma_f32_16x16x32_bf16 v[44:47], v[156:159], v[220:223], v[44:47]
	v_mfma_f32_16x16x32_bf16 v[40:43], v[164:167], v[220:223], v[40:43]
	v_mfma_f32_16x16x32_bf16 v[28:31], v[156:159], v[228:231], v[28:31]
	v_mfma_f32_16x16x32_bf16 v[24:27], v[164:167], v[228:231], v[24:27]
	v_mfma_f32_16x16x32_bf16 v[12:15], v[156:159], v[236:239], v[12:15]
	v_mfma_f32_16x16x32_bf16 v[8:11], v[164:167], v[236:239], v[8:11]
	s_setprio 0
	s_setprio 1
	v_mfma_f32_16x16x32_bf16 v[52:55], v[168:171], v[208:211], v[52:55]
	v_mfma_f32_16x16x32_bf16 v[48:51], v[176:179], v[208:211], v[48:51]
	v_mfma_f32_16x16x32_bf16 v[36:39], v[168:171], v[216:219], v[36:39]
	v_mfma_f32_16x16x32_bf16 v[32:35], v[176:179], v[216:219], v[32:35]
	v_mfma_f32_16x16x32_bf16 v[20:23], v[168:171], v[224:227], v[20:23]
	v_mfma_f32_16x16x32_bf16 v[16:19], v[176:179], v[224:227], v[16:19]
	v_mfma_f32_16x16x32_bf16 v[4:7], v[168:171], v[232:235], v[4:7]
	v_mfma_f32_16x16x32_bf16 v[0:3], v[176:179], v[232:235], v[0:3]
	v_mfma_f32_16x16x32_bf16 v[52:55], v[172:175], v[212:215], v[52:55]
	v_mfma_f32_16x16x32_bf16 v[48:51], v[204:207], v[212:215], v[48:51]
	v_mfma_f32_16x16x32_bf16 v[36:39], v[172:175], v[220:223], v[36:39]
	v_mfma_f32_16x16x32_bf16 v[32:35], v[204:207], v[220:223], v[32:35]
	v_mfma_f32_16x16x32_bf16 v[20:23], v[172:175], v[228:231], v[20:23]
	v_mfma_f32_16x16x32_bf16 v[16:19], v[204:207], v[228:231], v[16:19]
	v_mfma_f32_16x16x32_bf16 v[4:7], v[172:175], v[236:239], v[4:7]
	v_mfma_f32_16x16x32_bf16 v[0:3], v[204:207], v[236:239], v[0:3]
	s_setprio 0
	s_barrier
	s_add_i32 s73, s73, 2
	s_add_u32 s58, s58, 0x100
	s_addc_u32 s59, s59, 0
	s_add_u32 s71, s71, 0x100
	s_addc_u32 s72, s72, 0
	s_cmp_gt_u32 s73, 5
	s_cbranch_scc0 .LBB0_1093
	s_and_b64 vcc, exec, s[46:47]
	s_cbranch_vccz .LBB0_1096
	s_barrier

.LBB0_1117:
	s_add_u32 s4, s54, 0xfffe0080
	s_addc_u32 s5, s55, -1
	s_add_i32 s74, 0, 0x10000
	s_cmp_eq_u32 s73, 4
	s_cselect_b32 s59, s33, s5
	s_cselect_b32 s58, s36, s4
	s_cselect_b32 s35, s47, s72
	s_cselect_b32 s34, s49, s71
	s_add_i32 s75, 0, 0x14000
	v_lshl_add_u64 v[180:181], s[54:55], 0, v[134:135]
	s_add_i32 m0, s64, 0xc000
	s_nop 0
	global_load_lds_dwordx4 v[180:181], off
	v_lshl_add_u64 v[180:181], s[54:55], 0, v[136:137]
	s_add_i32 m0, s64, 0xe000
	s_nop 0
	global_load_lds_dwordx4 v[180:181], off
	v_add_u32_e32 v164, s74, v143
	v_add_u32_e32 v204, s75, v143
	ds_read_b128 v[138:141], v164
	ds_read_b128 v[156:159], v164 offset:1024
	ds_read_b128 v[160:163], v164 offset:2048
	ds_read_b128 v[164:167], v164 offset:3072
	ds_read_b128 v[168:171], v204
	ds_read_b128 v[172:175], v204 offset:1024
	ds_read_b128 v[176:179], v204 offset:2048
	ds_read_b128 v[204:207], v204 offset:3072
	ds_read_b128 v[208:211], v155
	ds_read_b128 v[212:215], v155 offset:1024
	ds_read_b128 v[216:219], v155 offset:2048
	ds_read_b128 v[220:223], v155 offset:3072
	ds_read_b128 v[224:227], v155 offset:4096
	ds_read_b128 v[228:231], v155 offset:5120
	ds_read_b128 v[232:235], v155 offset:6144
	ds_read_b128 v[236:239], v155 offset:7168
	s_waitcnt vmcnt(8)
	s_waitcnt lgkmcnt(0)
	s_barrier
	s_setprio 1
	s_waitcnt lgkmcnt(0)
	v_mfma_f32_16x16x32_bf16 v[124:127], v[138:141], v[208:211], v[124:127]
	v_mfma_f32_16x16x32_bf16 v[120:123], v[160:163], v[208:211], v[120:123]
	v_mfma_f32_16x16x32_bf16 v[108:111], v[138:141], v[216:219], v[108:111]
	v_mfma_f32_16x16x32_bf16 v[104:107], v[160:163], v[216:219], v[104:107]
	v_mfma_f32_16x16x32_bf16 v[92:95], v[138:141], v[224:227], v[92:95]
	v_mfma_f32_16x16x32_bf16 v[88:91], v[160:163], v[224:227], v[88:91]
	v_mfma_f32_16x16x32_bf16 v[76:79], v[138:141], v[232:235], v[76:79]
	v_mfma_f32_16x16x32_bf16 v[72:75], v[160:163], v[232:235], v[72:75]
	v_mfma_f32_16x16x32_bf16 v[124:127], v[156:159], v[212:215], v[124:127]
	v_mfma_f32_16x16x32_bf16 v[120:123], v[164:167], v[212:215], v[120:123]
	v_mfma_f32_16x16x32_bf16 v[108:111], v[156:159], v[220:223], v[108:111]
	v_mfma_f32_16x16x32_bf16 v[104:107], v[164:167], v[220:223], v[104:107]
	v_mfma_f32_16x16x32_bf16 v[92:95], v[156:159], v[228:231], v[92:95]
	v_mfma_f32_16x16x32_bf16 v[88:91], v[164:167], v[228:231], v[88:91]
	v_mfma_f32_16x16x32_bf16 v[76:79], v[156:159], v[236:239], v[76:79]
	v_mfma_f32_16x16x32_bf16 v[72:75], v[164:167], v[236:239], v[72:75]
	s_setprio 0
	s_setprio 1
	v_mfma_f32_16x16x32_bf16 v[116:119], v[168:171], v[208:211], v[116:119]
	v_mfma_f32_16x16x32_bf16 v[112:115], v[176:179], v[208:211], v[112:115]
	v_mfma_f32_16x16x32_bf16 v[100:103], v[168:171], v[216:219], v[100:103]
	v_mfma_f32_16x16x32_bf16 v[96:99], v[176:179], v[216:219], v[96:99]
	v_mfma_f32_16x16x32_bf16 v[84:87], v[168:171], v[224:227], v[84:87]
	v_mfma_f32_16x16x32_bf16 v[80:83], v[176:179], v[224:227], v[80:83]
	v_mfma_f32_16x16x32_bf16 v[68:71], v[168:171], v[232:235], v[68:71]
	v_mfma_f32_16x16x32_bf16 v[64:67], v[176:179], v[232:235], v[64:67]
	v_mfma_f32_16x16x32_bf16 v[116:119], v[172:175], v[212:215], v[116:119]
	v_mfma_f32_16x16x32_bf16 v[112:115], v[204:207], v[212:215], v[112:115]
	v_mfma_f32_16x16x32_bf16 v[100:103], v[172:175], v[220:223], v[100:103]
	v_mfma_f32_16x16x32_bf16 v[96:99], v[204:207], v[220:223], v[96:99]
	v_mfma_f32_16x16x32_bf16 v[84:87], v[172:175], v[228:231], v[84:87]
	v_mfma_f32_16x16x32_bf16 v[80:83], v[204:207], v[228:231], v[80:83]
	v_mfma_f32_16x16x32_bf16 v[68:71], v[172:175], v[236:239], v[68:71]
	v_mfma_f32_16x16x32_bf16 v[64:67], v[204:207], v[236:239], v[64:67]
	s_setprio 0
	s_barrier
	s_add_i32 s4, s74, s63
	v_lshl_add_u64 v[180:181], s[34:35], 0, v[144:145]
	s_mov_b32 m0, s4
	ds_read_b128 v[208:211], v155 offset:16384
	ds_read_b128 v[212:215], v155 offset:17408
	ds_read_b128 v[216:219], v155 offset:18432
	ds_read_b128 v[220:223], v155 offset:19456
	ds_read_b128 v[224:227], v155 offset:20480
	ds_read_b128 v[228:231], v155 offset:21504
	ds_read_b128 v[232:235], v155 offset:22528
	ds_read_b128 v[236:239], v155 offset:23552
	global_load_lds_dwordx4 v[180:181], off
	s_add_i32 m0, s4, 0x2000
	s_add_u32 s4, s34, 0x20000
	v_lshl_add_u64 v[202:203], s[34:35], 0, v[132:133]
	s_addc_u32 s5, s35, 0
	s_add_i32 s74, s75, s63
	global_load_lds_dwordx4 v[202:203], off
	v_lshl_add_u64 v[240:241], s[4:5], 0, v[144:145]
	s_mov_b32 m0, s74
	v_lshl_add_u64 v[242:243], s[58:59], 0, v[130:131]
	global_load_lds_dwordx4 v[240:241], off
	v_lshl_add_u64 v[240:241], s[4:5], 0, v[132:133]
	s_add_i32 m0, s74, 0x2000
	s_nop 0
	global_load_lds_dwordx4 v[240:241], off
	v_lshl_add_u64 v[240:241], s[58:59], 0, v[128:129]
	s_mov_b32 m0, s64
	s_nop 0
	global_load_lds_dwordx4 v[240:241], off
	s_mov_b32 m0, s65
	s_nop 0
	global_load_lds_dwordx4 v[242:243], off
	s_waitcnt vmcnt(8)
	s_waitcnt lgkmcnt(0)
	s_barrier
	s_setprio 1
	s_waitcnt lgkmcnt(0)
	v_mfma_f32_16x16x32_bf16 v[60:63], v[138:141], v[208:211], v[60:63]
	v_mfma_f32_16x16x32_bf16 v[56:59], v[160:163], v[208:211], v[56:59]
	v_mfma_f32_16x16x32_bf16 v[44:47], v[138:141], v[216:219], v[44:47]
	v_mfma_f32_16x16x32_bf16 v[40:43], v[160:163], v[216:219], v[40:43]
	v_mfma_f32_16x16x32_bf16 v[28:31], v[138:141], v[224:227], v[28:31]
	v_mfma_f32_16x16x32_bf16 v[24:27], v[160:163], v[224:227], v[24:27]
	v_mfma_f32_16x16x32_bf16 v[12:15], v[138:141], v[232:235], v[12:15]
	v_mfma_f32_16x16x32_bf16 v[8:11], v[160:163], v[232:235], v[8:11]
	v_mfma_f32_16x16x32_bf16 v[60:63], v[156:159], v[212:215], v[60:63]
	v_mfma_f32_16x16x32_bf16 v[56:59], v[164:167], v[212:215], v[56:59]
	v_mfma_f32_16x16x32_bf16 v[44:47], v[156:159], v[220:223], v[44:47]
	v_mfma_f32_16x16x32_bf16 v[40:43], v[164:167], v[220:223], v[40:43]
	v_mfma_f32_16x16x32_bf16 v[28:31], v[156:159], v[228:231], v[28:31]
	v_mfma_f32_16x16x32_bf16 v[24:27], v[164:167], v[228:231], v[24:27]
	v_mfma_f32_16x16x32_bf16 v[12:15], v[156:159], v[236:239], v[12:15]
	v_mfma_f32_16x16x32_bf16 v[8:11], v[164:167], v[236:239], v[8:11]
	s_setprio 0
	s_setprio 1
	v_mfma_f32_16x16x32_bf16 v[52:55], v[168:171], v[208:211], v[52:55]
	v_mfma_f32_16x16x32_bf16 v[48:51], v[176:179], v[208:211], v[48:51]
	v_mfma_f32_16x16x32_bf16 v[36:39], v[168:171], v[216:219], v[36:39]
	v_mfma_f32_16x16x32_bf16 v[32:35], v[176:179], v[216:219], v[32:35]
	v_mfma_f32_16x16x32_bf16 v[20:23], v[168:171], v[224:227], v[20:23]
	v_mfma_f32_16x16x32_bf16 v[16:19], v[176:179], v[224:227], v[16:19]
	v_mfma_f32_16x16x32_bf16 v[4:7], v[168:171], v[232:235], v[4:7]
	v_mfma_f32_16x16x32_bf16 v[0:3], v[176:179], v[232:235], v[0:3]
	v_mfma_f32_16x16x32_bf16 v[52:55], v[172:175], v[212:215], v[52:55]
	v_mfma_f32_16x16x32_bf16 v[48:51], v[204:207], v[212:215], v[48:51]
	v_mfma_f32_16x16x32_bf16 v[36:39], v[172:175], v[220:223], v[36:39]
	v_mfma_f32_16x16x32_bf16 v[32:35], v[204:207], v[220:223], v[32:35]
	v_mfma_f32_16x16x32_bf16 v[20:23], v[172:175], v[228:231], v[20:23]
	v_mfma_f32_16x16x32_bf16 v[16:19], v[204:207], v[228:231], v[16:19]
	v_mfma_f32_16x16x32_bf16 v[4:7], v[172:175], v[236:239], v[4:7]
	v_mfma_f32_16x16x32_bf16 v[0:3], v[204:207], v[236:239], v[0:3]
	s_setprio 0
	s_barrier
	s_add_i32 s74, 0, 0x18000
	s_add_i32 s75, 0, 0x1c000
	s_add_u32 s4, s58, 0x20000
	s_addc_u32 s5, s59, 0
	s_mov_b32 m0, s66
	v_lshl_add_u64 v[244:245], s[4:5], 0, v[128:129]
	global_load_lds_dwordx4 v[244:245], off
	v_lshl_add_u64 v[244:245], s[4:5], 0, v[130:131]
	s_mov_b32 m0, s67
	s_nop 0
	global_load_lds_dwordx4 v[244:245], off
	v_add_u32_e32 v164, s74, v143
	v_add_u32_e32 v204, s75, v143
	ds_read_b128 v[138:141], v164
	ds_read_b128 v[156:159], v164 offset:1024
	ds_read_b128 v[160:163], v164 offset:2048
	ds_read_b128 v[164:167], v164 offset:3072
	ds_read_b128 v[168:171], v204
	ds_read_b128 v[172:175], v204 offset:1024
	ds_read_b128 v[176:179], v204 offset:2048
	ds_read_b128 v[204:207], v204 offset:3072
	ds_read_b128 v[208:211], v155 offset:32768
	ds_read_b128 v[212:215], v155 offset:33792
	ds_read_b128 v[216:219], v155 offset:34816
	ds_read_b128 v[220:223], v155 offset:35840
	ds_read_b128 v[224:227], v155 offset:36864
	ds_read_b128 v[228:231], v155 offset:37888
	ds_read_b128 v[232:235], v155 offset:38912
	ds_read_b128 v[236:239], v155 offset:39936
	s_waitcnt vmcnt(8)
	s_waitcnt lgkmcnt(0)
	s_barrier
	s_setprio 1
	s_waitcnt lgkmcnt(0)
	v_mfma_f32_16x16x32_bf16 v[124:127], v[138:141], v[208:211], v[124:127]
	v_mfma_f32_16x16x32_bf16 v[120:123], v[160:163], v[208:211], v[120:123]
	v_mfma_f32_16x16x32_bf16 v[108:111], v[138:141], v[216:219], v[108:111]
	v_mfma_f32_16x16x32_bf16 v[104:107], v[160:163], v[216:219], v[104:107]
	v_mfma_f32_16x16x32_bf16 v[92:95], v[138:141], v[224:227], v[92:95]
	v_mfma_f32_16x16x32_bf16 v[88:91], v[160:163], v[224:227], v[88:91]
	v_mfma_f32_16x16x32_bf16 v[76:79], v[138:141], v[232:235], v[76:79]
	v_mfma_f32_16x16x32_bf16 v[72:75], v[160:163], v[232:235], v[72:75]
	v_mfma_f32_16x16x32_bf16 v[124:127], v[156:159], v[212:215], v[124:127]
	v_mfma_f32_16x16x32_bf16 v[120:123], v[164:167], v[212:215], v[120:123]
	v_mfma_f32_16x16x32_bf16 v[108:111], v[156:159], v[220:223], v[108:111]
	v_mfma_f32_16x16x32_bf16 v[104:107], v[164:167], v[220:223], v[104:107]
	v_mfma_f32_16x16x32_bf16 v[92:95], v[156:159], v[228:231], v[92:95]
	v_mfma_f32_16x16x32_bf16 v[88:91], v[164:167], v[228:231], v[88:91]
	v_mfma_f32_16x16x32_bf16 v[76:79], v[156:159], v[236:239], v[76:79]
	v_mfma_f32_16x16x32_bf16 v[72:75], v[164:167], v[236:239], v[72:75]
	s_setprio 0
	s_setprio 1
	v_mfma_f32_16x16x32_bf16 v[116:119], v[168:171], v[208:211], v[116:119]
	v_mfma_f32_16x16x32_bf16 v[112:115], v[176:179], v[208:211], v[112:115]
	v_mfma_f32_16x16x32_bf16 v[100:103], v[168:171], v[216:219], v[100:103]
	v_mfma_f32_16x16x32_bf16 v[96:99], v[176:179], v[216:219], v[96:99]
	v_mfma_f32_16x16x32_bf16 v[84:87], v[168:171], v[224:227], v[84:87]
	v_mfma_f32_16x16x32_bf16 v[80:83], v[176:179], v[224:227], v[80:83]
	v_mfma_f32_16x16x32_bf16 v[68:71], v[168:171], v[232:235], v[68:71]
	v_mfma_f32_16x16x32_bf16 v[64:67], v[176:179], v[232:235], v[64:67]
	v_mfma_f32_16x16x32_bf16 v[116:119], v[172:175], v[212:215], v[116:119]
	v_mfma_f32_16x16x32_bf16 v[112:115], v[204:207], v[212:215], v[112:115]
	v_mfma_f32_16x16x32_bf16 v[100:103], v[172:175], v[220:223], v[100:103]
	v_mfma_f32_16x16x32_bf16 v[96:99], v[204:207], v[220:223], v[96:99]
	v_mfma_f32_16x16x32_bf16 v[84:87], v[172:175], v[228:231], v[84:87]
	v_mfma_f32_16x16x32_bf16 v[80:83], v[204:207], v[228:231], v[80:83]
	v_mfma_f32_16x16x32_bf16 v[68:71], v[172:175], v[236:239], v[68:71]
	v_mfma_f32_16x16x32_bf16 v[64:67], v[204:207], v[236:239], v[64:67]
	s_setprio 0
	s_barrier
	s_add_i32 s4, s74, s63
	v_lshl_add_u64 v[180:181], v[180:181], 0, s[26:27]
	s_mov_b32 m0, s4
	ds_read_b128 v[208:211], v155 offset:49152
	ds_read_b128 v[212:215], v155 offset:50176
	ds_read_b128 v[216:219], v155 offset:51200
	ds_read_b128 v[220:223], v155 offset:52224
	ds_read_b128 v[224:227], v155 offset:53248
	ds_read_b128 v[228:231], v155 offset:54272
	ds_read_b128 v[232:235], v155 offset:55296
	ds_read_b128 v[236:239], v155 offset:56320
	global_load_lds_dwordx4 v[180:181], off
	s_add_i32 m0, s4, 0x2000
	s_add_u32 s4, s34, 0x20080
	v_lshl_add_u64 v[180:181], v[202:203], 0, s[26:27]
	s_addc_u32 s5, s35, 0
	s_add_i32 s34, s75, s63
	global_load_lds_dwordx4 v[180:181], off
	v_lshl_add_u64 v[180:181], s[4:5], 0, v[144:145]
	s_mov_b32 m0, s34
	s_nop 0
	global_load_lds_dwordx4 v[180:181], off
	v_lshl_add_u64 v[180:181], s[4:5], 0, v[132:133]
	s_add_i32 m0, s34, 0x2000
	s_nop 0
	global_load_lds_dwordx4 v[180:181], off
	v_lshl_add_u64 v[180:181], v[240:241], 0, s[26:27]
	s_mov_b32 m0, s68
	s_nop 0
	global_load_lds_dwordx4 v[180:181], off
	v_lshl_add_u64 v[180:181], v[242:243], 0, s[26:27]
	s_mov_b32 m0, s69
	s_nop 0
	global_load_lds_dwordx4 v[180:181], off
	s_waitcnt vmcnt(8)
	s_waitcnt lgkmcnt(0)
	s_barrier
	s_setprio 1
	s_waitcnt lgkmcnt(0)
	v_mfma_f32_16x16x32_bf16 v[60:63], v[138:141], v[208:211], v[60:63]
	v_mfma_f32_16x16x32_bf16 v[56:59], v[160:163], v[208:211], v[56:59]
	v_mfma_f32_16x16x32_bf16 v[44:47], v[138:141], v[216:219], v[44:47]
	v_mfma_f32_16x16x32_bf16 v[40:43], v[160:163], v[216:219], v[40:43]
	v_mfma_f32_16x16x32_bf16 v[28:31], v[138:141], v[224:227], v[28:31]
	v_mfma_f32_16x16x32_bf16 v[24:27], v[160:163], v[224:227], v[24:27]
	v_mfma_f32_16x16x32_bf16 v[12:15], v[138:141], v[232:235], v[12:15]
	v_mfma_f32_16x16x32_bf16 v[8:11], v[160:163], v[232:235], v[8:11]
	v_mfma_f32_16x16x32_bf16 v[60:63], v[156:159], v[212:215], v[60:63]
	v_mfma_f32_16x16x32_bf16 v[56:59], v[164:167], v[212:215], v[56:59]
	v_mfma_f32_16x16x32_bf16 v[44:47], v[156:159], v[220:223], v[44:47]
	v_mfma_f32_16x16x32_bf16 v[40:43], v[164:167], v[220:223], v[40:43]
	v_mfma_f32_16x16x32_bf16 v[28:31], v[156:159], v[228:231], v[28:31]
	v_mfma_f32_16x16x32_bf16 v[24:27], v[164:167], v[228:231], v[24:27]
	v_mfma_f32_16x16x32_bf16 v[12:15], v[156:159], v[236:239], v[12:15]
	v_mfma_f32_16x16x32_bf16 v[8:11], v[164:167], v[236:239], v[8:11]
	s_setprio 0
	s_setprio 1
	v_mfma_f32_16x16x32_bf16 v[52:55], v[168:171], v[208:211], v[52:55]
	v_mfma_f32_16x16x32_bf16 v[48:51], v[176:179], v[208:211], v[48:51]
	v_mfma_f32_16x16x32_bf16 v[36:39], v[168:171], v[216:219], v[36:39]
	v_mfma_f32_16x16x32_bf16 v[32:35], v[176:179], v[216:219], v[32:35]
	v_mfma_f32_16x16x32_bf16 v[20:23], v[168:171], v[224:227], v[20:23]
	v_mfma_f32_16x16x32_bf16 v[16:19], v[176:179], v[224:227], v[16:19]
	v_mfma_f32_16x16x32_bf16 v[4:7], v[168:171], v[232:235], v[4:7]
	v_mfma_f32_16x16x32_bf16 v[0:3], v[176:179], v[232:235], v[0:3]
	v_mfma_f32_16x16x32_bf16 v[52:55], v[172:175], v[212:215], v[52:55]
	v_mfma_f32_16x16x32_bf16 v[48:51], v[204:207], v[212:215], v[48:51]
	v_mfma_f32_16x16x32_bf16 v[36:39], v[172:175], v[220:223], v[36:39]
	v_mfma_f32_16x16x32_bf16 v[32:35], v[204:207], v[220:223], v[32:35]
	v_mfma_f32_16x16x32_bf16 v[20:23], v[172:175], v[228:231], v[20:23]
	v_mfma_f32_16x16x32_bf16 v[16:19], v[204:207], v[228:231], v[16:19]
	v_mfma_f32_16x16x32_bf16 v[4:7], v[172:175], v[236:239], v[4:7]
	v_mfma_f32_16x16x32_bf16 v[0:3], v[204:207], v[236:239], v[0:3]
	s_setprio 0
	s_barrier
	s_add_i32 s73, s73, 2
	s_add_u32 s54, s54, 0x100
	s_addc_u32 s55, s55, 0
	s_add_u32 s71, s71, 0x100
	s_addc_u32 s72, s72, 0
	s_cmp_gt_u32 s73, 5
	s_cbranch_scc0 .LBB0_1117
	s_and_b64 vcc, exec, s[44:45]
	s_cbranch_vccz .LBB0_1120
	s_barrier

.LBB0_1207:
	s_add_u32 s62, s60, 0x100
	s_addc_u32 s63, s61, 0
	s_add_i32 s4, 0, 0x10000
	s_cmp_eq_u32 s29, 12
	s_cselect_b32 s65, s55, s63
	s_cselect_b32 s64, s54, s62
	s_cselect_b32 s35, s59, s28
	s_cselect_b32 s34, s58, s3
	s_add_i32 s45, 0, 0x14000
	v_lshl_add_u64 v[142:143], s[60:61], 0, v[134:135]
	s_add_i32 m0, s69, 0xc000
	s_nop 0
	global_load_lds_dwordx4 v[142:143], off
	v_lshl_add_u64 v[142:143], s[60:61], 0, v[136:137]
	s_add_i32 m0, s69, 0xe000
	s_nop 0
	global_load_lds_dwordx4 v[142:143], off
	v_add_u32_e32 v176, s4, v160
	ds_read_b128 v[138:141], v176
	ds_read_b128 v[154:157], v176 offset:1024
	ds_read_b128 v[172:175], v176 offset:2048
	ds_read_b128 v[176:179], v176 offset:3072
	v_add_u32_e32 v216, s45, v160
	ds_read_b128 v[204:207], v216
	ds_read_b128 v[208:211], v216 offset:1024
	ds_read_b128 v[212:215], v216 offset:2048
	ds_read_b128 v[216:219], v216 offset:3072
	ds_read_b128 v[220:223], v170
	ds_read_b128 v[224:227], v170 offset:1024
	ds_read_b128 v[228:231], v170 offset:2048
	ds_read_b128 v[232:235], v170 offset:3072
	ds_read_b128 v[236:239], v170 offset:4096
	ds_read_b128 v[240:243], v170 offset:5120
	ds_read_b128 v[244:247], v170 offset:6144
	ds_read_b128 v[248:251], v170 offset:7168
	s_waitcnt vmcnt(8)
	s_waitcnt lgkmcnt(0)
	s_barrier
	s_setprio 1
	s_waitcnt lgkmcnt(0)
	v_mfma_f32_16x16x32_bf16 v[124:127], v[138:141], v[220:223], v[124:127]
	v_mfma_f32_16x16x32_bf16 v[120:123], v[172:175], v[220:223], v[120:123]
	v_mfma_f32_16x16x32_bf16 v[108:111], v[138:141], v[228:231], v[108:111]
	v_mfma_f32_16x16x32_bf16 v[104:107], v[172:175], v[228:231], v[104:107]
	v_mfma_f32_16x16x32_bf16 v[92:95], v[138:141], v[236:239], v[92:95]
	v_mfma_f32_16x16x32_bf16 v[88:91], v[172:175], v[236:239], v[88:91]
	v_mfma_f32_16x16x32_bf16 v[76:79], v[138:141], v[244:247], v[76:79]
	v_mfma_f32_16x16x32_bf16 v[72:75], v[172:175], v[244:247], v[72:75]
	v_mfma_f32_16x16x32_bf16 v[124:127], v[154:157], v[224:227], v[124:127]
	v_mfma_f32_16x16x32_bf16 v[120:123], v[176:179], v[224:227], v[120:123]
	v_mfma_f32_16x16x32_bf16 v[108:111], v[154:157], v[232:235], v[108:111]
	v_mfma_f32_16x16x32_bf16 v[104:107], v[176:179], v[232:235], v[104:107]
	v_mfma_f32_16x16x32_bf16 v[92:95], v[154:157], v[240:243], v[92:95]
	v_mfma_f32_16x16x32_bf16 v[88:91], v[176:179], v[240:243], v[88:91]
	v_mfma_f32_16x16x32_bf16 v[76:79], v[154:157], v[248:251], v[76:79]
	v_mfma_f32_16x16x32_bf16 v[72:75], v[176:179], v[248:251], v[72:75]
	s_setprio 0
	s_setprio 1
	v_mfma_f32_16x16x32_bf16 v[116:119], v[204:207], v[220:223], v[116:119]
	v_mfma_f32_16x16x32_bf16 v[112:115], v[212:215], v[220:223], v[112:115]
	v_mfma_f32_16x16x32_bf16 v[100:103], v[204:207], v[228:231], v[100:103]
	v_mfma_f32_16x16x32_bf16 v[96:99], v[212:215], v[228:231], v[96:99]
	v_mfma_f32_16x16x32_bf16 v[84:87], v[204:207], v[236:239], v[84:87]
	v_mfma_f32_16x16x32_bf16 v[80:83], v[212:215], v[236:239], v[80:83]
	v_mfma_f32_16x16x32_bf16 v[68:71], v[204:207], v[244:247], v[68:71]
	v_mfma_f32_16x16x32_bf16 v[64:67], v[212:215], v[244:247], v[64:67]
	v_mfma_f32_16x16x32_bf16 v[116:119], v[208:211], v[224:227], v[116:119]
	v_mfma_f32_16x16x32_bf16 v[112:115], v[216:219], v[224:227], v[112:115]
	v_mfma_f32_16x16x32_bf16 v[100:103], v[208:211], v[232:235], v[100:103]
	v_mfma_f32_16x16x32_bf16 v[96:99], v[216:219], v[232:235], v[96:99]
	v_mfma_f32_16x16x32_bf16 v[84:87], v[208:211], v[240:243], v[84:87]
	v_mfma_f32_16x16x32_bf16 v[80:83], v[216:219], v[240:243], v[80:83]
	v_mfma_f32_16x16x32_bf16 v[68:71], v[208:211], v[248:251], v[68:71]
	v_mfma_f32_16x16x32_bf16 v[64:67], v[216:219], v[248:251], v[64:67]
	s_setprio 0
	s_barrier
	s_add_i32 s4, s4, s33
	v_lshl_add_u64 v[142:143], s[34:35], 0, v[128:129]
	s_mov_b32 m0, s4
	ds_read_b128 v[220:223], v170 offset:16384
	ds_read_b128 v[224:227], v170 offset:17408
	ds_read_b128 v[228:231], v170 offset:18432
	ds_read_b128 v[232:235], v170 offset:19456
	ds_read_b128 v[236:239], v170 offset:20480
	ds_read_b128 v[240:243], v170 offset:21504
	ds_read_b128 v[244:247], v170 offset:22528
	ds_read_b128 v[248:251], v170 offset:23552
	global_load_lds_dwordx4 v[142:143], off
	s_add_i32 m0, s4, 0x2000
	s_add_u32 s4, s34, 0x40000
	v_lshl_add_u64 v[158:159], s[34:35], 0, v[130:131]
	s_addc_u32 s5, s35, 0
	s_add_i32 s45, s45, s33
	global_load_lds_dwordx4 v[158:159], off
	v_lshl_add_u64 v[180:181], s[4:5], 0, v[128:129]
	s_mov_b32 m0, s45
	v_lshl_add_u64 v[202:203], s[64:65], 0, v[130:131]
	global_load_lds_dwordx4 v[180:181], off
	v_lshl_add_u64 v[180:181], s[4:5], 0, v[130:131]
	s_add_i32 m0, s45, 0x2000
	s_nop 0
	global_load_lds_dwordx4 v[180:181], off
	v_lshl_add_u64 v[180:181], s[64:65], 0, v[128:129]
	s_mov_b32 m0, s69
	s_nop 0
	global_load_lds_dwordx4 v[180:181], off
	s_mov_b32 m0, s70
	s_nop 0
	global_load_lds_dwordx4 v[202:203], off
	s_waitcnt vmcnt(8)
	s_waitcnt lgkmcnt(0)
	s_barrier
	s_setprio 1
	s_waitcnt lgkmcnt(0)
	v_mfma_f32_16x16x32_bf16 v[60:63], v[138:141], v[220:223], v[60:63]
	v_mfma_f32_16x16x32_bf16 v[56:59], v[172:175], v[220:223], v[56:59]
	v_mfma_f32_16x16x32_bf16 v[44:47], v[138:141], v[228:231], v[44:47]
	v_mfma_f32_16x16x32_bf16 v[40:43], v[172:175], v[228:231], v[40:43]
	v_mfma_f32_16x16x32_bf16 v[28:31], v[138:141], v[236:239], v[28:31]
	v_mfma_f32_16x16x32_bf16 v[24:27], v[172:175], v[236:239], v[24:27]
	v_mfma_f32_16x16x32_bf16 v[12:15], v[138:141], v[244:247], v[12:15]
	v_mfma_f32_16x16x32_bf16 v[8:11], v[172:175], v[244:247], v[8:11]
	v_mfma_f32_16x16x32_bf16 v[60:63], v[154:157], v[224:227], v[60:63]
	v_mfma_f32_16x16x32_bf16 v[56:59], v[176:179], v[224:227], v[56:59]
	v_mfma_f32_16x16x32_bf16 v[44:47], v[154:157], v[232:235], v[44:47]
	v_mfma_f32_16x16x32_bf16 v[40:43], v[176:179], v[232:235], v[40:43]
	v_mfma_f32_16x16x32_bf16 v[28:31], v[154:157], v[240:243], v[28:31]
	v_mfma_f32_16x16x32_bf16 v[24:27], v[176:179], v[240:243], v[24:27]
	v_mfma_f32_16x16x32_bf16 v[12:15], v[154:157], v[248:251], v[12:15]
	v_mfma_f32_16x16x32_bf16 v[8:11], v[176:179], v[248:251], v[8:11]
	s_setprio 0
	s_setprio 1
	v_mfma_f32_16x16x32_bf16 v[52:55], v[204:207], v[220:223], v[52:55]
	v_mfma_f32_16x16x32_bf16 v[48:51], v[212:215], v[220:223], v[48:51]
	v_mfma_f32_16x16x32_bf16 v[36:39], v[204:207], v[228:231], v[36:39]
	v_mfma_f32_16x16x32_bf16 v[32:35], v[212:215], v[228:231], v[32:35]
	v_mfma_f32_16x16x32_bf16 v[20:23], v[204:207], v[236:239], v[20:23]
	v_mfma_f32_16x16x32_bf16 v[16:19], v[212:215], v[236:239], v[16:19]
	v_mfma_f32_16x16x32_bf16 v[4:7], v[204:207], v[244:247], v[4:7]
	v_mfma_f32_16x16x32_bf16 v[0:3], v[212:215], v[244:247], v[0:3]
	v_mfma_f32_16x16x32_bf16 v[52:55], v[208:211], v[224:227], v[52:55]
	v_mfma_f32_16x16x32_bf16 v[48:51], v[216:219], v[224:227], v[48:51]
	v_mfma_f32_16x16x32_bf16 v[36:39], v[208:211], v[232:235], v[36:39]
	v_mfma_f32_16x16x32_bf16 v[32:35], v[216:219], v[232:235], v[32:35]
	v_mfma_f32_16x16x32_bf16 v[20:23], v[208:211], v[240:243], v[20:23]
	v_mfma_f32_16x16x32_bf16 v[16:19], v[216:219], v[240:243], v[16:19]
	v_mfma_f32_16x16x32_bf16 v[4:7], v[208:211], v[248:251], v[4:7]
	v_mfma_f32_16x16x32_bf16 v[0:3], v[216:219], v[248:251], v[0:3]
	s_setprio 0
	s_barrier
	s_add_i32 s45, 0, 0x18000
	s_add_i32 s51, 0, 0x1c000
	s_add_u32 s4, s64, 0x40000
	s_addc_u32 s5, s65, 0
	s_mov_b32 m0, s71
	v_lshl_add_u64 v[252:253], s[4:5], 0, v[128:129]
	global_load_lds_dwordx4 v[252:253], off
	v_lshl_add_u64 v[252:253], s[4:5], 0, v[130:131]
	s_mov_b32 m0, s72
	s_nop 0
	global_load_lds_dwordx4 v[252:253], off
	v_add_u32_e32 v176, s45, v160
	ds_read_b128 v[138:141], v176
	ds_read_b128 v[154:157], v176 offset:1024
	ds_read_b128 v[172:175], v176 offset:2048
	ds_read_b128 v[176:179], v176 offset:3072
	v_add_u32_e32 v216, s51, v160
	ds_read_b128 v[204:207], v216
	ds_read_b128 v[208:211], v216 offset:1024
	ds_read_b128 v[212:215], v216 offset:2048
	ds_read_b128 v[216:219], v216 offset:3072
	ds_read_b128 v[220:223], v170 offset:32768
	ds_read_b128 v[224:227], v170 offset:33792
	ds_read_b128 v[228:231], v170 offset:34816
	ds_read_b128 v[232:235], v170 offset:35840
	ds_read_b128 v[236:239], v170 offset:36864
	ds_read_b128 v[240:243], v170 offset:37888
	ds_read_b128 v[244:247], v170 offset:38912
	ds_read_b128 v[248:251], v170 offset:39936
	s_waitcnt vmcnt(8)
	s_waitcnt lgkmcnt(0)
	s_barrier
	s_setprio 1
	s_waitcnt lgkmcnt(0)
	v_mfma_f32_16x16x32_bf16 v[124:127], v[138:141], v[220:223], v[124:127]
	v_mfma_f32_16x16x32_bf16 v[120:123], v[172:175], v[220:223], v[120:123]
	v_mfma_f32_16x16x32_bf16 v[108:111], v[138:141], v[228:231], v[108:111]
	v_mfma_f32_16x16x32_bf16 v[104:107], v[172:175], v[228:231], v[104:107]
	v_mfma_f32_16x16x32_bf16 v[92:95], v[138:141], v[236:239], v[92:95]
	v_mfma_f32_16x16x32_bf16 v[88:91], v[172:175], v[236:239], v[88:91]
	v_mfma_f32_16x16x32_bf16 v[76:79], v[138:141], v[244:247], v[76:79]
	v_mfma_f32_16x16x32_bf16 v[72:75], v[172:175], v[244:247], v[72:75]
	v_mfma_f32_16x16x32_bf16 v[124:127], v[154:157], v[224:227], v[124:127]
	v_mfma_f32_16x16x32_bf16 v[120:123], v[176:179], v[224:227], v[120:123]
	v_mfma_f32_16x16x32_bf16 v[108:111], v[154:157], v[232:235], v[108:111]
	v_mfma_f32_16x16x32_bf16 v[104:107], v[176:179], v[232:235], v[104:107]
	v_mfma_f32_16x16x32_bf16 v[92:95], v[154:157], v[240:243], v[92:95]
	v_mfma_f32_16x16x32_bf16 v[88:91], v[176:179], v[240:243], v[88:91]
	v_mfma_f32_16x16x32_bf16 v[76:79], v[154:157], v[248:251], v[76:79]
	v_mfma_f32_16x16x32_bf16 v[72:75], v[176:179], v[248:251], v[72:75]
	s_setprio 0
	s_setprio 1
	v_mfma_f32_16x16x32_bf16 v[116:119], v[204:207], v[220:223], v[116:119]
	v_mfma_f32_16x16x32_bf16 v[112:115], v[212:215], v[220:223], v[112:115]
	v_mfma_f32_16x16x32_bf16 v[100:103], v[204:207], v[228:231], v[100:103]
	v_mfma_f32_16x16x32_bf16 v[96:99], v[212:215], v[228:231], v[96:99]
	v_mfma_f32_16x16x32_bf16 v[84:87], v[204:207], v[236:239], v[84:87]
	v_mfma_f32_16x16x32_bf16 v[80:83], v[212:215], v[236:239], v[80:83]
	v_mfma_f32_16x16x32_bf16 v[68:71], v[204:207], v[244:247], v[68:71]
	v_mfma_f32_16x16x32_bf16 v[64:67], v[212:215], v[244:247], v[64:67]
	v_mfma_f32_16x16x32_bf16 v[116:119], v[208:211], v[224:227], v[116:119]
	v_mfma_f32_16x16x32_bf16 v[112:115], v[216:219], v[224:227], v[112:115]
	v_mfma_f32_16x16x32_bf16 v[100:103], v[208:211], v[232:235], v[100:103]
	v_mfma_f32_16x16x32_bf16 v[96:99], v[216:219], v[232:235], v[96:99]
	v_mfma_f32_16x16x32_bf16 v[84:87], v[208:211], v[240:243], v[84:87]
	v_mfma_f32_16x16x32_bf16 v[80:83], v[216:219], v[240:243], v[80:83]
	v_mfma_f32_16x16x32_bf16 v[68:71], v[208:211], v[248:251], v[68:71]
	v_mfma_f32_16x16x32_bf16 v[64:67], v[216:219], v[248:251], v[64:67]
	s_setprio 0
	s_barrier
	s_add_i32 s4, s45, s33
	v_lshl_add_u64 v[142:143], v[142:143], 0, s[26:27]
	s_mov_b32 m0, s4
	ds_read_b128 v[220:223], v170 offset:49152
	ds_read_b128 v[224:227], v170 offset:50176
	ds_read_b128 v[228:231], v170 offset:51200
	ds_read_b128 v[232:235], v170 offset:52224
	ds_read_b128 v[236:239], v170 offset:53248
	ds_read_b128 v[240:243], v170 offset:54272
	ds_read_b128 v[244:247], v170 offset:55296
	ds_read_b128 v[248:251], v170 offset:56320
	global_load_lds_dwordx4 v[142:143], off
	s_add_i32 m0, s4, 0x2000
	s_add_u32 s4, s34, 0x40080
	v_lshl_add_u64 v[142:143], v[158:159], 0, s[26:27]
	s_addc_u32 s5, s35, 0
	s_add_i32 s34, s51, s33
	global_load_lds_dwordx4 v[142:143], off
	v_lshl_add_u64 v[142:143], s[4:5], 0, v[128:129]
	s_mov_b32 m0, s34
	s_nop 0
	global_load_lds_dwordx4 v[142:143], off
	v_lshl_add_u64 v[142:143], s[4:5], 0, v[130:131]
	s_add_i32 m0, s34, 0x2000
	s_nop 0
	global_load_lds_dwordx4 v[142:143], off
	v_lshl_add_u64 v[142:143], v[180:181], 0, s[26:27]
	s_mov_b32 m0, s73
	s_nop 0
	global_load_lds_dwordx4 v[142:143], off
	v_lshl_add_u64 v[142:143], v[202:203], 0, s[26:27]
	s_mov_b32 m0, s74
	s_nop 0
	global_load_lds_dwordx4 v[142:143], off
	s_waitcnt vmcnt(8)
	s_waitcnt lgkmcnt(0)
	s_barrier
	s_setprio 1
	s_waitcnt lgkmcnt(0)
	v_mfma_f32_16x16x32_bf16 v[60:63], v[138:141], v[220:223], v[60:63]
	v_mfma_f32_16x16x32_bf16 v[56:59], v[172:175], v[220:223], v[56:59]
	v_mfma_f32_16x16x32_bf16 v[44:47], v[138:141], v[228:231], v[44:47]
	v_mfma_f32_16x16x32_bf16 v[40:43], v[172:175], v[228:231], v[40:43]
	v_mfma_f32_16x16x32_bf16 v[28:31], v[138:141], v[236:239], v[28:31]
	v_mfma_f32_16x16x32_bf16 v[24:27], v[172:175], v[236:239], v[24:27]
	v_mfma_f32_16x16x32_bf16 v[12:15], v[138:141], v[244:247], v[12:15]
	v_mfma_f32_16x16x32_bf16 v[8:11], v[172:175], v[244:247], v[8:11]
	v_mfma_f32_16x16x32_bf16 v[60:63], v[154:157], v[224:227], v[60:63]
	v_mfma_f32_16x16x32_bf16 v[56:59], v[176:179], v[224:227], v[56:59]
	v_mfma_f32_16x16x32_bf16 v[44:47], v[154:157], v[232:235], v[44:47]
	v_mfma_f32_16x16x32_bf16 v[40:43], v[176:179], v[232:235], v[40:43]
	v_mfma_f32_16x16x32_bf16 v[28:31], v[154:157], v[240:243], v[28:31]
	v_mfma_f32_16x16x32_bf16 v[24:27], v[176:179], v[240:243], v[24:27]
	v_mfma_f32_16x16x32_bf16 v[12:15], v[154:157], v[248:251], v[12:15]
	v_mfma_f32_16x16x32_bf16 v[8:11], v[176:179], v[248:251], v[8:11]
	s_setprio 0
	s_setprio 1
	v_mfma_f32_16x16x32_bf16 v[52:55], v[204:207], v[220:223], v[52:55]
	v_mfma_f32_16x16x32_bf16 v[48:51], v[212:215], v[220:223], v[48:51]
	v_mfma_f32_16x16x32_bf16 v[36:39], v[204:207], v[228:231], v[36:39]
	v_mfma_f32_16x16x32_bf16 v[32:35], v[212:215], v[228:231], v[32:35]
	v_mfma_f32_16x16x32_bf16 v[20:23], v[204:207], v[236:239], v[20:23]
	v_mfma_f32_16x16x32_bf16 v[16:19], v[212:215], v[236:239], v[16:19]
	v_mfma_f32_16x16x32_bf16 v[4:7], v[204:207], v[244:247], v[4:7]
	v_mfma_f32_16x16x32_bf16 v[0:3], v[212:215], v[244:247], v[0:3]
	v_mfma_f32_16x16x32_bf16 v[52:55], v[208:211], v[224:227], v[52:55]
	v_mfma_f32_16x16x32_bf16 v[48:51], v[216:219], v[224:227], v[48:51]
	v_mfma_f32_16x16x32_bf16 v[36:39], v[208:211], v[232:235], v[36:39]
	v_mfma_f32_16x16x32_bf16 v[32:35], v[216:219], v[232:235], v[32:35]
	v_mfma_f32_16x16x32_bf16 v[20:23], v[208:211], v[240:243], v[20:23]
	v_mfma_f32_16x16x32_bf16 v[16:19], v[216:219], v[240:243], v[16:19]
	v_mfma_f32_16x16x32_bf16 v[4:7], v[208:211], v[248:251], v[4:7]
	v_mfma_f32_16x16x32_bf16 v[0:3], v[216:219], v[248:251], v[0:3]
	s_setprio 0
	s_barrier
	s_add_i32 s29, s29, 2
	s_add_u32 s3, s3, 0x100
	s_addc_u32 s28, s28, 0
	s_cmp_gt_u32 s29, 13
	s_mov_b64 s[60:61], s[62:63]
	s_cbranch_scc0 .LBB0_1207
	s_and_b64 vcc, exec, s[48:49]
	s_cbranch_vccz .LBB0_1210
	s_barrier

.LBB0_1305:
	s_add_u32 s4, s2, 0xfffc0080
	s_addc_u32 s5, s3, -1
	s_add_i32 s74, 0, 0x10000
	s_cmp_eq_u32 s73, 12
	s_cselect_b32 s61, s36, s5
	s_cselect_b32 s60, s51, s4
	s_cselect_b32 s35, s49, s72
	s_cselect_b32 s34, s70, s71
	s_add_i32 s75, 0, 0x14000
	v_lshl_add_u64 v[180:181], s[2:3], 0, v[134:135]
	s_add_i32 m0, s59, 0xc000
	s_nop 0
	global_load_lds_dwordx4 v[180:181], off
	v_lshl_add_u64 v[180:181], s[2:3], 0, v[136:137]
	s_add_i32 m0, s59, 0xe000
	s_nop 0
	global_load_lds_dwordx4 v[180:181], off
	v_add_u32_e32 v164, s74, v143
	v_add_u32_e32 v204, s75, v143
	ds_read_b128 v[138:141], v164
	ds_read_b128 v[156:159], v164 offset:1024
	ds_read_b128 v[160:163], v164 offset:2048
	ds_read_b128 v[164:167], v164 offset:3072
	ds_read_b128 v[168:171], v204
	ds_read_b128 v[172:175], v204 offset:1024
	ds_read_b128 v[176:179], v204 offset:2048
	ds_read_b128 v[204:207], v204 offset:3072
	ds_read_b128 v[208:211], v155
	ds_read_b128 v[212:215], v155 offset:1024
	ds_read_b128 v[216:219], v155 offset:2048
	ds_read_b128 v[220:223], v155 offset:3072
	ds_read_b128 v[224:227], v155 offset:4096
	ds_read_b128 v[228:231], v155 offset:5120
	ds_read_b128 v[232:235], v155 offset:6144
	ds_read_b128 v[236:239], v155 offset:7168
	s_waitcnt vmcnt(8)
	s_waitcnt lgkmcnt(0)
	s_barrier
	s_setprio 1
	s_waitcnt lgkmcnt(0)
	v_mfma_f32_16x16x32_bf16 v[124:127], v[138:141], v[208:211], v[124:127]
	v_mfma_f32_16x16x32_bf16 v[120:123], v[160:163], v[208:211], v[120:123]
	v_mfma_f32_16x16x32_bf16 v[108:111], v[138:141], v[216:219], v[108:111]
	v_mfma_f32_16x16x32_bf16 v[104:107], v[160:163], v[216:219], v[104:107]
	v_mfma_f32_16x16x32_bf16 v[92:95], v[138:141], v[224:227], v[92:95]
	v_mfma_f32_16x16x32_bf16 v[88:91], v[160:163], v[224:227], v[88:91]
	v_mfma_f32_16x16x32_bf16 v[76:79], v[138:141], v[232:235], v[76:79]
	v_mfma_f32_16x16x32_bf16 v[72:75], v[160:163], v[232:235], v[72:75]
	v_mfma_f32_16x16x32_bf16 v[124:127], v[156:159], v[212:215], v[124:127]
	v_mfma_f32_16x16x32_bf16 v[120:123], v[164:167], v[212:215], v[120:123]
	v_mfma_f32_16x16x32_bf16 v[108:111], v[156:159], v[220:223], v[108:111]
	v_mfma_f32_16x16x32_bf16 v[104:107], v[164:167], v[220:223], v[104:107]
	v_mfma_f32_16x16x32_bf16 v[92:95], v[156:159], v[228:231], v[92:95]
	v_mfma_f32_16x16x32_bf16 v[88:91], v[164:167], v[228:231], v[88:91]
	v_mfma_f32_16x16x32_bf16 v[76:79], v[156:159], v[236:239], v[76:79]
	v_mfma_f32_16x16x32_bf16 v[72:75], v[164:167], v[236:239], v[72:75]
	s_setprio 0
	s_setprio 1
	v_mfma_f32_16x16x32_bf16 v[116:119], v[168:171], v[208:211], v[116:119]
	v_mfma_f32_16x16x32_bf16 v[112:115], v[176:179], v[208:211], v[112:115]
	v_mfma_f32_16x16x32_bf16 v[100:103], v[168:171], v[216:219], v[100:103]
	v_mfma_f32_16x16x32_bf16 v[96:99], v[176:179], v[216:219], v[96:99]
	v_mfma_f32_16x16x32_bf16 v[84:87], v[168:171], v[224:227], v[84:87]
	v_mfma_f32_16x16x32_bf16 v[80:83], v[176:179], v[224:227], v[80:83]
	v_mfma_f32_16x16x32_bf16 v[68:71], v[168:171], v[232:235], v[68:71]
	v_mfma_f32_16x16x32_bf16 v[64:67], v[176:179], v[232:235], v[64:67]
	v_mfma_f32_16x16x32_bf16 v[116:119], v[172:175], v[212:215], v[116:119]
	v_mfma_f32_16x16x32_bf16 v[112:115], v[204:207], v[212:215], v[112:115]
	v_mfma_f32_16x16x32_bf16 v[100:103], v[172:175], v[220:223], v[100:103]
	v_mfma_f32_16x16x32_bf16 v[96:99], v[204:207], v[220:223], v[96:99]
	v_mfma_f32_16x16x32_bf16 v[84:87], v[172:175], v[228:231], v[84:87]
	v_mfma_f32_16x16x32_bf16 v[80:83], v[204:207], v[228:231], v[80:83]
	v_mfma_f32_16x16x32_bf16 v[68:71], v[172:175], v[236:239], v[68:71]
	v_mfma_f32_16x16x32_bf16 v[64:67], v[204:207], v[236:239], v[64:67]
	s_setprio 0
	s_barrier
	s_add_i32 s4, s74, s1
	v_lshl_add_u64 v[180:181], s[34:35], 0, v[144:145]
	s_mov_b32 m0, s4
	ds_read_b128 v[208:211], v155 offset:16384
	ds_read_b128 v[212:215], v155 offset:17408
	ds_read_b128 v[216:219], v155 offset:18432
	ds_read_b128 v[220:223], v155 offset:19456
	ds_read_b128 v[224:227], v155 offset:20480
	ds_read_b128 v[228:231], v155 offset:21504
	ds_read_b128 v[232:235], v155 offset:22528
	ds_read_b128 v[236:239], v155 offset:23552
	global_load_lds_dwordx4 v[180:181], off
	s_add_i32 m0, s4, 0x2000
	s_add_u32 s4, s34, 0x40000
	v_lshl_add_u64 v[202:203], s[34:35], 0, v[128:129]
	s_addc_u32 s5, s35, 0
	s_add_i32 s74, s75, s1
	global_load_lds_dwordx4 v[202:203], off
	v_lshl_add_u64 v[240:241], s[4:5], 0, v[144:145]
	s_mov_b32 m0, s74
	v_lshl_add_u64 v[242:243], s[60:61], 0, v[130:131]
	global_load_lds_dwordx4 v[240:241], off
	v_lshl_add_u64 v[240:241], s[4:5], 0, v[128:129]
	s_add_i32 m0, s74, 0x2000
	s_nop 0
	global_load_lds_dwordx4 v[240:241], off
	v_lshl_add_u64 v[240:241], s[60:61], 0, v[132:133]
	s_mov_b32 m0, s59
	s_nop 0
	global_load_lds_dwordx4 v[240:241], off
	s_mov_b32 m0, s64
	s_nop 0
	global_load_lds_dwordx4 v[242:243], off
	s_waitcnt vmcnt(8)
	s_waitcnt lgkmcnt(0)
	s_barrier
	s_setprio 1
	s_waitcnt lgkmcnt(0)
	v_mfma_f32_16x16x32_bf16 v[60:63], v[138:141], v[208:211], v[60:63]
	v_mfma_f32_16x16x32_bf16 v[56:59], v[160:163], v[208:211], v[56:59]
	v_mfma_f32_16x16x32_bf16 v[44:47], v[138:141], v[216:219], v[44:47]
	v_mfma_f32_16x16x32_bf16 v[40:43], v[160:163], v[216:219], v[40:43]
	v_mfma_f32_16x16x32_bf16 v[28:31], v[138:141], v[224:227], v[28:31]
	v_mfma_f32_16x16x32_bf16 v[24:27], v[160:163], v[224:227], v[24:27]
	v_mfma_f32_16x16x32_bf16 v[12:15], v[138:141], v[232:235], v[12:15]
	v_mfma_f32_16x16x32_bf16 v[8:11], v[160:163], v[232:235], v[8:11]
	v_mfma_f32_16x16x32_bf16 v[60:63], v[156:159], v[212:215], v[60:63]
	v_mfma_f32_16x16x32_bf16 v[56:59], v[164:167], v[212:215], v[56:59]
	v_mfma_f32_16x16x32_bf16 v[44:47], v[156:159], v[220:223], v[44:47]
	v_mfma_f32_16x16x32_bf16 v[40:43], v[164:167], v[220:223], v[40:43]
	v_mfma_f32_16x16x32_bf16 v[28:31], v[156:159], v[228:231], v[28:31]
	v_mfma_f32_16x16x32_bf16 v[24:27], v[164:167], v[228:231], v[24:27]
	v_mfma_f32_16x16x32_bf16 v[12:15], v[156:159], v[236:239], v[12:15]
	v_mfma_f32_16x16x32_bf16 v[8:11], v[164:167], v[236:239], v[8:11]
	s_setprio 0
	s_setprio 1
	v_mfma_f32_16x16x32_bf16 v[52:55], v[168:171], v[208:211], v[52:55]
	v_mfma_f32_16x16x32_bf16 v[48:51], v[176:179], v[208:211], v[48:51]
	v_mfma_f32_16x16x32_bf16 v[36:39], v[168:171], v[216:219], v[36:39]
	v_mfma_f32_16x16x32_bf16 v[32:35], v[176:179], v[216:219], v[32:35]
	v_mfma_f32_16x16x32_bf16 v[20:23], v[168:171], v[224:227], v[20:23]
	v_mfma_f32_16x16x32_bf16 v[16:19], v[176:179], v[224:227], v[16:19]
	v_mfma_f32_16x16x32_bf16 v[4:7], v[168:171], v[232:235], v[4:7]
	v_mfma_f32_16x16x32_bf16 v[0:3], v[176:179], v[232:235], v[0:3]
	v_mfma_f32_16x16x32_bf16 v[52:55], v[172:175], v[212:215], v[52:55]
	v_mfma_f32_16x16x32_bf16 v[48:51], v[204:207], v[212:215], v[48:51]
	v_mfma_f32_16x16x32_bf16 v[36:39], v[172:175], v[220:223], v[36:39]
	v_mfma_f32_16x16x32_bf16 v[32:35], v[204:207], v[220:223], v[32:35]
	v_mfma_f32_16x16x32_bf16 v[20:23], v[172:175], v[228:231], v[20:23]
	v_mfma_f32_16x16x32_bf16 v[16:19], v[204:207], v[228:231], v[16:19]
	v_mfma_f32_16x16x32_bf16 v[4:7], v[172:175], v[236:239], v[4:7]
	v_mfma_f32_16x16x32_bf16 v[0:3], v[204:207], v[236:239], v[0:3]
	s_setprio 0
	s_barrier
	s_add_i32 s74, 0, 0x18000
	s_add_i32 s75, 0, 0x1c000
	s_add_u32 s4, s60, 0x40000
	s_addc_u32 s5, s61, 0
	s_mov_b32 m0, s65
	v_lshl_add_u64 v[244:245], s[4:5], 0, v[132:133]
	global_load_lds_dwordx4 v[244:245], off
	v_lshl_add_u64 v[244:245], s[4:5], 0, v[130:131]
	s_mov_b32 m0, s66
	s_nop 0
	global_load_lds_dwordx4 v[244:245], off
	v_add_u32_e32 v164, s74, v143
	v_add_u32_e32 v204, s75, v143
	ds_read_b128 v[138:141], v164
	ds_read_b128 v[156:159], v164 offset:1024
	ds_read_b128 v[160:163], v164 offset:2048
	ds_read_b128 v[164:167], v164 offset:3072
	ds_read_b128 v[168:171], v204
	ds_read_b128 v[172:175], v204 offset:1024
	ds_read_b128 v[176:179], v204 offset:2048
	ds_read_b128 v[204:207], v204 offset:3072
	ds_read_b128 v[208:211], v155 offset:32768
	ds_read_b128 v[212:215], v155 offset:33792
	ds_read_b128 v[216:219], v155 offset:34816
	ds_read_b128 v[220:223], v155 offset:35840
	ds_read_b128 v[224:227], v155 offset:36864
	ds_read_b128 v[228:231], v155 offset:37888
	ds_read_b128 v[232:235], v155 offset:38912
	ds_read_b128 v[236:239], v155 offset:39936
	s_waitcnt vmcnt(8)
	s_waitcnt lgkmcnt(0)
	s_barrier
	s_setprio 1
	s_waitcnt lgkmcnt(0)
	v_mfma_f32_16x16x32_bf16 v[124:127], v[138:141], v[208:211], v[124:127]
	v_mfma_f32_16x16x32_bf16 v[120:123], v[160:163], v[208:211], v[120:123]
	v_mfma_f32_16x16x32_bf16 v[108:111], v[138:141], v[216:219], v[108:111]
	v_mfma_f32_16x16x32_bf16 v[104:107], v[160:163], v[216:219], v[104:107]
	v_mfma_f32_16x16x32_bf16 v[92:95], v[138:141], v[224:227], v[92:95]
	v_mfma_f32_16x16x32_bf16 v[88:91], v[160:163], v[224:227], v[88:91]
	v_mfma_f32_16x16x32_bf16 v[76:79], v[138:141], v[232:235], v[76:79]
	v_mfma_f32_16x16x32_bf16 v[72:75], v[160:163], v[232:235], v[72:75]
	v_mfma_f32_16x16x32_bf16 v[124:127], v[156:159], v[212:215], v[124:127]
	v_mfma_f32_16x16x32_bf16 v[120:123], v[164:167], v[212:215], v[120:123]
	v_mfma_f32_16x16x32_bf16 v[108:111], v[156:159], v[220:223], v[108:111]
	v_mfma_f32_16x16x32_bf16 v[104:107], v[164:167], v[220:223], v[104:107]
	v_mfma_f32_16x16x32_bf16 v[92:95], v[156:159], v[228:231], v[92:95]
	v_mfma_f32_16x16x32_bf16 v[88:91], v[164:167], v[228:231], v[88:91]
	v_mfma_f32_16x16x32_bf16 v[76:79], v[156:159], v[236:239], v[76:79]
	v_mfma_f32_16x16x32_bf16 v[72:75], v[164:167], v[236:239], v[72:75]
	s_setprio 0
	s_setprio 1
	v_mfma_f32_16x16x32_bf16 v[116:119], v[168:171], v[208:211], v[116:119]
	v_mfma_f32_16x16x32_bf16 v[112:115], v[176:179], v[208:211], v[112:115]
	v_mfma_f32_16x16x32_bf16 v[100:103], v[168:171], v[216:219], v[100:103]
	v_mfma_f32_16x16x32_bf16 v[96:99], v[176:179], v[216:219], v[96:99]
	v_mfma_f32_16x16x32_bf16 v[84:87], v[168:171], v[224:227], v[84:87]
	v_mfma_f32_16x16x32_bf16 v[80:83], v[176:179], v[224:227], v[80:83]
	v_mfma_f32_16x16x32_bf16 v[68:71], v[168:171], v[232:235], v[68:71]
	v_mfma_f32_16x16x32_bf16 v[64:67], v[176:179], v[232:235], v[64:67]
	v_mfma_f32_16x16x32_bf16 v[116:119], v[172:175], v[212:215], v[116:119]
	v_mfma_f32_16x16x32_bf16 v[112:115], v[204:207], v[212:215], v[112:115]
	v_mfma_f32_16x16x32_bf16 v[100:103], v[172:175], v[220:223], v[100:103]
	v_mfma_f32_16x16x32_bf16 v[96:99], v[204:207], v[220:223], v[96:99]
	v_mfma_f32_16x16x32_bf16 v[84:87], v[172:175], v[228:231], v[84:87]
	v_mfma_f32_16x16x32_bf16 v[80:83], v[204:207], v[228:231], v[80:83]
	v_mfma_f32_16x16x32_bf16 v[68:71], v[172:175], v[236:239], v[68:71]
	v_mfma_f32_16x16x32_bf16 v[64:67], v[204:207], v[236:239], v[64:67]
	s_setprio 0
	s_barrier
	s_add_i32 s4, s74, s1
	v_lshl_add_u64 v[180:181], v[180:181], 0, s[26:27]
	s_mov_b32 m0, s4
	ds_read_b128 v[208:211], v155 offset:49152
	ds_read_b128 v[212:215], v155 offset:50176
	ds_read_b128 v[216:219], v155 offset:51200
	ds_read_b128 v[220:223], v155 offset:52224
	ds_read_b128 v[224:227], v155 offset:53248
	ds_read_b128 v[228:231], v155 offset:54272
	ds_read_b128 v[232:235], v155 offset:55296
	ds_read_b128 v[236:239], v155 offset:56320
	global_load_lds_dwordx4 v[180:181], off
	s_add_i32 m0, s4, 0x2000
	s_add_u32 s4, s34, 0x40080
	v_lshl_add_u64 v[180:181], v[202:203], 0, s[26:27]
	s_addc_u32 s5, s35, 0
	s_add_i32 s34, s75, s1
	global_load_lds_dwordx4 v[180:181], off
	v_lshl_add_u64 v[180:181], s[4:5], 0, v[144:145]
	s_mov_b32 m0, s34
	s_nop 0
	global_load_lds_dwordx4 v[180:181], off
	v_lshl_add_u64 v[180:181], s[4:5], 0, v[128:129]
	s_add_i32 m0, s34, 0x2000
	s_nop 0
	global_load_lds_dwordx4 v[180:181], off
	v_lshl_add_u64 v[180:181], v[240:241], 0, s[26:27]
	s_mov_b32 m0, s67
	s_nop 0
	global_load_lds_dwordx4 v[180:181], off
	v_lshl_add_u64 v[180:181], v[242:243], 0, s[26:27]
	s_mov_b32 m0, s68
	s_nop 0
	global_load_lds_dwordx4 v[180:181], off
	s_waitcnt vmcnt(8)
	s_waitcnt lgkmcnt(0)
	s_barrier
	s_setprio 1
	s_waitcnt lgkmcnt(0)
	v_mfma_f32_16x16x32_bf16 v[60:63], v[138:141], v[208:211], v[60:63]
	v_mfma_f32_16x16x32_bf16 v[56:59], v[160:163], v[208:211], v[56:59]
	v_mfma_f32_16x16x32_bf16 v[44:47], v[138:141], v[216:219], v[44:47]
	v_mfma_f32_16x16x32_bf16 v[40:43], v[160:163], v[216:219], v[40:43]
	v_mfma_f32_16x16x32_bf16 v[28:31], v[138:141], v[224:227], v[28:31]
	v_mfma_f32_16x16x32_bf16 v[24:27], v[160:163], v[224:227], v[24:27]
	v_mfma_f32_16x16x32_bf16 v[12:15], v[138:141], v[232:235], v[12:15]
	v_mfma_f32_16x16x32_bf16 v[8:11], v[160:163], v[232:235], v[8:11]
	v_mfma_f32_16x16x32_bf16 v[60:63], v[156:159], v[212:215], v[60:63]
	v_mfma_f32_16x16x32_bf16 v[56:59], v[164:167], v[212:215], v[56:59]
	v_mfma_f32_16x16x32_bf16 v[44:47], v[156:159], v[220:223], v[44:47]
	v_mfma_f32_16x16x32_bf16 v[40:43], v[164:167], v[220:223], v[40:43]
	v_mfma_f32_16x16x32_bf16 v[28:31], v[156:159], v[228:231], v[28:31]
	v_mfma_f32_16x16x32_bf16 v[24:27], v[164:167], v[228:231], v[24:27]
	v_mfma_f32_16x16x32_bf16 v[12:15], v[156:159], v[236:239], v[12:15]
	v_mfma_f32_16x16x32_bf16 v[8:11], v[164:167], v[236:239], v[8:11]
	s_setprio 0
	s_setprio 1
	v_mfma_f32_16x16x32_bf16 v[52:55], v[168:171], v[208:211], v[52:55]
	v_mfma_f32_16x16x32_bf16 v[48:51], v[176:179], v[208:211], v[48:51]
	v_mfma_f32_16x16x32_bf16 v[36:39], v[168:171], v[216:219], v[36:39]
	v_mfma_f32_16x16x32_bf16 v[32:35], v[176:179], v[216:219], v[32:35]
	v_mfma_f32_16x16x32_bf16 v[20:23], v[168:171], v[224:227], v[20:23]
	v_mfma_f32_16x16x32_bf16 v[16:19], v[176:179], v[224:227], v[16:19]
	v_mfma_f32_16x16x32_bf16 v[4:7], v[168:171], v[232:235], v[4:7]
	v_mfma_f32_16x16x32_bf16 v[0:3], v[176:179], v[232:235], v[0:3]
	v_mfma_f32_16x16x32_bf16 v[52:55], v[172:175], v[212:215], v[52:55]
	v_mfma_f32_16x16x32_bf16 v[48:51], v[204:207], v[212:215], v[48:51]
	v_mfma_f32_16x16x32_bf16 v[36:39], v[172:175], v[220:223], v[36:39]
	v_mfma_f32_16x16x32_bf16 v[32:35], v[204:207], v[220:223], v[32:35]
	v_mfma_f32_16x16x32_bf16 v[20:23], v[172:175], v[228:231], v[20:23]
	v_mfma_f32_16x16x32_bf16 v[16:19], v[204:207], v[228:231], v[16:19]
	v_mfma_f32_16x16x32_bf16 v[4:7], v[172:175], v[236:239], v[4:7]
	v_mfma_f32_16x16x32_bf16 v[0:3], v[204:207], v[236:239], v[0:3]
	s_setprio 0
	s_barrier
	s_add_i32 s73, s73, 2
	s_add_u32 s2, s2, 0x100
	s_addc_u32 s3, s3, 0
	s_add_u32 s71, s71, 0x100
	s_addc_u32 s72, s72, 0
	s_cmp_gt_u32 s73, 13
	s_cbranch_scc0 .LBB0_1305
	s_and_b64 vcc, s[38:39], exec
	s_cselect_b32 s4, s50, s58
	v_lshl_add_u32 v178, s4, 8, v142
	v_ashrrev_i32_e32 v179, 31, v178
	v_lshl_add_u64 v[178:179], v[178:179], 4, s[44:45]
	global_load_dwordx4 v[208:211], v[178:179], off
	global_load_dwordx4 v[212:215], v[178:179], off offset:256
	global_load_dwordx4 v[216:219], v[178:179], off offset:512
	global_load_dwordx4 v[220:223], v[178:179], off offset:768
	global_load_dwordx4 v[224:227], v[178:179], off offset:2048
	global_load_dwordx4 v[228:231], v[178:179], off offset:2304
	global_load_dwordx4 v[232:235], v[178:179], off offset:2560
	global_load_dwordx4 v[236:239], v[178:179], off offset:2816
	s_and_b64 vcc, exec, s[46:47]
	s_cbranch_vccz .LBB0_1308
	s_barrier

.LBB0_1399:
	s_add_u32 s58, s54, 0x100
	s_addc_u32 s59, s55, 0
	s_add_i32 s4, 0, 0x10000
	s_cmp_eq_u32 s29, 40
	s_cselect_b32 s61, s45, s59
	s_cselect_b32 s60, s44, s58
	s_cselect_b32 s35, s53, s28
	s_cselect_b32 s34, s52, s3
	s_add_i32 s47, 0, 0x14000
	v_lshl_add_u64 v[142:143], s[54:55], 0, v[134:135]
	s_add_i32 m0, s65, 0xc000
	s_nop 0
	global_load_lds_dwordx4 v[142:143], off
	v_lshl_add_u64 v[142:143], s[54:55], 0, v[136:137]
	s_add_i32 m0, s65, 0xe000
	s_nop 0
	global_load_lds_dwordx4 v[142:143], off
	v_add_u32_e32 v176, s4, v160
	ds_read_b128 v[138:141], v176
	ds_read_b128 v[154:157], v176 offset:1024
	ds_read_b128 v[172:175], v176 offset:2048
	ds_read_b128 v[176:179], v176 offset:3072
	v_add_u32_e32 v216, s47, v160
	ds_read_b128 v[204:207], v216
	ds_read_b128 v[208:211], v216 offset:1024
	ds_read_b128 v[212:215], v216 offset:2048
	ds_read_b128 v[216:219], v216 offset:3072
	ds_read_b128 v[220:223], v170
	ds_read_b128 v[224:227], v170 offset:1024
	ds_read_b128 v[228:231], v170 offset:2048
	ds_read_b128 v[232:235], v170 offset:3072
	ds_read_b128 v[236:239], v170 offset:4096
	ds_read_b128 v[240:243], v170 offset:5120
	ds_read_b128 v[244:247], v170 offset:6144
	ds_read_b128 v[248:251], v170 offset:7168
	s_waitcnt vmcnt(8)
	s_waitcnt lgkmcnt(0)
	s_barrier
	s_setprio 1
	s_waitcnt lgkmcnt(0)
	v_mfma_f32_16x16x32_bf16 v[124:127], v[138:141], v[220:223], v[124:127]
	v_mfma_f32_16x16x32_bf16 v[120:123], v[172:175], v[220:223], v[120:123]
	v_mfma_f32_16x16x32_bf16 v[108:111], v[138:141], v[228:231], v[108:111]
	v_mfma_f32_16x16x32_bf16 v[104:107], v[172:175], v[228:231], v[104:107]
	v_mfma_f32_16x16x32_bf16 v[92:95], v[138:141], v[236:239], v[92:95]
	v_mfma_f32_16x16x32_bf16 v[88:91], v[172:175], v[236:239], v[88:91]
	v_mfma_f32_16x16x32_bf16 v[76:79], v[138:141], v[244:247], v[76:79]
	v_mfma_f32_16x16x32_bf16 v[72:75], v[172:175], v[244:247], v[72:75]
	v_mfma_f32_16x16x32_bf16 v[124:127], v[154:157], v[224:227], v[124:127]
	v_mfma_f32_16x16x32_bf16 v[120:123], v[176:179], v[224:227], v[120:123]
	v_mfma_f32_16x16x32_bf16 v[108:111], v[154:157], v[232:235], v[108:111]
	v_mfma_f32_16x16x32_bf16 v[104:107], v[176:179], v[232:235], v[104:107]
	v_mfma_f32_16x16x32_bf16 v[92:95], v[154:157], v[240:243], v[92:95]
	v_mfma_f32_16x16x32_bf16 v[88:91], v[176:179], v[240:243], v[88:91]
	v_mfma_f32_16x16x32_bf16 v[76:79], v[154:157], v[248:251], v[76:79]
	v_mfma_f32_16x16x32_bf16 v[72:75], v[176:179], v[248:251], v[72:75]
	s_setprio 0
	s_setprio 1
	v_mfma_f32_16x16x32_bf16 v[116:119], v[204:207], v[220:223], v[116:119]
	v_mfma_f32_16x16x32_bf16 v[112:115], v[212:215], v[220:223], v[112:115]
	v_mfma_f32_16x16x32_bf16 v[100:103], v[204:207], v[228:231], v[100:103]
	v_mfma_f32_16x16x32_bf16 v[96:99], v[212:215], v[228:231], v[96:99]
	v_mfma_f32_16x16x32_bf16 v[84:87], v[204:207], v[236:239], v[84:87]
	v_mfma_f32_16x16x32_bf16 v[80:83], v[212:215], v[236:239], v[80:83]
	v_mfma_f32_16x16x32_bf16 v[68:71], v[204:207], v[244:247], v[68:71]
	v_mfma_f32_16x16x32_bf16 v[64:67], v[212:215], v[244:247], v[64:67]
	v_mfma_f32_16x16x32_bf16 v[116:119], v[208:211], v[224:227], v[116:119]
	v_mfma_f32_16x16x32_bf16 v[112:115], v[216:219], v[224:227], v[112:115]
	v_mfma_f32_16x16x32_bf16 v[100:103], v[208:211], v[232:235], v[100:103]
	v_mfma_f32_16x16x32_bf16 v[96:99], v[216:219], v[232:235], v[96:99]
	v_mfma_f32_16x16x32_bf16 v[84:87], v[208:211], v[240:243], v[84:87]
	v_mfma_f32_16x16x32_bf16 v[80:83], v[216:219], v[240:243], v[80:83]
	v_mfma_f32_16x16x32_bf16 v[68:71], v[208:211], v[248:251], v[68:71]
	v_mfma_f32_16x16x32_bf16 v[64:67], v[216:219], v[248:251], v[64:67]
	s_setprio 0
	s_barrier
	s_add_i32 s4, s4, s33
	v_lshl_add_u64 v[142:143], s[34:35], 0, v[128:129]
	s_mov_b32 m0, s4
	ds_read_b128 v[220:223], v170 offset:16384
	ds_read_b128 v[224:227], v170 offset:17408
	ds_read_b128 v[228:231], v170 offset:18432
	ds_read_b128 v[232:235], v170 offset:19456
	ds_read_b128 v[236:239], v170 offset:20480
	ds_read_b128 v[240:243], v170 offset:21504
	ds_read_b128 v[244:247], v170 offset:22528
	ds_read_b128 v[248:251], v170 offset:23552
	global_load_lds_dwordx4 v[142:143], off
	s_add_i32 m0, s4, 0x2000
	s_add_u32 s4, s34, 0xb0000
	v_lshl_add_u64 v[158:159], s[34:35], 0, v[130:131]
	s_addc_u32 s5, s35, 0
	s_add_i32 s47, s47, s33
	global_load_lds_dwordx4 v[158:159], off
	v_lshl_add_u64 v[180:181], s[4:5], 0, v[128:129]
	s_mov_b32 m0, s47
	v_lshl_add_u64 v[202:203], s[60:61], 0, v[130:131]
	global_load_lds_dwordx4 v[180:181], off
	v_lshl_add_u64 v[180:181], s[4:5], 0, v[130:131]
	s_add_i32 m0, s47, 0x2000
	s_nop 0
	global_load_lds_dwordx4 v[180:181], off
	v_lshl_add_u64 v[180:181], s[60:61], 0, v[128:129]
	s_mov_b32 m0, s65
	s_nop 0
	global_load_lds_dwordx4 v[180:181], off
	s_mov_b32 m0, s66
	s_nop 0
	global_load_lds_dwordx4 v[202:203], off
	s_waitcnt vmcnt(8)
	s_waitcnt lgkmcnt(0)
	s_barrier
	s_setprio 1
	s_waitcnt lgkmcnt(0)
	v_mfma_f32_16x16x32_bf16 v[60:63], v[138:141], v[220:223], v[60:63]
	v_mfma_f32_16x16x32_bf16 v[56:59], v[172:175], v[220:223], v[56:59]
	v_mfma_f32_16x16x32_bf16 v[44:47], v[138:141], v[228:231], v[44:47]
	v_mfma_f32_16x16x32_bf16 v[40:43], v[172:175], v[228:231], v[40:43]
	v_mfma_f32_16x16x32_bf16 v[28:31], v[138:141], v[236:239], v[28:31]
	v_mfma_f32_16x16x32_bf16 v[24:27], v[172:175], v[236:239], v[24:27]
	v_mfma_f32_16x16x32_bf16 v[12:15], v[138:141], v[244:247], v[12:15]
	v_mfma_f32_16x16x32_bf16 v[8:11], v[172:175], v[244:247], v[8:11]
	v_mfma_f32_16x16x32_bf16 v[60:63], v[154:157], v[224:227], v[60:63]
	v_mfma_f32_16x16x32_bf16 v[56:59], v[176:179], v[224:227], v[56:59]
	v_mfma_f32_16x16x32_bf16 v[44:47], v[154:157], v[232:235], v[44:47]
	v_mfma_f32_16x16x32_bf16 v[40:43], v[176:179], v[232:235], v[40:43]
	v_mfma_f32_16x16x32_bf16 v[28:31], v[154:157], v[240:243], v[28:31]
	v_mfma_f32_16x16x32_bf16 v[24:27], v[176:179], v[240:243], v[24:27]
	v_mfma_f32_16x16x32_bf16 v[12:15], v[154:157], v[248:251], v[12:15]
	v_mfma_f32_16x16x32_bf16 v[8:11], v[176:179], v[248:251], v[8:11]
	s_setprio 0
	s_setprio 1
	v_mfma_f32_16x16x32_bf16 v[52:55], v[204:207], v[220:223], v[52:55]
	v_mfma_f32_16x16x32_bf16 v[48:51], v[212:215], v[220:223], v[48:51]
	v_mfma_f32_16x16x32_bf16 v[36:39], v[204:207], v[228:231], v[36:39]
	v_mfma_f32_16x16x32_bf16 v[32:35], v[212:215], v[228:231], v[32:35]
	v_mfma_f32_16x16x32_bf16 v[20:23], v[204:207], v[236:239], v[20:23]
	v_mfma_f32_16x16x32_bf16 v[16:19], v[212:215], v[236:239], v[16:19]
	v_mfma_f32_16x16x32_bf16 v[4:7], v[204:207], v[244:247], v[4:7]
	v_mfma_f32_16x16x32_bf16 v[0:3], v[212:215], v[244:247], v[0:3]
	v_mfma_f32_16x16x32_bf16 v[52:55], v[208:211], v[224:227], v[52:55]
	v_mfma_f32_16x16x32_bf16 v[48:51], v[216:219], v[224:227], v[48:51]
	v_mfma_f32_16x16x32_bf16 v[36:39], v[208:211], v[232:235], v[36:39]
	v_mfma_f32_16x16x32_bf16 v[32:35], v[216:219], v[232:235], v[32:35]
	v_mfma_f32_16x16x32_bf16 v[20:23], v[208:211], v[240:243], v[20:23]
	v_mfma_f32_16x16x32_bf16 v[16:19], v[216:219], v[240:243], v[16:19]
	v_mfma_f32_16x16x32_bf16 v[4:7], v[208:211], v[248:251], v[4:7]
	v_mfma_f32_16x16x32_bf16 v[0:3], v[216:219], v[248:251], v[0:3]
	s_setprio 0
	s_barrier
	s_add_i32 s47, 0, 0x18000
	s_add_i32 s54, 0, 0x1c000
	s_add_u32 s4, s60, 0xb0000
	s_addc_u32 s5, s61, 0
	s_mov_b32 m0, s67
	v_lshl_add_u64 v[252:253], s[4:5], 0, v[128:129]
	global_load_lds_dwordx4 v[252:253], off
	v_lshl_add_u64 v[252:253], s[4:5], 0, v[130:131]
	s_mov_b32 m0, s68
	s_nop 0
	global_load_lds_dwordx4 v[252:253], off
	v_add_u32_e32 v176, s47, v160
	ds_read_b128 v[138:141], v176
	ds_read_b128 v[154:157], v176 offset:1024
	ds_read_b128 v[172:175], v176 offset:2048
	ds_read_b128 v[176:179], v176 offset:3072
	v_add_u32_e32 v216, s54, v160
	ds_read_b128 v[204:207], v216
	ds_read_b128 v[208:211], v216 offset:1024
	ds_read_b128 v[212:215], v216 offset:2048
	ds_read_b128 v[216:219], v216 offset:3072
	ds_read_b128 v[220:223], v170 offset:32768
	ds_read_b128 v[224:227], v170 offset:33792
	ds_read_b128 v[228:231], v170 offset:34816
	ds_read_b128 v[232:235], v170 offset:35840
	ds_read_b128 v[236:239], v170 offset:36864
	ds_read_b128 v[240:243], v170 offset:37888
	ds_read_b128 v[244:247], v170 offset:38912
	ds_read_b128 v[248:251], v170 offset:39936
	s_waitcnt vmcnt(8)
	s_waitcnt lgkmcnt(0)
	s_barrier
	s_setprio 1
	s_waitcnt lgkmcnt(0)
	v_mfma_f32_16x16x32_bf16 v[124:127], v[138:141], v[220:223], v[124:127]
	v_mfma_f32_16x16x32_bf16 v[120:123], v[172:175], v[220:223], v[120:123]
	v_mfma_f32_16x16x32_bf16 v[108:111], v[138:141], v[228:231], v[108:111]
	v_mfma_f32_16x16x32_bf16 v[104:107], v[172:175], v[228:231], v[104:107]
	v_mfma_f32_16x16x32_bf16 v[92:95], v[138:141], v[236:239], v[92:95]
	v_mfma_f32_16x16x32_bf16 v[88:91], v[172:175], v[236:239], v[88:91]
	v_mfma_f32_16x16x32_bf16 v[76:79], v[138:141], v[244:247], v[76:79]
	v_mfma_f32_16x16x32_bf16 v[72:75], v[172:175], v[244:247], v[72:75]
	v_mfma_f32_16x16x32_bf16 v[124:127], v[154:157], v[224:227], v[124:127]
	v_mfma_f32_16x16x32_bf16 v[120:123], v[176:179], v[224:227], v[120:123]
	v_mfma_f32_16x16x32_bf16 v[108:111], v[154:157], v[232:235], v[108:111]
	v_mfma_f32_16x16x32_bf16 v[104:107], v[176:179], v[232:235], v[104:107]
	v_mfma_f32_16x16x32_bf16 v[92:95], v[154:157], v[240:243], v[92:95]
	v_mfma_f32_16x16x32_bf16 v[88:91], v[176:179], v[240:243], v[88:91]
	v_mfma_f32_16x16x32_bf16 v[76:79], v[154:157], v[248:251], v[76:79]
	v_mfma_f32_16x16x32_bf16 v[72:75], v[176:179], v[248:251], v[72:75]
	s_setprio 0
	s_setprio 1
	v_mfma_f32_16x16x32_bf16 v[116:119], v[204:207], v[220:223], v[116:119]
	v_mfma_f32_16x16x32_bf16 v[112:115], v[212:215], v[220:223], v[112:115]
	v_mfma_f32_16x16x32_bf16 v[100:103], v[204:207], v[228:231], v[100:103]
	v_mfma_f32_16x16x32_bf16 v[96:99], v[212:215], v[228:231], v[96:99]
	v_mfma_f32_16x16x32_bf16 v[84:87], v[204:207], v[236:239], v[84:87]
	v_mfma_f32_16x16x32_bf16 v[80:83], v[212:215], v[236:239], v[80:83]
	v_mfma_f32_16x16x32_bf16 v[68:71], v[204:207], v[244:247], v[68:71]
	v_mfma_f32_16x16x32_bf16 v[64:67], v[212:215], v[244:247], v[64:67]
	v_mfma_f32_16x16x32_bf16 v[116:119], v[208:211], v[224:227], v[116:119]
	v_mfma_f32_16x16x32_bf16 v[112:115], v[216:219], v[224:227], v[112:115]
	v_mfma_f32_16x16x32_bf16 v[100:103], v[208:211], v[232:235], v[100:103]
	v_mfma_f32_16x16x32_bf16 v[96:99], v[216:219], v[232:235], v[96:99]
	v_mfma_f32_16x16x32_bf16 v[84:87], v[208:211], v[240:243], v[84:87]
	v_mfma_f32_16x16x32_bf16 v[80:83], v[216:219], v[240:243], v[80:83]
	v_mfma_f32_16x16x32_bf16 v[68:71], v[208:211], v[248:251], v[68:71]
	v_mfma_f32_16x16x32_bf16 v[64:67], v[216:219], v[248:251], v[64:67]
	s_setprio 0
	s_barrier
	s_add_i32 s4, s47, s33
	v_lshl_add_u64 v[142:143], v[142:143], 0, s[26:27]
	s_mov_b32 m0, s4
	ds_read_b128 v[220:223], v170 offset:49152
	ds_read_b128 v[224:227], v170 offset:50176
	ds_read_b128 v[228:231], v170 offset:51200
	ds_read_b128 v[232:235], v170 offset:52224
	ds_read_b128 v[236:239], v170 offset:53248
	ds_read_b128 v[240:243], v170 offset:54272
	ds_read_b128 v[244:247], v170 offset:55296
	ds_read_b128 v[248:251], v170 offset:56320
	global_load_lds_dwordx4 v[142:143], off
	s_add_i32 m0, s4, 0x2000
	s_add_u32 s4, s34, 0xb0080
	v_lshl_add_u64 v[142:143], v[158:159], 0, s[26:27]
	s_addc_u32 s5, s35, 0
	s_add_i32 s34, s54, s33
	global_load_lds_dwordx4 v[142:143], off
	v_lshl_add_u64 v[142:143], s[4:5], 0, v[128:129]
	s_mov_b32 m0, s34
	s_nop 0
	global_load_lds_dwordx4 v[142:143], off
	v_lshl_add_u64 v[142:143], s[4:5], 0, v[130:131]
	s_add_i32 m0, s34, 0x2000
	s_nop 0
	global_load_lds_dwordx4 v[142:143], off
	v_lshl_add_u64 v[142:143], v[180:181], 0, s[26:27]
	s_mov_b32 m0, s69
	s_nop 0
	global_load_lds_dwordx4 v[142:143], off
	v_lshl_add_u64 v[142:143], v[202:203], 0, s[26:27]
	s_mov_b32 m0, s70
	s_nop 0
	global_load_lds_dwordx4 v[142:143], off
	s_waitcnt vmcnt(8)
	s_waitcnt lgkmcnt(0)
	s_barrier
	s_setprio 1
	s_waitcnt lgkmcnt(0)
	v_mfma_f32_16x16x32_bf16 v[60:63], v[138:141], v[220:223], v[60:63]
	v_mfma_f32_16x16x32_bf16 v[56:59], v[172:175], v[220:223], v[56:59]
	v_mfma_f32_16x16x32_bf16 v[44:47], v[138:141], v[228:231], v[44:47]
	v_mfma_f32_16x16x32_bf16 v[40:43], v[172:175], v[228:231], v[40:43]
	v_mfma_f32_16x16x32_bf16 v[28:31], v[138:141], v[236:239], v[28:31]
	v_mfma_f32_16x16x32_bf16 v[24:27], v[172:175], v[236:239], v[24:27]
	v_mfma_f32_16x16x32_bf16 v[12:15], v[138:141], v[244:247], v[12:15]
	v_mfma_f32_16x16x32_bf16 v[8:11], v[172:175], v[244:247], v[8:11]
	v_mfma_f32_16x16x32_bf16 v[60:63], v[154:157], v[224:227], v[60:63]
	v_mfma_f32_16x16x32_bf16 v[56:59], v[176:179], v[224:227], v[56:59]
	v_mfma_f32_16x16x32_bf16 v[44:47], v[154:157], v[232:235], v[44:47]
	v_mfma_f32_16x16x32_bf16 v[40:43], v[176:179], v[232:235], v[40:43]
	v_mfma_f32_16x16x32_bf16 v[28:31], v[154:157], v[240:243], v[28:31]
	v_mfma_f32_16x16x32_bf16 v[24:27], v[176:179], v[240:243], v[24:27]
	v_mfma_f32_16x16x32_bf16 v[12:15], v[154:157], v[248:251], v[12:15]
	v_mfma_f32_16x16x32_bf16 v[8:11], v[176:179], v[248:251], v[8:11]
	s_setprio 0
	s_setprio 1
	v_mfma_f32_16x16x32_bf16 v[52:55], v[204:207], v[220:223], v[52:55]
	v_mfma_f32_16x16x32_bf16 v[48:51], v[212:215], v[220:223], v[48:51]
	v_mfma_f32_16x16x32_bf16 v[36:39], v[204:207], v[228:231], v[36:39]
	v_mfma_f32_16x16x32_bf16 v[32:35], v[212:215], v[228:231], v[32:35]
	v_mfma_f32_16x16x32_bf16 v[20:23], v[204:207], v[236:239], v[20:23]
	v_mfma_f32_16x16x32_bf16 v[16:19], v[212:215], v[236:239], v[16:19]
	v_mfma_f32_16x16x32_bf16 v[4:7], v[204:207], v[244:247], v[4:7]
	v_mfma_f32_16x16x32_bf16 v[0:3], v[212:215], v[244:247], v[0:3]
	v_mfma_f32_16x16x32_bf16 v[52:55], v[208:211], v[224:227], v[52:55]
	v_mfma_f32_16x16x32_bf16 v[48:51], v[216:219], v[224:227], v[48:51]
	v_mfma_f32_16x16x32_bf16 v[36:39], v[208:211], v[232:235], v[36:39]
	v_mfma_f32_16x16x32_bf16 v[32:35], v[216:219], v[232:235], v[32:35]
	v_mfma_f32_16x16x32_bf16 v[20:23], v[208:211], v[240:243], v[20:23]
	v_mfma_f32_16x16x32_bf16 v[16:19], v[216:219], v[240:243], v[16:19]
	v_mfma_f32_16x16x32_bf16 v[4:7], v[208:211], v[248:251], v[4:7]
	v_mfma_f32_16x16x32_bf16 v[0:3], v[216:219], v[248:251], v[0:3]
	s_setprio 0
	s_barrier
	s_add_i32 s29, s29, 2
	s_add_u32 s3, s3, 0x100
	s_addc_u32 s28, s28, 0
	s_cmp_gt_u32 s29, 41
	s_mov_b64 s[54:55], s[58:59]
	s_cbranch_scc0 .LBB0_1399
	s_and_b64 vcc, exec, s[50:51]
	s_cbranch_vccz .LBB0_1402
	s_barrier
